# RES epilogue (phases 3,5,8,10) de-serialised: 16 residual loads issued up front, counted waits, DPP row-sum, batched atomics
# speedup vs baseline: 1.0974x; 1.0331x over previous
.LBB0_300:
	s_and_b32 s12, s17, 0x1ffffc0
	s_lshl_b32 s14, s17, 3
	s_and_b32 s14, s14, 56
	s_or_b32 s12, s12, s3
	s_or_b32 s12, s12, s14
	s_lshl_b32 s12, s12, 7
	s_lshl_b64 s[26:27], s[12:13], 11
	v_lshl_add_u64 v[74:75], v[70:71], 0, s[26:27]
	v_add_co_u32_e32 v78, vcc, s20, v74
	s_lshl_b32 s14, s17, 4
	s_nop 0
	v_addc_co_u32_e32 v79, vcc, 0, v75, vcc
	v_add_co_u32_e32 v80, vcc, s21, v74
	s_and_b32 s14, s14, 0x380
	s_nop 0
	v_addc_co_u32_e32 v81, vcc, 0, v75, vcc
	v_add_co_u32_e32 v82, vcc, s22, v74
	s_lshl_b32 s12, s14, 11
	s_nop 0
	v_addc_co_u32_e32 v83, vcc, 0, v75, vcc
	v_lshl_add_u64 v[76:77], v[72:73], 0, s[12:13]
	global_load_dwordx4 v[2:5], v[74:75], off
	global_load_dwordx4 v[6:9], v[78:79], off
	global_load_dwordx4 v[10:13], v[80:81], off
	global_load_dwordx4 v[14:17], v[82:83], off
	global_load_dwordx4 v[18:21], v[76:77], off
	v_add_co_u32_e32 v84, vcc, s20, v76
	s_nop 1
	v_addc_co_u32_e32 v85, vcc, 0, v77, vcc
	v_add_co_u32_e32 v86, vcc, s21, v76
	global_load_dwordx4 v[22:25], v[84:85], off
	s_nop 0
	v_addc_co_u32_e32 v87, vcc, 0, v77, vcc
	global_load_dwordx4 v[26:29], v[86:87], off
	v_add_co_u32_e32 v88, vcc, s22, v76
	s_nop 1
	v_addc_co_u32_e32 v89, vcc, 0, v77, vcc
	global_load_dwordx4 v[30:33], v[88:89], off
	global_load_dwordx4 v[112:115], v[74:75], off offset:128
	global_load_dwordx4 v[116:119], v[76:77], off offset:128
	global_load_dwordx4 v[120:123], v[78:79], off offset:128
	global_load_dwordx4 v[124:127], v[80:81], off offset:128
	global_load_dwordx4 v[128:131], v[82:83], off offset:128
	global_load_dwordx4 v[132:135], v[84:85], off offset:128
	global_load_dwordx4 v[136:139], v[86:87], off offset:128
	global_load_dwordx4 v[140:143], v[88:89], off offset:128
	s_waitcnt vmcnt(15)
	ds_write_b128 v90, v[2:5]
	s_waitcnt vmcnt(11)
	ds_write_b128 v90, v[18:21] offset:36864
	ds_write_b128 v90, v[6:9] offset:4608
	ds_write_b128 v90, v[10:13] offset:9216
	ds_write_b128 v90, v[14:17] offset:13824
	s_waitcnt vmcnt(10)
	ds_write_b128 v90, v[22:25] offset:41472
	s_waitcnt vmcnt(9)
	ds_write_b128 v90, v[26:29] offset:46080
	s_waitcnt vmcnt(8)
	ds_write_b128 v90, v[30:33] offset:50688
	s_waitcnt lgkmcnt(0)
	s_barrier
	global_load_dwordx4 v[144:147], v[78:79], off offset:256
	global_load_dwordx4 v[148:151], v[80:81], off offset:256
	global_load_dwordx4 v[152:155], v[74:75], off offset:256
	global_load_dwordx4 v[156:159], v[76:77], off offset:256
	global_load_dwordx4 v[160:163], v[82:83], off offset:256
	global_load_dwordx4 v[164:167], v[84:85], off offset:256
	global_load_dwordx4 v[168:171], v[86:87], off offset:256
	global_load_dwordx4 v[172:175], v[88:89], off offset:256
	ds_read_b128 v[18:21], v66
	ds_read_b128 v[34:37], v67 offset:36864
	ds_read_b128 v[176:179], v66 offset:32
	ds_read_b128 v[180:183], v67 offset:36896
	ds_read_b128 v[50:53], v67 offset:41472
	ds_read_b128 v[184:187], v67 offset:41504
	ds_read_b128 v[54:57], v66 offset:4608
	ds_read_b128 v[188:191], v66 offset:4640
	s_waitcnt lgkmcnt(6)
	v_mfma_f32_32x32x16_bf16 v[2:17], v[18:21], v[34:37], 0
	s_waitcnt lgkmcnt(3)
	v_mfma_f32_32x32x16_bf16 v[18:33], v[18:21], v[50:53], 0
	s_waitcnt lgkmcnt(1)
	v_mfma_f32_32x32x16_bf16 v[34:49], v[54:57], v[34:37], 0
	v_mfma_f32_32x32x16_bf16 v[50:65], v[54:57], v[50:53], 0
	v_mfma_f32_32x32x16_bf16 v[2:17], v[176:179], v[180:183], v[2:17]
	v_mfma_f32_32x32x16_bf16 v[18:33], v[176:179], v[184:187], v[18:33]
	s_waitcnt lgkmcnt(0)
	v_mfma_f32_32x32x16_bf16 v[34:49], v[188:191], v[180:183], v[34:49]
	v_mfma_f32_32x32x16_bf16 v[50:65], v[188:191], v[184:187], v[50:65]
	ds_read_b128 v[176:179], v66 offset:64
	ds_read_b128 v[180:183], v67 offset:36928
	ds_read_b128 v[184:187], v66 offset:96
	ds_read_b128 v[188:191], v67 offset:36960
	ds_read_b128 v[192:195], v67 offset:41536
	ds_read_b128 v[196:199], v67 offset:41568
	s_waitcnt lgkmcnt(4)
	v_mfma_f32_32x32x16_bf16 v[2:17], v[176:179], v[180:183], v[2:17]
	s_waitcnt lgkmcnt(1)
	v_mfma_f32_32x32x16_bf16 v[18:33], v[176:179], v[192:195], v[18:33]
	ds_read_b128 v[176:179], v66 offset:4672
	ds_read_b128 v[200:203], v66 offset:4704
	s_waitcnt vmcnt(15)
	ds_write_b128 v90, v[112:115] offset:18432
	s_waitcnt vmcnt(13)
	ds_write_b128 v90, v[120:123] offset:23040
	s_waitcnt vmcnt(12)
	ds_write_b128 v90, v[124:127] offset:27648
	s_waitcnt vmcnt(11)
	ds_write_b128 v90, v[128:131] offset:32256
	ds_write_b128 v90, v[116:119] offset:55296
	s_waitcnt vmcnt(10)
	ds_write_b128 v90, v[132:135] offset:59904
	s_waitcnt vmcnt(9)
	ds_write_b128 v90, v[136:139] offset:64512
	s_waitcnt vmcnt(8)
	ds_write_b128 v91, v[140:143] offset:32256
	s_waitcnt lgkmcnt(0)
	s_barrier
	global_load_dwordx4 v[112:115], v[78:79], off offset:384
	global_load_dwordx4 v[116:119], v[80:81], off offset:384
	global_load_dwordx4 v[120:123], v[74:75], off offset:384
	global_load_dwordx4 v[124:127], v[76:77], off offset:384
	global_load_dwordx4 v[128:131], v[82:83], off offset:384
	global_load_dwordx4 v[132:135], v[84:85], off offset:384
	global_load_dwordx4 v[136:139], v[86:87], off offset:384
	global_load_dwordx4 v[140:143], v[88:89], off offset:384
	v_mfma_f32_32x32x16_bf16 v[34:49], v[176:179], v[180:183], v[34:49]
	v_mfma_f32_32x32x16_bf16 v[50:65], v[176:179], v[192:195], v[50:65]
	v_mfma_f32_32x32x16_bf16 v[2:17], v[184:187], v[188:191], v[2:17]
	v_mfma_f32_32x32x16_bf16 v[18:33], v[184:187], v[196:199], v[18:33]
	v_mfma_f32_32x32x16_bf16 v[34:49], v[200:203], v[188:191], v[34:49]
	v_mfma_f32_32x32x16_bf16 v[50:65], v[200:203], v[196:199], v[50:65]
	ds_read_b128 v[176:179], v66 offset:18432
	ds_read_b128 v[180:183], v67 offset:55296
	ds_read_b128 v[184:187], v66 offset:18464
	ds_read_b128 v[188:191], v67 offset:55328
	ds_read_b128 v[192:195], v67 offset:59904
	ds_read_b128 v[196:199], v67 offset:59936
	s_waitcnt lgkmcnt(4)
	v_mfma_f32_32x32x16_bf16 v[2:17], v[176:179], v[180:183], v[2:17]
	s_waitcnt lgkmcnt(1)
	v_mfma_f32_32x32x16_bf16 v[18:33], v[176:179], v[192:195], v[18:33]
	ds_read_b128 v[176:179], v66 offset:23040
	ds_read_b128 v[200:203], v66 offset:23072
	s_waitcnt lgkmcnt(1)
	v_mfma_f32_32x32x16_bf16 v[34:49], v[176:179], v[180:183], v[34:49]
	v_mfma_f32_32x32x16_bf16 v[50:65], v[176:179], v[192:195], v[50:65]
	v_mfma_f32_32x32x16_bf16 v[2:17], v[184:187], v[188:191], v[2:17]
	v_mfma_f32_32x32x16_bf16 v[18:33], v[184:187], v[196:199], v[18:33]
	s_waitcnt lgkmcnt(0)
	v_mfma_f32_32x32x16_bf16 v[34:49], v[200:203], v[188:191], v[34:49]
	ds_read_b128 v[176:179], v66 offset:18496
	ds_read_b128 v[180:183], v67 offset:55360
	ds_read_b128 v[184:187], v66 offset:18528
	ds_read_b128 v[188:191], v67 offset:55392
	v_mfma_f32_32x32x16_bf16 v[50:65], v[200:203], v[196:199], v[50:65]
	ds_read_b128 v[192:195], v67 offset:59968
	ds_read_b128 v[196:199], v67 offset:60000
	s_waitcnt lgkmcnt(4)
	v_mfma_f32_32x32x16_bf16 v[2:17], v[176:179], v[180:183], v[2:17]
	s_waitcnt lgkmcnt(1)
	v_mfma_f32_32x32x16_bf16 v[18:33], v[176:179], v[192:195], v[18:33]
	ds_read_b128 v[176:179], v66 offset:23104
	ds_read_b128 v[200:203], v66 offset:23136
	s_waitcnt vmcnt(13)
	ds_write_b128 v90, v[152:155]
	ds_write_b128 v90, v[144:147] offset:4608
	ds_write_b128 v90, v[148:151] offset:9216
	s_waitcnt vmcnt(11)
	ds_write_b128 v90, v[160:163] offset:13824
	ds_write_b128 v90, v[156:159] offset:36864
	s_waitcnt vmcnt(10)
	ds_write_b128 v90, v[164:167] offset:41472
	s_waitcnt vmcnt(9)
	ds_write_b128 v90, v[168:171] offset:46080
	s_waitcnt vmcnt(8)
	ds_write_b128 v90, v[172:175] offset:50688
	s_waitcnt lgkmcnt(0)
	s_barrier
	global_load_dwordx4 v[144:147], v[78:79], off offset:512
	global_load_dwordx4 v[148:151], v[80:81], off offset:512
	global_load_dwordx4 v[152:155], v[74:75], off offset:512
	global_load_dwordx4 v[156:159], v[76:77], off offset:512
	global_load_dwordx4 v[160:163], v[82:83], off offset:512
	global_load_dwordx4 v[164:167], v[84:85], off offset:512
	global_load_dwordx4 v[168:171], v[86:87], off offset:512
	global_load_dwordx4 v[172:175], v[88:89], off offset:512
	v_mfma_f32_32x32x16_bf16 v[34:49], v[176:179], v[180:183], v[34:49]
	v_mfma_f32_32x32x16_bf16 v[50:65], v[176:179], v[192:195], v[50:65]
	v_mfma_f32_32x32x16_bf16 v[2:17], v[184:187], v[188:191], v[2:17]
	v_mfma_f32_32x32x16_bf16 v[18:33], v[184:187], v[196:199], v[18:33]
	v_mfma_f32_32x32x16_bf16 v[34:49], v[200:203], v[188:191], v[34:49]
	v_mfma_f32_32x32x16_bf16 v[50:65], v[200:203], v[196:199], v[50:65]
	ds_read_b128 v[176:179], v66
	ds_read_b128 v[180:183], v67 offset:36864
	ds_read_b128 v[184:187], v66 offset:32
	ds_read_b128 v[188:191], v67 offset:36896
	ds_read_b128 v[192:195], v67 offset:41472
	ds_read_b128 v[196:199], v67 offset:41504
	s_waitcnt lgkmcnt(4)
	v_mfma_f32_32x32x16_bf16 v[2:17], v[176:179], v[180:183], v[2:17]
	s_waitcnt lgkmcnt(1)
	v_mfma_f32_32x32x16_bf16 v[18:33], v[176:179], v[192:195], v[18:33]
	ds_read_b128 v[176:179], v66 offset:4608
	ds_read_b128 v[200:203], v66 offset:4640
	s_waitcnt lgkmcnt(1)
	v_mfma_f32_32x32x16_bf16 v[34:49], v[176:179], v[180:183], v[34:49]
	v_mfma_f32_32x32x16_bf16 v[50:65], v[176:179], v[192:195], v[50:65]
	v_mfma_f32_32x32x16_bf16 v[2:17], v[184:187], v[188:191], v[2:17]
	v_mfma_f32_32x32x16_bf16 v[18:33], v[184:187], v[196:199], v[18:33]
	s_waitcnt lgkmcnt(0)
	v_mfma_f32_32x32x16_bf16 v[34:49], v[200:203], v[188:191], v[34:49]
	ds_read_b128 v[176:179], v66 offset:64
	ds_read_b128 v[180:183], v67 offset:36928
	ds_read_b128 v[184:187], v66 offset:96
	ds_read_b128 v[188:191], v67 offset:36960
	v_mfma_f32_32x32x16_bf16 v[50:65], v[200:203], v[196:199], v[50:65]
	ds_read_b128 v[192:195], v67 offset:41536
	ds_read_b128 v[196:199], v67 offset:41568
	s_waitcnt lgkmcnt(4)
	v_mfma_f32_32x32x16_bf16 v[2:17], v[176:179], v[180:183], v[2:17]
	s_waitcnt lgkmcnt(1)
	v_mfma_f32_32x32x16_bf16 v[18:33], v[176:179], v[192:195], v[18:33]
	ds_read_b128 v[176:179], v66 offset:4672
	ds_read_b128 v[200:203], v66 offset:4704
	s_waitcnt vmcnt(13)
	ds_write_b128 v90, v[120:123] offset:18432
	ds_write_b128 v90, v[112:115] offset:23040
	ds_write_b128 v90, v[116:119] offset:27648
	s_waitcnt vmcnt(11)
	ds_write_b128 v90, v[128:131] offset:32256
	ds_write_b128 v90, v[124:127] offset:55296
	s_waitcnt vmcnt(10)
	ds_write_b128 v90, v[132:135] offset:59904
	s_waitcnt vmcnt(9)
	ds_write_b128 v90, v[136:139] offset:64512
	s_waitcnt vmcnt(8)
	ds_write_b128 v91, v[140:143] offset:32256
	s_waitcnt lgkmcnt(0)
	s_barrier
	global_load_dwordx4 v[112:115], v[78:79], off offset:640
	global_load_dwordx4 v[116:119], v[80:81], off offset:640
	global_load_dwordx4 v[120:123], v[74:75], off offset:640
	global_load_dwordx4 v[124:127], v[76:77], off offset:640
	global_load_dwordx4 v[128:131], v[82:83], off offset:640
	global_load_dwordx4 v[132:135], v[84:85], off offset:640
	global_load_dwordx4 v[136:139], v[86:87], off offset:640
	global_load_dwordx4 v[140:143], v[88:89], off offset:640
	v_mfma_f32_32x32x16_bf16 v[34:49], v[176:179], v[180:183], v[34:49]
	v_mfma_f32_32x32x16_bf16 v[50:65], v[176:179], v[192:195], v[50:65]
	v_mfma_f32_32x32x16_bf16 v[2:17], v[184:187], v[188:191], v[2:17]
	v_mfma_f32_32x32x16_bf16 v[18:33], v[184:187], v[196:199], v[18:33]
	v_mfma_f32_32x32x16_bf16 v[34:49], v[200:203], v[188:191], v[34:49]
	v_mfma_f32_32x32x16_bf16 v[50:65], v[200:203], v[196:199], v[50:65]
	ds_read_b128 v[176:179], v66 offset:18432
	ds_read_b128 v[180:183], v67 offset:55296
	ds_read_b128 v[184:187], v66 offset:18464
	ds_read_b128 v[188:191], v67 offset:55328
	ds_read_b128 v[192:195], v67 offset:59904
	ds_read_b128 v[196:199], v67 offset:59936
	s_waitcnt lgkmcnt(4)
	v_mfma_f32_32x32x16_bf16 v[2:17], v[176:179], v[180:183], v[2:17]
	s_waitcnt lgkmcnt(1)
	v_mfma_f32_32x32x16_bf16 v[18:33], v[176:179], v[192:195], v[18:33]
	ds_read_b128 v[176:179], v66 offset:23040
	ds_read_b128 v[200:203], v66 offset:23072
	s_waitcnt lgkmcnt(1)
	v_mfma_f32_32x32x16_bf16 v[34:49], v[176:179], v[180:183], v[34:49]
	v_mfma_f32_32x32x16_bf16 v[50:65], v[176:179], v[192:195], v[50:65]
	v_mfma_f32_32x32x16_bf16 v[2:17], v[184:187], v[188:191], v[2:17]
	v_mfma_f32_32x32x16_bf16 v[18:33], v[184:187], v[196:199], v[18:33]
	s_waitcnt lgkmcnt(0)
	v_mfma_f32_32x32x16_bf16 v[34:49], v[200:203], v[188:191], v[34:49]
	ds_read_b128 v[176:179], v66 offset:18496
	ds_read_b128 v[180:183], v67 offset:55360
	ds_read_b128 v[184:187], v66 offset:18528
	ds_read_b128 v[188:191], v67 offset:55392
	v_mfma_f32_32x32x16_bf16 v[50:65], v[200:203], v[196:199], v[50:65]
	ds_read_b128 v[192:195], v67 offset:59968
	ds_read_b128 v[196:199], v67 offset:60000
	s_waitcnt lgkmcnt(4)
	v_mfma_f32_32x32x16_bf16 v[2:17], v[176:179], v[180:183], v[2:17]
	s_waitcnt lgkmcnt(1)
	v_mfma_f32_32x32x16_bf16 v[18:33], v[176:179], v[192:195], v[18:33]
	ds_read_b128 v[176:179], v66 offset:23104
	ds_read_b128 v[200:203], v66 offset:23136
	s_waitcnt vmcnt(13)
	ds_write_b128 v90, v[152:155]
	ds_write_b128 v90, v[144:147] offset:4608
	ds_write_b128 v90, v[148:151] offset:9216
	s_waitcnt vmcnt(11)
	ds_write_b128 v90, v[160:163] offset:13824
	ds_write_b128 v90, v[156:159] offset:36864
	s_waitcnt vmcnt(10)
	ds_write_b128 v90, v[164:167] offset:41472
	s_waitcnt vmcnt(9)
	ds_write_b128 v90, v[168:171] offset:46080
	s_waitcnt vmcnt(8)
	ds_write_b128 v90, v[172:175] offset:50688
	s_waitcnt lgkmcnt(0)
	s_barrier
	global_load_dwordx4 v[144:147], v[78:79], off offset:768
	global_load_dwordx4 v[148:151], v[80:81], off offset:768
	global_load_dwordx4 v[152:155], v[74:75], off offset:768
	global_load_dwordx4 v[156:159], v[76:77], off offset:768
	global_load_dwordx4 v[160:163], v[82:83], off offset:768
	global_load_dwordx4 v[164:167], v[84:85], off offset:768
	global_load_dwordx4 v[168:171], v[86:87], off offset:768
	global_load_dwordx4 v[172:175], v[88:89], off offset:768
	v_mfma_f32_32x32x16_bf16 v[34:49], v[176:179], v[180:183], v[34:49]
	v_mfma_f32_32x32x16_bf16 v[50:65], v[176:179], v[192:195], v[50:65]
	v_mfma_f32_32x32x16_bf16 v[2:17], v[184:187], v[188:191], v[2:17]
	v_mfma_f32_32x32x16_bf16 v[18:33], v[184:187], v[196:199], v[18:33]
	v_mfma_f32_32x32x16_bf16 v[34:49], v[200:203], v[188:191], v[34:49]
	v_mfma_f32_32x32x16_bf16 v[50:65], v[200:203], v[196:199], v[50:65]
	ds_read_b128 v[176:179], v66
	ds_read_b128 v[180:183], v67 offset:36864
	ds_read_b128 v[184:187], v66 offset:32
	ds_read_b128 v[188:191], v67 offset:36896
	ds_read_b128 v[192:195], v67 offset:41472
	ds_read_b128 v[196:199], v67 offset:41504
	s_waitcnt lgkmcnt(4)
	v_mfma_f32_32x32x16_bf16 v[2:17], v[176:179], v[180:183], v[2:17]
	s_waitcnt lgkmcnt(1)
	v_mfma_f32_32x32x16_bf16 v[18:33], v[176:179], v[192:195], v[18:33]
	ds_read_b128 v[176:179], v66 offset:4608
	ds_read_b128 v[200:203], v66 offset:4640
	s_waitcnt lgkmcnt(1)
	v_mfma_f32_32x32x16_bf16 v[34:49], v[176:179], v[180:183], v[34:49]
	v_mfma_f32_32x32x16_bf16 v[50:65], v[176:179], v[192:195], v[50:65]
	v_mfma_f32_32x32x16_bf16 v[2:17], v[184:187], v[188:191], v[2:17]
	v_mfma_f32_32x32x16_bf16 v[18:33], v[184:187], v[196:199], v[18:33]
	s_waitcnt lgkmcnt(0)
	v_mfma_f32_32x32x16_bf16 v[34:49], v[200:203], v[188:191], v[34:49]
	ds_read_b128 v[176:179], v66 offset:64
	ds_read_b128 v[180:183], v67 offset:36928
	ds_read_b128 v[184:187], v66 offset:96
	ds_read_b128 v[188:191], v67 offset:36960
	v_mfma_f32_32x32x16_bf16 v[50:65], v[200:203], v[196:199], v[50:65]
	ds_read_b128 v[192:195], v67 offset:41536
	ds_read_b128 v[196:199], v67 offset:41568
	s_waitcnt lgkmcnt(4)
	v_mfma_f32_32x32x16_bf16 v[2:17], v[176:179], v[180:183], v[2:17]
	s_waitcnt lgkmcnt(1)
	v_mfma_f32_32x32x16_bf16 v[18:33], v[176:179], v[192:195], v[18:33]
	ds_read_b128 v[176:179], v66 offset:4672
	ds_read_b128 v[200:203], v66 offset:4704
	s_waitcnt vmcnt(13)
	ds_write_b128 v90, v[120:123] offset:18432
	ds_write_b128 v90, v[112:115] offset:23040
	ds_write_b128 v90, v[116:119] offset:27648
	s_waitcnt vmcnt(11)
	ds_write_b128 v90, v[128:131] offset:32256
	ds_write_b128 v90, v[124:127] offset:55296
	s_waitcnt vmcnt(10)
	ds_write_b128 v90, v[132:135] offset:59904
	s_waitcnt vmcnt(9)
	ds_write_b128 v90, v[136:139] offset:64512
	s_waitcnt vmcnt(8)
	ds_write_b128 v91, v[140:143] offset:32256
	s_waitcnt lgkmcnt(0)
	s_barrier
	global_load_dwordx4 v[112:115], v[78:79], off offset:896
	global_load_dwordx4 v[116:119], v[80:81], off offset:896
	global_load_dwordx4 v[120:123], v[74:75], off offset:896
	global_load_dwordx4 v[124:127], v[76:77], off offset:896
	global_load_dwordx4 v[128:131], v[82:83], off offset:896
	global_load_dwordx4 v[132:135], v[84:85], off offset:896
	global_load_dwordx4 v[136:139], v[86:87], off offset:896
	global_load_dwordx4 v[140:143], v[88:89], off offset:896
	v_mfma_f32_32x32x16_bf16 v[34:49], v[176:179], v[180:183], v[34:49]
	v_mfma_f32_32x32x16_bf16 v[50:65], v[176:179], v[192:195], v[50:65]
	v_mfma_f32_32x32x16_bf16 v[2:17], v[184:187], v[188:191], v[2:17]
	v_mfma_f32_32x32x16_bf16 v[18:33], v[184:187], v[196:199], v[18:33]
	v_mfma_f32_32x32x16_bf16 v[34:49], v[200:203], v[188:191], v[34:49]
	v_mfma_f32_32x32x16_bf16 v[50:65], v[200:203], v[196:199], v[50:65]
	ds_read_b128 v[176:179], v66 offset:18432
	ds_read_b128 v[180:183], v67 offset:55296
	ds_read_b128 v[184:187], v66 offset:18464
	ds_read_b128 v[188:191], v67 offset:55328
	ds_read_b128 v[192:195], v67 offset:59904
	ds_read_b128 v[196:199], v67 offset:59936
	s_waitcnt lgkmcnt(4)
	v_mfma_f32_32x32x16_bf16 v[2:17], v[176:179], v[180:183], v[2:17]
	s_waitcnt lgkmcnt(1)
	v_mfma_f32_32x32x16_bf16 v[18:33], v[176:179], v[192:195], v[18:33]
	ds_read_b128 v[176:179], v66 offset:23040
	ds_read_b128 v[200:203], v66 offset:23072
	s_waitcnt lgkmcnt(1)
	v_mfma_f32_32x32x16_bf16 v[34:49], v[176:179], v[180:183], v[34:49]
	v_mfma_f32_32x32x16_bf16 v[50:65], v[176:179], v[192:195], v[50:65]
	v_mfma_f32_32x32x16_bf16 v[2:17], v[184:187], v[188:191], v[2:17]
	v_mfma_f32_32x32x16_bf16 v[18:33], v[184:187], v[196:199], v[18:33]
	s_waitcnt lgkmcnt(0)
	v_mfma_f32_32x32x16_bf16 v[34:49], v[200:203], v[188:191], v[34:49]
	ds_read_b128 v[176:179], v66 offset:18496
	ds_read_b128 v[180:183], v67 offset:55360
	ds_read_b128 v[184:187], v66 offset:18528
	ds_read_b128 v[188:191], v67 offset:55392
	v_mfma_f32_32x32x16_bf16 v[50:65], v[200:203], v[196:199], v[50:65]
	ds_read_b128 v[192:195], v67 offset:59968
	ds_read_b128 v[196:199], v67 offset:60000
	s_waitcnt lgkmcnt(4)
	v_mfma_f32_32x32x16_bf16 v[2:17], v[176:179], v[180:183], v[2:17]
	s_waitcnt lgkmcnt(1)
	v_mfma_f32_32x32x16_bf16 v[18:33], v[176:179], v[192:195], v[18:33]
	ds_read_b128 v[176:179], v66 offset:23104
	ds_read_b128 v[200:203], v66 offset:23136
	s_waitcnt vmcnt(13)
	ds_write_b128 v90, v[152:155]
	ds_write_b128 v90, v[144:147] offset:4608
	ds_write_b128 v90, v[148:151] offset:9216
	s_waitcnt vmcnt(11)
	ds_write_b128 v90, v[160:163] offset:13824
	ds_write_b128 v90, v[156:159] offset:36864
	s_waitcnt vmcnt(10)
	ds_write_b128 v90, v[164:167] offset:41472
	s_waitcnt vmcnt(9)
	ds_write_b128 v90, v[168:171] offset:46080
	s_waitcnt vmcnt(8)
	ds_write_b128 v90, v[172:175] offset:50688
	s_waitcnt lgkmcnt(0)
	s_barrier
	global_load_dwordx4 v[144:147], v[78:79], off offset:1024
	global_load_dwordx4 v[148:151], v[80:81], off offset:1024
	global_load_dwordx4 v[152:155], v[74:75], off offset:1024
	global_load_dwordx4 v[156:159], v[76:77], off offset:1024
	global_load_dwordx4 v[160:163], v[82:83], off offset:1024
	global_load_dwordx4 v[164:167], v[84:85], off offset:1024
	global_load_dwordx4 v[168:171], v[86:87], off offset:1024
	global_load_dwordx4 v[172:175], v[88:89], off offset:1024
	v_mfma_f32_32x32x16_bf16 v[34:49], v[176:179], v[180:183], v[34:49]
	v_mfma_f32_32x32x16_bf16 v[50:65], v[176:179], v[192:195], v[50:65]
	v_mfma_f32_32x32x16_bf16 v[2:17], v[184:187], v[188:191], v[2:17]
	v_mfma_f32_32x32x16_bf16 v[18:33], v[184:187], v[196:199], v[18:33]
	v_mfma_f32_32x32x16_bf16 v[34:49], v[200:203], v[188:191], v[34:49]
	v_mfma_f32_32x32x16_bf16 v[50:65], v[200:203], v[196:199], v[50:65]
	ds_read_b128 v[176:179], v66
	ds_read_b128 v[180:183], v67 offset:36864
	ds_read_b128 v[184:187], v66 offset:32
	ds_read_b128 v[188:191], v67 offset:36896
	ds_read_b128 v[192:195], v67 offset:41472
	ds_read_b128 v[196:199], v67 offset:41504
	s_waitcnt lgkmcnt(4)
	v_mfma_f32_32x32x16_bf16 v[2:17], v[176:179], v[180:183], v[2:17]
	s_waitcnt lgkmcnt(1)
	v_mfma_f32_32x32x16_bf16 v[18:33], v[176:179], v[192:195], v[18:33]
	ds_read_b128 v[176:179], v66 offset:4608
	ds_read_b128 v[200:203], v66 offset:4640
	s_waitcnt lgkmcnt(1)
	v_mfma_f32_32x32x16_bf16 v[34:49], v[176:179], v[180:183], v[34:49]
	v_mfma_f32_32x32x16_bf16 v[50:65], v[176:179], v[192:195], v[50:65]
	v_mfma_f32_32x32x16_bf16 v[2:17], v[184:187], v[188:191], v[2:17]
	v_mfma_f32_32x32x16_bf16 v[18:33], v[184:187], v[196:199], v[18:33]
	s_waitcnt lgkmcnt(0)
	v_mfma_f32_32x32x16_bf16 v[34:49], v[200:203], v[188:191], v[34:49]
	ds_read_b128 v[176:179], v66 offset:64
	ds_read_b128 v[180:183], v67 offset:36928
	ds_read_b128 v[184:187], v66 offset:96
	ds_read_b128 v[188:191], v67 offset:36960
	v_mfma_f32_32x32x16_bf16 v[50:65], v[200:203], v[196:199], v[50:65]
	ds_read_b128 v[192:195], v67 offset:41536
	ds_read_b128 v[196:199], v67 offset:41568
	s_waitcnt lgkmcnt(4)
	v_mfma_f32_32x32x16_bf16 v[2:17], v[176:179], v[180:183], v[2:17]
	s_waitcnt lgkmcnt(1)
	v_mfma_f32_32x32x16_bf16 v[18:33], v[176:179], v[192:195], v[18:33]
	ds_read_b128 v[176:179], v66 offset:4672
	ds_read_b128 v[200:203], v66 offset:4704
	s_waitcnt vmcnt(13)
	ds_write_b128 v90, v[120:123] offset:18432
	ds_write_b128 v90, v[112:115] offset:23040
	ds_write_b128 v90, v[116:119] offset:27648
	s_waitcnt vmcnt(11)
	ds_write_b128 v90, v[128:131] offset:32256
	ds_write_b128 v90, v[124:127] offset:55296
	s_waitcnt vmcnt(10)
	ds_write_b128 v90, v[132:135] offset:59904
	s_waitcnt vmcnt(9)
	ds_write_b128 v90, v[136:139] offset:64512
	s_waitcnt vmcnt(8)
	ds_write_b128 v91, v[140:143] offset:32256
	s_waitcnt lgkmcnt(0)
	s_barrier
	global_load_dwordx4 v[112:115], v[78:79], off offset:1152
	global_load_dwordx4 v[116:119], v[80:81], off offset:1152
	global_load_dwordx4 v[120:123], v[74:75], off offset:1152
	global_load_dwordx4 v[124:127], v[76:77], off offset:1152
	global_load_dwordx4 v[128:131], v[82:83], off offset:1152
	global_load_dwordx4 v[132:135], v[84:85], off offset:1152
	global_load_dwordx4 v[136:139], v[86:87], off offset:1152
	global_load_dwordx4 v[140:143], v[88:89], off offset:1152
	v_mfma_f32_32x32x16_bf16 v[34:49], v[176:179], v[180:183], v[34:49]
	v_mfma_f32_32x32x16_bf16 v[50:65], v[176:179], v[192:195], v[50:65]
	v_mfma_f32_32x32x16_bf16 v[2:17], v[184:187], v[188:191], v[2:17]
	v_mfma_f32_32x32x16_bf16 v[18:33], v[184:187], v[196:199], v[18:33]
	v_mfma_f32_32x32x16_bf16 v[34:49], v[200:203], v[188:191], v[34:49]
	v_mfma_f32_32x32x16_bf16 v[50:65], v[200:203], v[196:199], v[50:65]
	ds_read_b128 v[176:179], v66 offset:18432
	ds_read_b128 v[180:183], v67 offset:55296
	ds_read_b128 v[184:187], v66 offset:18464
	ds_read_b128 v[188:191], v67 offset:55328
	ds_read_b128 v[192:195], v67 offset:59904
	ds_read_b128 v[196:199], v67 offset:59936
	s_waitcnt lgkmcnt(4)
	v_mfma_f32_32x32x16_bf16 v[2:17], v[176:179], v[180:183], v[2:17]
	s_waitcnt lgkmcnt(1)
	v_mfma_f32_32x32x16_bf16 v[18:33], v[176:179], v[192:195], v[18:33]
	ds_read_b128 v[176:179], v66 offset:23040
	ds_read_b128 v[200:203], v66 offset:23072
	s_waitcnt lgkmcnt(1)
	v_mfma_f32_32x32x16_bf16 v[34:49], v[176:179], v[180:183], v[34:49]
	v_mfma_f32_32x32x16_bf16 v[50:65], v[176:179], v[192:195], v[50:65]
	v_mfma_f32_32x32x16_bf16 v[2:17], v[184:187], v[188:191], v[2:17]
	v_mfma_f32_32x32x16_bf16 v[18:33], v[184:187], v[196:199], v[18:33]
	s_waitcnt lgkmcnt(0)
	v_mfma_f32_32x32x16_bf16 v[34:49], v[200:203], v[188:191], v[34:49]
	ds_read_b128 v[176:179], v66 offset:18496
	ds_read_b128 v[180:183], v67 offset:55360
	ds_read_b128 v[184:187], v66 offset:18528
	ds_read_b128 v[188:191], v67 offset:55392
	v_mfma_f32_32x32x16_bf16 v[50:65], v[200:203], v[196:199], v[50:65]
	ds_read_b128 v[192:195], v67 offset:59968
	ds_read_b128 v[196:199], v67 offset:60000
	s_waitcnt lgkmcnt(4)
	v_mfma_f32_32x32x16_bf16 v[2:17], v[176:179], v[180:183], v[2:17]
	s_waitcnt lgkmcnt(1)
	v_mfma_f32_32x32x16_bf16 v[18:33], v[176:179], v[192:195], v[18:33]
	ds_read_b128 v[176:179], v66 offset:23104
	ds_read_b128 v[200:203], v66 offset:23136
	s_waitcnt vmcnt(13)
	ds_write_b128 v90, v[152:155]
	ds_write_b128 v90, v[144:147] offset:4608
	ds_write_b128 v90, v[148:151] offset:9216
	s_waitcnt vmcnt(11)
	ds_write_b128 v90, v[160:163] offset:13824
	ds_write_b128 v90, v[156:159] offset:36864
	s_waitcnt vmcnt(10)
	ds_write_b128 v90, v[164:167] offset:41472
	s_waitcnt vmcnt(9)
	ds_write_b128 v90, v[168:171] offset:46080
	s_waitcnt vmcnt(8)
	ds_write_b128 v90, v[172:175] offset:50688
	s_waitcnt lgkmcnt(0)
	s_barrier
	global_load_dwordx4 v[144:147], v[78:79], off offset:1280
	global_load_dwordx4 v[148:151], v[80:81], off offset:1280
	global_load_dwordx4 v[152:155], v[74:75], off offset:1280
	global_load_dwordx4 v[156:159], v[76:77], off offset:1280
	global_load_dwordx4 v[160:163], v[82:83], off offset:1280
	global_load_dwordx4 v[164:167], v[84:85], off offset:1280
	global_load_dwordx4 v[168:171], v[86:87], off offset:1280
	global_load_dwordx4 v[172:175], v[88:89], off offset:1280
	v_mfma_f32_32x32x16_bf16 v[34:49], v[176:179], v[180:183], v[34:49]
	v_mfma_f32_32x32x16_bf16 v[50:65], v[176:179], v[192:195], v[50:65]
	v_mfma_f32_32x32x16_bf16 v[2:17], v[184:187], v[188:191], v[2:17]
	v_mfma_f32_32x32x16_bf16 v[18:33], v[184:187], v[196:199], v[18:33]
	v_mfma_f32_32x32x16_bf16 v[34:49], v[200:203], v[188:191], v[34:49]
	v_mfma_f32_32x32x16_bf16 v[50:65], v[200:203], v[196:199], v[50:65]
	ds_read_b128 v[176:179], v66
	ds_read_b128 v[180:183], v67 offset:36864
	ds_read_b128 v[184:187], v66 offset:32
	ds_read_b128 v[188:191], v67 offset:36896
	ds_read_b128 v[192:195], v67 offset:41472
	ds_read_b128 v[196:199], v67 offset:41504
	s_waitcnt lgkmcnt(4)
	v_mfma_f32_32x32x16_bf16 v[2:17], v[176:179], v[180:183], v[2:17]
	s_waitcnt lgkmcnt(1)
	v_mfma_f32_32x32x16_bf16 v[18:33], v[176:179], v[192:195], v[18:33]
	ds_read_b128 v[176:179], v66 offset:4608
	ds_read_b128 v[200:203], v66 offset:4640
	s_waitcnt lgkmcnt(1)
	v_mfma_f32_32x32x16_bf16 v[34:49], v[176:179], v[180:183], v[34:49]
	v_mfma_f32_32x32x16_bf16 v[50:65], v[176:179], v[192:195], v[50:65]
	v_mfma_f32_32x32x16_bf16 v[2:17], v[184:187], v[188:191], v[2:17]
	v_mfma_f32_32x32x16_bf16 v[18:33], v[184:187], v[196:199], v[18:33]
	s_waitcnt lgkmcnt(0)
	v_mfma_f32_32x32x16_bf16 v[34:49], v[200:203], v[188:191], v[34:49]
	ds_read_b128 v[176:179], v66 offset:64
	ds_read_b128 v[180:183], v67 offset:36928
	ds_read_b128 v[184:187], v66 offset:96
	ds_read_b128 v[188:191], v67 offset:36960
	v_mfma_f32_32x32x16_bf16 v[50:65], v[200:203], v[196:199], v[50:65]
	ds_read_b128 v[192:195], v67 offset:41536
	ds_read_b128 v[196:199], v67 offset:41568
	s_waitcnt lgkmcnt(4)
	v_mfma_f32_32x32x16_bf16 v[2:17], v[176:179], v[180:183], v[2:17]
	s_waitcnt lgkmcnt(1)
	v_mfma_f32_32x32x16_bf16 v[18:33], v[176:179], v[192:195], v[18:33]
	ds_read_b128 v[176:179], v66 offset:4672
	ds_read_b128 v[200:203], v66 offset:4704
	s_waitcnt vmcnt(13)
	ds_write_b128 v90, v[120:123] offset:18432
	ds_write_b128 v90, v[112:115] offset:23040
	ds_write_b128 v90, v[116:119] offset:27648
	s_waitcnt vmcnt(11)
	ds_write_b128 v90, v[128:131] offset:32256
	ds_write_b128 v90, v[124:127] offset:55296
	s_waitcnt vmcnt(10)
	ds_write_b128 v90, v[132:135] offset:59904
	s_waitcnt vmcnt(9)
	ds_write_b128 v90, v[136:139] offset:64512
	s_waitcnt vmcnt(8)
	ds_write_b128 v91, v[140:143] offset:32256
	s_waitcnt lgkmcnt(0)
	s_barrier
	global_load_dwordx4 v[112:115], v[78:79], off offset:1408
	global_load_dwordx4 v[116:119], v[80:81], off offset:1408
	global_load_dwordx4 v[120:123], v[74:75], off offset:1408
	global_load_dwordx4 v[124:127], v[76:77], off offset:1408
	global_load_dwordx4 v[128:131], v[82:83], off offset:1408
	global_load_dwordx4 v[132:135], v[84:85], off offset:1408
	global_load_dwordx4 v[136:139], v[86:87], off offset:1408
	global_load_dwordx4 v[140:143], v[88:89], off offset:1408
	v_mfma_f32_32x32x16_bf16 v[34:49], v[176:179], v[180:183], v[34:49]
	v_mfma_f32_32x32x16_bf16 v[50:65], v[176:179], v[192:195], v[50:65]
	v_mfma_f32_32x32x16_bf16 v[2:17], v[184:187], v[188:191], v[2:17]
	v_mfma_f32_32x32x16_bf16 v[18:33], v[184:187], v[196:199], v[18:33]
	v_mfma_f32_32x32x16_bf16 v[34:49], v[200:203], v[188:191], v[34:49]
	v_mfma_f32_32x32x16_bf16 v[50:65], v[200:203], v[196:199], v[50:65]
	ds_read_b128 v[176:179], v66 offset:18432
	ds_read_b128 v[180:183], v67 offset:55296
	ds_read_b128 v[184:187], v66 offset:18464
	ds_read_b128 v[188:191], v67 offset:55328
	ds_read_b128 v[192:195], v67 offset:59904
	ds_read_b128 v[196:199], v67 offset:59936
	s_waitcnt lgkmcnt(4)
	v_mfma_f32_32x32x16_bf16 v[2:17], v[176:179], v[180:183], v[2:17]
	s_waitcnt lgkmcnt(1)
	v_mfma_f32_32x32x16_bf16 v[18:33], v[176:179], v[192:195], v[18:33]
	ds_read_b128 v[176:179], v66 offset:23040
	ds_read_b128 v[200:203], v66 offset:23072
	s_waitcnt lgkmcnt(1)
	v_mfma_f32_32x32x16_bf16 v[34:49], v[176:179], v[180:183], v[34:49]
	v_mfma_f32_32x32x16_bf16 v[50:65], v[176:179], v[192:195], v[50:65]
	v_mfma_f32_32x32x16_bf16 v[2:17], v[184:187], v[188:191], v[2:17]
	v_mfma_f32_32x32x16_bf16 v[18:33], v[184:187], v[196:199], v[18:33]
	s_waitcnt lgkmcnt(0)
	v_mfma_f32_32x32x16_bf16 v[34:49], v[200:203], v[188:191], v[34:49]
	ds_read_b128 v[176:179], v66 offset:18496
	ds_read_b128 v[180:183], v67 offset:55360
	ds_read_b128 v[184:187], v66 offset:18528
	ds_read_b128 v[188:191], v67 offset:55392
	v_mfma_f32_32x32x16_bf16 v[50:65], v[200:203], v[196:199], v[50:65]
	ds_read_b128 v[192:195], v67 offset:59968
	ds_read_b128 v[196:199], v67 offset:60000
	s_waitcnt lgkmcnt(4)
	v_mfma_f32_32x32x16_bf16 v[2:17], v[176:179], v[180:183], v[2:17]
	s_waitcnt lgkmcnt(1)
	v_mfma_f32_32x32x16_bf16 v[18:33], v[176:179], v[192:195], v[18:33]
	ds_read_b128 v[176:179], v66 offset:23104
	ds_read_b128 v[200:203], v66 offset:23136
	s_waitcnt vmcnt(13)
	ds_write_b128 v90, v[152:155]
	ds_write_b128 v90, v[144:147] offset:4608
	ds_write_b128 v90, v[148:151] offset:9216
	s_waitcnt vmcnt(11)
	ds_write_b128 v90, v[160:163] offset:13824
	ds_write_b128 v90, v[156:159] offset:36864
	s_waitcnt vmcnt(10)
	ds_write_b128 v90, v[164:167] offset:41472
	s_waitcnt vmcnt(9)
	ds_write_b128 v90, v[168:171] offset:46080
	s_waitcnt vmcnt(8)
	ds_write_b128 v90, v[172:175] offset:50688
	s_waitcnt lgkmcnt(0)
	s_barrier
	global_load_dwordx4 v[144:147], v[78:79], off offset:1536
	global_load_dwordx4 v[148:151], v[80:81], off offset:1536
	global_load_dwordx4 v[152:155], v[74:75], off offset:1536
	global_load_dwordx4 v[156:159], v[76:77], off offset:1536
	global_load_dwordx4 v[160:163], v[82:83], off offset:1536
	global_load_dwordx4 v[164:167], v[84:85], off offset:1536
	global_load_dwordx4 v[168:171], v[86:87], off offset:1536
	global_load_dwordx4 v[172:175], v[88:89], off offset:1536
	v_mfma_f32_32x32x16_bf16 v[34:49], v[176:179], v[180:183], v[34:49]
	v_mfma_f32_32x32x16_bf16 v[50:65], v[176:179], v[192:195], v[50:65]
	v_mfma_f32_32x32x16_bf16 v[2:17], v[184:187], v[188:191], v[2:17]
	v_mfma_f32_32x32x16_bf16 v[18:33], v[184:187], v[196:199], v[18:33]
	v_mfma_f32_32x32x16_bf16 v[34:49], v[200:203], v[188:191], v[34:49]
	v_mfma_f32_32x32x16_bf16 v[50:65], v[200:203], v[196:199], v[50:65]
	ds_read_b128 v[176:179], v66
	ds_read_b128 v[180:183], v67 offset:36864
	ds_read_b128 v[184:187], v66 offset:32
	ds_read_b128 v[188:191], v67 offset:36896
	ds_read_b128 v[192:195], v67 offset:41472
	ds_read_b128 v[196:199], v67 offset:41504
	s_waitcnt lgkmcnt(4)
	v_mfma_f32_32x32x16_bf16 v[2:17], v[176:179], v[180:183], v[2:17]
	s_waitcnt lgkmcnt(1)
	v_mfma_f32_32x32x16_bf16 v[18:33], v[176:179], v[192:195], v[18:33]
	ds_read_b128 v[176:179], v66 offset:4608
	ds_read_b128 v[200:203], v66 offset:4640
	s_waitcnt lgkmcnt(1)
	v_mfma_f32_32x32x16_bf16 v[34:49], v[176:179], v[180:183], v[34:49]
	v_mfma_f32_32x32x16_bf16 v[50:65], v[176:179], v[192:195], v[50:65]
	v_mfma_f32_32x32x16_bf16 v[2:17], v[184:187], v[188:191], v[2:17]
	v_mfma_f32_32x32x16_bf16 v[18:33], v[184:187], v[196:199], v[18:33]
	s_waitcnt lgkmcnt(0)
	v_mfma_f32_32x32x16_bf16 v[34:49], v[200:203], v[188:191], v[34:49]
	ds_read_b128 v[176:179], v66 offset:64
	ds_read_b128 v[180:183], v67 offset:36928
	ds_read_b128 v[184:187], v66 offset:96
	ds_read_b128 v[188:191], v67 offset:36960
	v_mfma_f32_32x32x16_bf16 v[50:65], v[200:203], v[196:199], v[50:65]
	ds_read_b128 v[192:195], v67 offset:41536
	ds_read_b128 v[196:199], v67 offset:41568
	s_waitcnt lgkmcnt(4)
	v_mfma_f32_32x32x16_bf16 v[2:17], v[176:179], v[180:183], v[2:17]
	s_waitcnt lgkmcnt(1)
	v_mfma_f32_32x32x16_bf16 v[18:33], v[176:179], v[192:195], v[18:33]
	ds_read_b128 v[176:179], v66 offset:4672
	ds_read_b128 v[200:203], v66 offset:4704
	s_waitcnt vmcnt(13)
	ds_write_b128 v90, v[120:123] offset:18432
	ds_write_b128 v90, v[112:115] offset:23040
	ds_write_b128 v90, v[116:119] offset:27648
	s_waitcnt vmcnt(11)
	ds_write_b128 v90, v[128:131] offset:32256
	ds_write_b128 v90, v[124:127] offset:55296
	s_waitcnt vmcnt(10)
	ds_write_b128 v90, v[132:135] offset:59904
	s_waitcnt vmcnt(9)
	ds_write_b128 v90, v[136:139] offset:64512
	s_waitcnt vmcnt(8)
	ds_write_b128 v91, v[140:143] offset:32256
	s_waitcnt lgkmcnt(0)
	s_barrier
	global_load_dwordx4 v[112:115], v[78:79], off offset:1664
	global_load_dwordx4 v[116:119], v[80:81], off offset:1664
	global_load_dwordx4 v[120:123], v[74:75], off offset:1664
	global_load_dwordx4 v[124:127], v[76:77], off offset:1664
	global_load_dwordx4 v[128:131], v[82:83], off offset:1664
	global_load_dwordx4 v[132:135], v[84:85], off offset:1664
	global_load_dwordx4 v[136:139], v[86:87], off offset:1664
	global_load_dwordx4 v[140:143], v[88:89], off offset:1664
	v_mfma_f32_32x32x16_bf16 v[34:49], v[176:179], v[180:183], v[34:49]
	v_mfma_f32_32x32x16_bf16 v[50:65], v[176:179], v[192:195], v[50:65]
	v_mfma_f32_32x32x16_bf16 v[2:17], v[184:187], v[188:191], v[2:17]
	v_mfma_f32_32x32x16_bf16 v[18:33], v[184:187], v[196:199], v[18:33]
	v_mfma_f32_32x32x16_bf16 v[34:49], v[200:203], v[188:191], v[34:49]
	v_mfma_f32_32x32x16_bf16 v[50:65], v[200:203], v[196:199], v[50:65]
	ds_read_b128 v[176:179], v66 offset:18432
	ds_read_b128 v[180:183], v67 offset:55296
	ds_read_b128 v[184:187], v66 offset:18464
	ds_read_b128 v[188:191], v67 offset:55328
	ds_read_b128 v[192:195], v67 offset:59904
	ds_read_b128 v[196:199], v67 offset:59936
	s_waitcnt lgkmcnt(4)
	v_mfma_f32_32x32x16_bf16 v[2:17], v[176:179], v[180:183], v[2:17]
	s_waitcnt lgkmcnt(1)
	v_mfma_f32_32x32x16_bf16 v[18:33], v[176:179], v[192:195], v[18:33]
	ds_read_b128 v[176:179], v66 offset:23040
	ds_read_b128 v[200:203], v66 offset:23072
	s_waitcnt lgkmcnt(1)
	v_mfma_f32_32x32x16_bf16 v[34:49], v[176:179], v[180:183], v[34:49]
	v_mfma_f32_32x32x16_bf16 v[50:65], v[176:179], v[192:195], v[50:65]
	v_mfma_f32_32x32x16_bf16 v[2:17], v[184:187], v[188:191], v[2:17]
	v_mfma_f32_32x32x16_bf16 v[18:33], v[184:187], v[196:199], v[18:33]
	s_waitcnt lgkmcnt(0)
	v_mfma_f32_32x32x16_bf16 v[34:49], v[200:203], v[188:191], v[34:49]
	ds_read_b128 v[176:179], v66 offset:18496
	ds_read_b128 v[180:183], v67 offset:55360
	ds_read_b128 v[184:187], v66 offset:18528
	ds_read_b128 v[188:191], v67 offset:55392
	v_mfma_f32_32x32x16_bf16 v[50:65], v[200:203], v[196:199], v[50:65]
	ds_read_b128 v[192:195], v67 offset:59968
	ds_read_b128 v[196:199], v67 offset:60000
	s_waitcnt lgkmcnt(4)
	v_mfma_f32_32x32x16_bf16 v[2:17], v[176:179], v[180:183], v[2:17]
	s_waitcnt lgkmcnt(1)
	v_mfma_f32_32x32x16_bf16 v[18:33], v[176:179], v[192:195], v[18:33]
	ds_read_b128 v[176:179], v66 offset:23104
	ds_read_b128 v[200:203], v66 offset:23136
	s_waitcnt vmcnt(13)
	ds_write_b128 v90, v[152:155]
	ds_write_b128 v90, v[144:147] offset:4608
	ds_write_b128 v90, v[148:151] offset:9216
	s_waitcnt vmcnt(11)
	ds_write_b128 v90, v[160:163] offset:13824
	ds_write_b128 v90, v[156:159] offset:36864
	s_waitcnt vmcnt(10)
	ds_write_b128 v90, v[164:167] offset:41472
	s_waitcnt vmcnt(9)
	ds_write_b128 v90, v[168:171] offset:46080
	s_waitcnt vmcnt(8)
	ds_write_b128 v90, v[172:175] offset:50688
	s_waitcnt lgkmcnt(0)
	s_barrier
	global_load_dwordx4 v[144:147], v[78:79], off offset:1792
	global_load_dwordx4 v[148:151], v[80:81], off offset:1792
	global_load_dwordx4 v[152:155], v[74:75], off offset:1792
	global_load_dwordx4 v[156:159], v[76:77], off offset:1792
	global_load_dwordx4 v[160:163], v[82:83], off offset:1792
	global_load_dwordx4 v[164:167], v[84:85], off offset:1792
	global_load_dwordx4 v[168:171], v[86:87], off offset:1792
	global_load_dwordx4 v[172:175], v[88:89], off offset:1792
	v_mfma_f32_32x32x16_bf16 v[34:49], v[176:179], v[180:183], v[34:49]
	v_mfma_f32_32x32x16_bf16 v[50:65], v[176:179], v[192:195], v[50:65]
	v_mfma_f32_32x32x16_bf16 v[2:17], v[184:187], v[188:191], v[2:17]
	v_mfma_f32_32x32x16_bf16 v[18:33], v[184:187], v[196:199], v[18:33]
	v_mfma_f32_32x32x16_bf16 v[34:49], v[200:203], v[188:191], v[34:49]
	v_mfma_f32_32x32x16_bf16 v[50:65], v[200:203], v[196:199], v[50:65]
	ds_read_b128 v[176:179], v66
	ds_read_b128 v[180:183], v67 offset:36864
	ds_read_b128 v[184:187], v66 offset:32
	ds_read_b128 v[188:191], v67 offset:36896
	ds_read_b128 v[192:195], v67 offset:41472
	ds_read_b128 v[196:199], v67 offset:41504
	s_waitcnt lgkmcnt(4)
	v_mfma_f32_32x32x16_bf16 v[2:17], v[176:179], v[180:183], v[2:17]
	s_waitcnt lgkmcnt(1)
	v_mfma_f32_32x32x16_bf16 v[18:33], v[176:179], v[192:195], v[18:33]
	ds_read_b128 v[176:179], v66 offset:4608
	ds_read_b128 v[200:203], v66 offset:4640
	s_waitcnt lgkmcnt(1)
	v_mfma_f32_32x32x16_bf16 v[34:49], v[176:179], v[180:183], v[34:49]
	v_mfma_f32_32x32x16_bf16 v[50:65], v[176:179], v[192:195], v[50:65]
	v_mfma_f32_32x32x16_bf16 v[2:17], v[184:187], v[188:191], v[2:17]
	v_mfma_f32_32x32x16_bf16 v[18:33], v[184:187], v[196:199], v[18:33]
	s_waitcnt lgkmcnt(0)
	v_mfma_f32_32x32x16_bf16 v[34:49], v[200:203], v[188:191], v[34:49]
	ds_read_b128 v[176:179], v66 offset:64
	ds_read_b128 v[180:183], v67 offset:36928
	ds_read_b128 v[184:187], v66 offset:96
	ds_read_b128 v[188:191], v67 offset:36960
	v_mfma_f32_32x32x16_bf16 v[50:65], v[200:203], v[196:199], v[50:65]
	ds_read_b128 v[192:195], v67 offset:41536
	ds_read_b128 v[196:199], v67 offset:41568
	s_waitcnt lgkmcnt(4)
	v_mfma_f32_32x32x16_bf16 v[2:17], v[176:179], v[180:183], v[2:17]
	s_waitcnt lgkmcnt(1)
	v_mfma_f32_32x32x16_bf16 v[18:33], v[176:179], v[192:195], v[18:33]
	ds_read_b128 v[176:179], v66 offset:4672
	ds_read_b128 v[200:203], v66 offset:4704
	s_waitcnt vmcnt(13)
	ds_write_b128 v90, v[120:123] offset:18432
	ds_write_b128 v90, v[112:115] offset:23040
	ds_write_b128 v90, v[116:119] offset:27648
	s_waitcnt vmcnt(11)
	ds_write_b128 v90, v[128:131] offset:32256
	ds_write_b128 v90, v[124:127] offset:55296
	s_waitcnt vmcnt(10)
	ds_write_b128 v90, v[132:135] offset:59904
	s_waitcnt vmcnt(9)
	ds_write_b128 v90, v[136:139] offset:64512
	s_waitcnt vmcnt(8)
	ds_write_b128 v91, v[140:143] offset:32256
	s_waitcnt lgkmcnt(0)
	s_barrier
	global_load_dwordx4 v[112:115], v[78:79], off offset:1920
	s_nop 0
	global_load_dwordx4 v[78:81], v[80:81], off offset:1920
	s_nop 0
	global_load_dwordx4 v[116:119], v[74:75], off offset:1920
	s_nop 0
	global_load_dwordx4 v[74:77], v[76:77], off offset:1920
	s_nop 0
	global_load_dwordx4 v[120:123], v[82:83], off offset:1920
	s_nop 0
	global_load_dwordx4 v[82:85], v[84:85], off offset:1920
	s_nop 0
	global_load_dwordx4 v[124:127], v[86:87], off offset:1920
	s_nop 0
	global_load_dwordx4 v[86:89], v[88:89], off offset:1920
	v_mfma_f32_32x32x16_bf16 v[34:49], v[176:179], v[180:183], v[34:49]
	v_mfma_f32_32x32x16_bf16 v[50:65], v[176:179], v[192:195], v[50:65]
	v_mfma_f32_32x32x16_bf16 v[2:17], v[184:187], v[188:191], v[2:17]
	v_mfma_f32_32x32x16_bf16 v[18:33], v[184:187], v[196:199], v[18:33]
	v_mfma_f32_32x32x16_bf16 v[34:49], v[200:203], v[188:191], v[34:49]
	v_mfma_f32_32x32x16_bf16 v[50:65], v[200:203], v[196:199], v[50:65]
	ds_read_b128 v[128:131], v66 offset:18432
	ds_read_b128 v[132:135], v67 offset:55296
	ds_read_b128 v[136:139], v66 offset:18464
	ds_read_b128 v[140:143], v67 offset:55328
	ds_read_b128 v[176:179], v67 offset:59904
	ds_read_b128 v[180:183], v67 offset:59936
	s_waitcnt lgkmcnt(4)
	v_mfma_f32_32x32x16_bf16 v[2:17], v[128:131], v[132:135], v[2:17]
	s_waitcnt lgkmcnt(1)
	v_mfma_f32_32x32x16_bf16 v[18:33], v[128:131], v[176:179], v[18:33]
	ds_read_b128 v[128:131], v66 offset:23040
	ds_read_b128 v[184:187], v66 offset:23072
	s_waitcnt lgkmcnt(1)
	v_mfma_f32_32x32x16_bf16 v[34:49], v[128:131], v[132:135], v[34:49]
	v_mfma_f32_32x32x16_bf16 v[50:65], v[128:131], v[176:179], v[50:65]
	v_mfma_f32_32x32x16_bf16 v[2:17], v[136:139], v[140:143], v[2:17]
	v_mfma_f32_32x32x16_bf16 v[18:33], v[136:139], v[180:183], v[18:33]
	s_waitcnt lgkmcnt(0)
	v_mfma_f32_32x32x16_bf16 v[34:49], v[184:187], v[140:143], v[34:49]
	ds_read_b128 v[128:131], v66 offset:18496
	ds_read_b128 v[132:135], v67 offset:55360
	ds_read_b128 v[136:139], v66 offset:18528
	ds_read_b128 v[140:143], v67 offset:55392
	v_mfma_f32_32x32x16_bf16 v[50:65], v[184:187], v[180:183], v[50:65]
	ds_read_b128 v[176:179], v67 offset:59968
	ds_read_b128 v[180:183], v67 offset:60000
	s_waitcnt lgkmcnt(4)
	v_mfma_f32_32x32x16_bf16 v[2:17], v[128:131], v[132:135], v[2:17]
	s_waitcnt lgkmcnt(1)
	v_mfma_f32_32x32x16_bf16 v[18:33], v[128:131], v[176:179], v[18:33]
	ds_read_b128 v[128:131], v66 offset:23104
	ds_read_b128 v[184:187], v66 offset:23136
	s_waitcnt vmcnt(13)
	ds_write_b128 v90, v[152:155]
	ds_write_b128 v90, v[144:147] offset:4608
	ds_write_b128 v90, v[148:151] offset:9216
	s_waitcnt vmcnt(11)
	ds_write_b128 v90, v[160:163] offset:13824
	ds_write_b128 v90, v[156:159] offset:36864
	s_waitcnt vmcnt(10)
	ds_write_b128 v90, v[164:167] offset:41472
	s_waitcnt vmcnt(9)
	ds_write_b128 v90, v[168:171] offset:46080
	s_waitcnt vmcnt(8)
	ds_write_b128 v90, v[172:175] offset:50688
	s_waitcnt lgkmcnt(0)
	s_barrier
	v_mfma_f32_32x32x16_bf16 v[34:49], v[128:131], v[132:135], v[34:49]
	v_mfma_f32_32x32x16_bf16 v[50:65], v[128:131], v[176:179], v[50:65]
	v_mfma_f32_32x32x16_bf16 v[2:17], v[136:139], v[140:143], v[2:17]
	v_mfma_f32_32x32x16_bf16 v[18:33], v[136:139], v[180:183], v[18:33]
	v_mfma_f32_32x32x16_bf16 v[34:49], v[184:187], v[140:143], v[34:49]
	v_mfma_f32_32x32x16_bf16 v[50:65], v[184:187], v[180:183], v[50:65]
	ds_read_b128 v[128:131], v66
	ds_read_b128 v[132:135], v67 offset:36864
	ds_read_b128 v[136:139], v66 offset:32
	ds_read_b128 v[140:143], v67 offset:36896
	ds_read_b128 v[144:147], v67 offset:41472
	ds_read_b128 v[148:151], v67 offset:41504
	s_waitcnt lgkmcnt(4)
	v_mfma_f32_32x32x16_bf16 v[2:17], v[128:131], v[132:135], v[2:17]
	s_waitcnt lgkmcnt(1)
	v_mfma_f32_32x32x16_bf16 v[18:33], v[128:131], v[144:147], v[18:33]
	ds_read_b128 v[128:131], v66 offset:4608
	ds_read_b128 v[152:155], v66 offset:4640
	s_waitcnt lgkmcnt(1)
	v_mfma_f32_32x32x16_bf16 v[34:49], v[128:131], v[132:135], v[34:49]
	v_mfma_f32_32x32x16_bf16 v[50:65], v[128:131], v[144:147], v[50:65]
	v_mfma_f32_32x32x16_bf16 v[2:17], v[136:139], v[140:143], v[2:17]
	v_mfma_f32_32x32x16_bf16 v[18:33], v[136:139], v[148:151], v[18:33]
	s_waitcnt lgkmcnt(0)
	v_mfma_f32_32x32x16_bf16 v[34:49], v[152:155], v[140:143], v[34:49]
	ds_read_b128 v[128:131], v66 offset:64
	ds_read_b128 v[132:135], v67 offset:36928
	ds_read_b128 v[136:139], v66 offset:96
	ds_read_b128 v[140:143], v67 offset:36960
	v_mfma_f32_32x32x16_bf16 v[50:65], v[152:155], v[148:151], v[50:65]
	ds_read_b128 v[144:147], v67 offset:41536
	ds_read_b128 v[148:151], v67 offset:41568
	s_waitcnt lgkmcnt(4)
	v_mfma_f32_32x32x16_bf16 v[2:17], v[128:131], v[132:135], v[2:17]
	s_waitcnt lgkmcnt(1)
	v_mfma_f32_32x32x16_bf16 v[18:33], v[128:131], v[144:147], v[18:33]
	ds_read_b128 v[128:131], v66 offset:4672
	ds_read_b128 v[152:155], v66 offset:4704
	s_waitcnt vmcnt(5)
	ds_write_b128 v90, v[116:119] offset:18432
	ds_write_b128 v90, v[112:115] offset:23040
	ds_write_b128 v90, v[78:81] offset:27648
	s_waitcnt vmcnt(3)
	ds_write_b128 v90, v[120:123] offset:32256
	ds_write_b128 v90, v[74:77] offset:55296
	s_waitcnt vmcnt(2)
	ds_write_b128 v90, v[82:85] offset:59904
	s_waitcnt vmcnt(1)
	ds_write_b128 v90, v[124:127] offset:64512
	s_waitcnt vmcnt(0)
	ds_write_b128 v91, v[86:89] offset:32256
	s_waitcnt lgkmcnt(0)
	s_barrier
	v_mfma_f32_32x32x16_bf16 v[34:49], v[128:131], v[132:135], v[34:49]
	v_mfma_f32_32x32x16_bf16 v[50:65], v[128:131], v[144:147], v[50:65]
	v_mfma_f32_32x32x16_bf16 v[2:17], v[136:139], v[140:143], v[2:17]
	v_mfma_f32_32x32x16_bf16 v[18:33], v[136:139], v[148:151], v[18:33]
	v_mfma_f32_32x32x16_bf16 v[34:49], v[152:155], v[140:143], v[34:49]
	v_mfma_f32_32x32x16_bf16 v[50:65], v[152:155], v[148:151], v[50:65]
	ds_read_b128 v[74:77], v66 offset:18432
	ds_read_b128 v[78:81], v67 offset:55296
	ds_read_b128 v[82:85], v66 offset:18464
	ds_read_b128 v[86:89], v67 offset:55328
	ds_read_b128 v[112:115], v67 offset:59904
	ds_read_b128 v[116:119], v67 offset:59936
	s_and_b64 vcc, exec, s[4:5]
	s_waitcnt lgkmcnt(4)
	v_mfma_f32_32x32x16_bf16 v[2:17], v[74:77], v[78:81], v[2:17]
	s_waitcnt lgkmcnt(1)
	v_mfma_f32_32x32x16_bf16 v[18:33], v[74:77], v[112:115], v[18:33]
	ds_read_b128 v[74:77], v66 offset:23040
	ds_read_b128 v[120:123], v66 offset:23072
	s_waitcnt lgkmcnt(1)
	v_mfma_f32_32x32x16_bf16 v[34:49], v[74:77], v[78:81], v[34:49]
	v_mfma_f32_32x32x16_bf16 v[50:65], v[74:77], v[112:115], v[50:65]
	v_mfma_f32_32x32x16_bf16 v[2:17], v[82:85], v[86:89], v[2:17]
	v_mfma_f32_32x32x16_bf16 v[18:33], v[82:85], v[116:119], v[18:33]
	s_waitcnt lgkmcnt(0)
	v_mfma_f32_32x32x16_bf16 v[34:49], v[120:123], v[86:89], v[34:49]
	ds_read_b128 v[74:77], v66 offset:18496
	ds_read_b128 v[78:81], v67 offset:55360
	ds_read_b128 v[82:85], v66 offset:18528
	ds_read_b128 v[86:89], v67 offset:55392
	v_mfma_f32_32x32x16_bf16 v[50:65], v[120:123], v[116:119], v[50:65]
	ds_read_b128 v[112:115], v67 offset:59968
	ds_read_b128 v[116:119], v67 offset:60000
	s_waitcnt lgkmcnt(4)
	v_mfma_f32_32x32x16_bf16 v[2:17], v[74:77], v[78:81], v[2:17]
	s_waitcnt lgkmcnt(1)
	v_mfma_f32_32x32x16_bf16 v[18:33], v[74:77], v[112:115], v[18:33]
	ds_read_b128 v[74:77], v66 offset:23104
	ds_read_b128 v[120:123], v66 offset:23136
	s_waitcnt lgkmcnt(0)
	s_barrier
	v_mfma_f32_32x32x16_bf16 v[34:49], v[74:77], v[78:81], v[34:49]
	v_mfma_f32_32x32x16_bf16 v[50:65], v[74:77], v[112:115], v[50:65]
	v_mfma_f32_32x32x16_bf16 v[2:17], v[82:85], v[86:89], v[2:17]
	v_mfma_f32_32x32x16_bf16 v[18:33], v[82:85], v[116:119], v[18:33]
	v_mfma_f32_32x32x16_bf16 v[34:49], v[120:123], v[86:89], v[34:49]
	s_nop 10
	ds_write2_b32 v93, v2, v18 offset1:32
	v_mfma_f32_32x32x16_bf16 v[50:65], v[120:123], v[116:119], v[50:65]
	s_nop 11
	ds_write2_b32 v95, v34, v50 offset0:32 offset1:64
	ds_write2_b32 v93, v3, v19 offset0:129 offset1:161
	ds_write2_b32 v95, v35, v51 offset0:161 offset1:193
	ds_write2_b32 v96, v4, v20 offset0:2 offset1:34
	ds_write2_b32 v97, v36, v52 offset0:34 offset1:66
	ds_write2_b32 v96, v5, v21 offset0:131 offset1:163
	ds_write2_b32 v97, v37, v53 offset0:163 offset1:195
	ds_write2_b32 v98, v6, v22 offset0:8 offset1:40
	ds_write2_b32 v99, v38, v54 offset0:40 offset1:72
	ds_write2_b32 v98, v7, v23 offset0:137 offset1:169
	ds_write2_b32 v99, v39, v55 offset0:169 offset1:201
	ds_write2_b32 v100, v8, v24 offset0:10 offset1:42
	ds_write2_b32 v101, v40, v56 offset0:42 offset1:74
	ds_write2_b32 v100, v9, v25 offset0:139 offset1:171
	ds_write2_b32 v101, v41, v57 offset0:171 offset1:203
	ds_write2_b32 v102, v10, v26 offset0:16 offset1:48
	ds_write2_b32 v103, v42, v58 offset0:48 offset1:80
	ds_write2_b32 v102, v11, v27 offset0:145 offset1:177
	ds_write2_b32 v103, v43, v59 offset0:177 offset1:209
	ds_write2_b32 v104, v12, v28 offset0:18 offset1:50
	ds_write2_b32 v105, v44, v60 offset0:50 offset1:82
	ds_write2_b32 v104, v13, v29 offset0:147 offset1:179
	ds_write2_b32 v105, v45, v61 offset0:179 offset1:211
	ds_write2_b32 v106, v14, v30 offset0:24 offset1:56
	ds_write2_b32 v107, v46, v62 offset0:56 offset1:88
	ds_write2_b32 v106, v15, v31 offset0:153 offset1:185
	ds_write2_b32 v107, v47, v63 offset0:185 offset1:217
	ds_write2_b32 v108, v16, v32 offset0:26 offset1:58
	ds_write2_b32 v109, v48, v64 offset0:58 offset1:90
	ds_write2_b32 v108, v17, v33 offset0:155 offset1:187
	ds_write2_b32 v109, v49, v65 offset0:187 offset1:219
	v_or_b32_e32 v6, s14, v92
	v_lshlrev_b32_e32 v68, 2, v6
	s_waitcnt lgkmcnt(0)
	s_barrier
	s_lshl_b32 s12, s17, 7
	s_and_b32 s12, s12, 0xffffe000
	s_lshl_b32 s14, s18, 7
	s_or_b32 s12, s12, s23
	s_and_b32 s14, s14, 0x1c00
	s_or_b32 s12, s14, s12
	v_mov_b32_e32 v2, v6
	v_add_u32_e32 v3, s12, v1
	v_lshlrev_b32_e32 v64, 12, v3
	v_lshl_add_u32 v64, v2, 2, v64
	v_lshlrev_b32_e32 v74, 2, v2
	global_load_dwordx4 v[120:123], v74, s[50:51]
	global_load_dwordx4 v[4:7], v64, s[44:45]
	v_add_u32_e32 v74, 0x8000, v64
	global_load_dwordx4 v[8:11], v74, s[44:45]
	v_add_u32_e32 v65, 0x10000, v64
	global_load_dwordx4 v[12:15], v65, s[44:45]
	v_add_u32_e32 v74, 0x18000, v64
	global_load_dwordx4 v[16:19], v74, s[44:45]
	v_add_u32_e32 v65, 0x20000, v64
	global_load_dwordx4 v[20:23], v65, s[44:45]
	v_add_u32_e32 v74, 0x28000, v64
	global_load_dwordx4 v[24:27], v74, s[44:45]
	v_add_u32_e32 v65, 0x30000, v64
	global_load_dwordx4 v[28:31], v65, s[44:45]
	v_add_u32_e32 v74, 0x38000, v64
	global_load_dwordx4 v[32:35], v74, s[44:45]
	v_add_u32_e32 v65, 0x40000, v64
	global_load_dwordx4 v[36:39], v65, s[44:45]
	v_add_u32_e32 v74, 0x48000, v64
	global_load_dwordx4 v[40:43], v74, s[44:45]
	v_add_u32_e32 v65, 0x50000, v64
	global_load_dwordx4 v[44:47], v65, s[44:45]
	v_add_u32_e32 v74, 0x58000, v64
	global_load_dwordx4 v[48:51], v74, s[44:45]
	v_add_u32_e32 v65, 0x60000, v64
	global_load_dwordx4 v[52:55], v65, s[44:45]
	v_add_u32_e32 v74, 0x68000, v64
	global_load_dwordx4 v[56:59], v74, s[44:45]
	v_add_u32_e32 v65, 0x70000, v64
	global_load_dwordx4 v[60:63], v65, s[44:45]
	v_add_u32_e32 v74, 0x78000, v64
	global_load_dwordx4 v[76:79], v74, s[44:45]
	v_and_b32_e32 v75, 7, v3
	v_mul_u32_u24_e32 v75, 0x204, v75
	v_and_b32_e32 v88, 0x7f, v2
	v_lshl_add_u32 v75, v88, 2, v75
	v_lshlrev_b32_e32 v156, 2, v3
	s_movk_i32 s14, 0x7fff
	v_mov_b32_e32 v157, 1
	ds_read2_b32 v[80:81], v75 offset1:1
	ds_read2_b32 v[82:83], v75 offset0:2 offset1:3
	v_add_u32_e32 v89, 0x1020, v75
	ds_read2_b32 v[84:85], v89 offset1:1
	ds_read2_b32 v[86:87], v89 offset0:2 offset1:3
	v_add_u32_e32 v88, 0x2040, v75
	ds_read2_b32 v[112:113], v88 offset1:1
	ds_read2_b32 v[114:115], v88 offset0:2 offset1:3
	v_add_u32_e32 v89, 0x3060, v75
	ds_read2_b32 v[116:117], v89 offset1:1
	ds_read2_b32 v[118:119], v89 offset0:2 offset1:3
	s_waitcnt vmcnt(15) lgkmcnt(6)
	v_pk_add_f32 v[4:5], v[4:5], v[80:81]
	v_pk_add_f32 v[6:7], v[6:7], v[82:83]
	s_waitcnt vmcnt(14) lgkmcnt(4)
	v_pk_add_f32 v[8:9], v[8:9], v[84:85]
	v_pk_add_f32 v[10:11], v[10:11], v[86:87]
	s_waitcnt vmcnt(13) lgkmcnt(2)
	v_pk_add_f32 v[12:13], v[12:13], v[112:113]
	v_pk_add_f32 v[14:15], v[14:15], v[114:115]
	s_waitcnt vmcnt(12) lgkmcnt(0)
	v_pk_add_f32 v[16:17], v[16:17], v[116:117]
	v_pk_add_f32 v[18:19], v[18:19], v[118:119]
	v_add_u32_e32 v88, 0x4080, v75
	ds_read2_b32 v[80:81], v88 offset1:1
	ds_read2_b32 v[82:83], v88 offset0:2 offset1:3
	v_add_u32_e32 v89, 0x50a0, v75
	ds_read2_b32 v[84:85], v89 offset1:1
	ds_read2_b32 v[86:87], v89 offset0:2 offset1:3
	v_add_u32_e32 v88, 0x60c0, v75
	ds_read2_b32 v[112:113], v88 offset1:1
	ds_read2_b32 v[114:115], v88 offset0:2 offset1:3
	v_add_u32_e32 v89, 0x70e0, v75
	ds_read2_b32 v[116:117], v89 offset1:1
	ds_read2_b32 v[118:119], v89 offset0:2 offset1:3
	global_store_dwordx4 v64, v[4:7], s[80:81]
	v_pk_mul_f32 v[140:141], v[4:5], v[4:5]
	v_pk_mul_f32 v[142:143], v[6:7], v[6:7]
	v_pk_mul_f32 v[144:145], v[4:5], v[120:121]
	v_pk_mul_f32 v[146:147], v[6:7], v[122:123]
	v_lshrrev_b32_e32 v158, 1, v64
	v_add_f32_e32 v124, v140, v141
	v_and_b32_sdwa v148, v144, v157 dst_sel:DWORD dst_unused:UNUSED_PAD src0_sel:WORD_1 src1_sel:DWORD
	v_and_b32_sdwa v149, v145, v157 dst_sel:DWORD dst_unused:UNUSED_PAD src0_sel:WORD_1 src1_sel:DWORD
	v_and_b32_sdwa v150, v146, v157 dst_sel:DWORD dst_unused:UNUSED_PAD src0_sel:WORD_1 src1_sel:DWORD
	v_and_b32_sdwa v151, v147, v157 dst_sel:DWORD dst_unused:UNUSED_PAD src0_sel:WORD_1 src1_sel:DWORD
	v_add_f32_e32 v124, v124, v142
	v_add3_u32 v144, v144, v148, s14
	v_add3_u32 v145, v145, v149, s14
	v_add3_u32 v146, v146, v150, s14
	v_add3_u32 v147, v147, v151, s14
	v_add_f32_e32 v124, v124, v143
	v_and_b32_e32 v145, 0xffff0000, v145
	v_and_b32_e32 v147, 0xffff0000, v147
	s_nop 0
	v_or_b32_sdwa v152, v145, v144 dst_sel:DWORD dst_unused:UNUSED_PAD src0_sel:DWORD src1_sel:WORD_1
	v_or_b32_sdwa v153, v147, v146 dst_sel:DWORD dst_unused:UNUSED_PAD src0_sel:DWORD src1_sel:WORD_1
	global_store_dwordx2 v158, v[152:153], s[92:93]
	v_add_u32_e32 v74, 0x8000, v64
	global_store_dwordx4 v74, v[8:11], s[80:81]
	v_pk_mul_f32 v[140:141], v[8:9], v[8:9]
	v_pk_mul_f32 v[142:143], v[10:11], v[10:11]
	v_pk_mul_f32 v[144:145], v[8:9], v[120:121]
	v_pk_mul_f32 v[146:147], v[10:11], v[122:123]
	v_lshrrev_b32_e32 v159, 1, v74
	v_add_f32_e32 v125, v140, v141
	v_and_b32_sdwa v148, v144, v157 dst_sel:DWORD dst_unused:UNUSED_PAD src0_sel:WORD_1 src1_sel:DWORD
	v_and_b32_sdwa v149, v145, v157 dst_sel:DWORD dst_unused:UNUSED_PAD src0_sel:WORD_1 src1_sel:DWORD
	v_and_b32_sdwa v150, v146, v157 dst_sel:DWORD dst_unused:UNUSED_PAD src0_sel:WORD_1 src1_sel:DWORD
	v_and_b32_sdwa v151, v147, v157 dst_sel:DWORD dst_unused:UNUSED_PAD src0_sel:WORD_1 src1_sel:DWORD
	v_add_f32_e32 v125, v125, v142
	v_add3_u32 v144, v144, v148, s14
	v_add3_u32 v145, v145, v149, s14
	v_add3_u32 v146, v146, v150, s14
	v_add3_u32 v147, v147, v151, s14
	v_add_f32_e32 v125, v125, v143
	v_and_b32_e32 v145, 0xffff0000, v145
	v_and_b32_e32 v147, 0xffff0000, v147
	s_nop 0
	v_or_b32_sdwa v154, v145, v144 dst_sel:DWORD dst_unused:UNUSED_PAD src0_sel:DWORD src1_sel:WORD_1
	v_or_b32_sdwa v155, v147, v146 dst_sel:DWORD dst_unused:UNUSED_PAD src0_sel:DWORD src1_sel:WORD_1
	global_store_dwordx2 v159, v[154:155], s[92:93]
	v_add_u32_e32 v65, 0x10000, v64
	global_store_dwordx4 v65, v[12:15], s[80:81]
	v_pk_mul_f32 v[140:141], v[12:13], v[12:13]
	v_pk_mul_f32 v[142:143], v[14:15], v[14:15]
	v_pk_mul_f32 v[144:145], v[12:13], v[120:121]
	v_pk_mul_f32 v[146:147], v[14:15], v[122:123]
	v_lshrrev_b32_e32 v158, 1, v65
	v_add_f32_e32 v126, v140, v141
	v_and_b32_sdwa v148, v144, v157 dst_sel:DWORD dst_unused:UNUSED_PAD src0_sel:WORD_1 src1_sel:DWORD
	v_and_b32_sdwa v149, v145, v157 dst_sel:DWORD dst_unused:UNUSED_PAD src0_sel:WORD_1 src1_sel:DWORD
	v_and_b32_sdwa v150, v146, v157 dst_sel:DWORD dst_unused:UNUSED_PAD src0_sel:WORD_1 src1_sel:DWORD
	v_and_b32_sdwa v151, v147, v157 dst_sel:DWORD dst_unused:UNUSED_PAD src0_sel:WORD_1 src1_sel:DWORD
	v_add_f32_e32 v126, v126, v142
	v_add3_u32 v144, v144, v148, s14
	v_add3_u32 v145, v145, v149, s14
	v_add3_u32 v146, v146, v150, s14
	v_add3_u32 v147, v147, v151, s14
	v_add_f32_e32 v126, v126, v143
	v_and_b32_e32 v145, 0xffff0000, v145
	v_and_b32_e32 v147, 0xffff0000, v147
	s_nop 0
	v_or_b32_sdwa v152, v145, v144 dst_sel:DWORD dst_unused:UNUSED_PAD src0_sel:DWORD src1_sel:WORD_1
	v_or_b32_sdwa v153, v147, v146 dst_sel:DWORD dst_unused:UNUSED_PAD src0_sel:DWORD src1_sel:WORD_1
	global_store_dwordx2 v158, v[152:153], s[92:93]
	v_add_u32_e32 v74, 0x18000, v64
	global_store_dwordx4 v74, v[16:19], s[80:81]
	v_pk_mul_f32 v[140:141], v[16:17], v[16:17]
	v_pk_mul_f32 v[142:143], v[18:19], v[18:19]
	v_pk_mul_f32 v[144:145], v[16:17], v[120:121]
	v_pk_mul_f32 v[146:147], v[18:19], v[122:123]
	v_lshrrev_b32_e32 v159, 1, v74
	v_add_f32_e32 v127, v140, v141
	v_and_b32_sdwa v148, v144, v157 dst_sel:DWORD dst_unused:UNUSED_PAD src0_sel:WORD_1 src1_sel:DWORD
	v_and_b32_sdwa v149, v145, v157 dst_sel:DWORD dst_unused:UNUSED_PAD src0_sel:WORD_1 src1_sel:DWORD
	v_and_b32_sdwa v150, v146, v157 dst_sel:DWORD dst_unused:UNUSED_PAD src0_sel:WORD_1 src1_sel:DWORD
	v_and_b32_sdwa v151, v147, v157 dst_sel:DWORD dst_unused:UNUSED_PAD src0_sel:WORD_1 src1_sel:DWORD
	v_add_f32_e32 v127, v127, v142
	v_add3_u32 v144, v144, v148, s14
	v_add3_u32 v145, v145, v149, s14
	v_add3_u32 v146, v146, v150, s14
	v_add3_u32 v147, v147, v151, s14
	v_add_f32_e32 v127, v127, v143
	v_and_b32_e32 v145, 0xffff0000, v145
	v_and_b32_e32 v147, 0xffff0000, v147
	s_nop 0
	v_or_b32_sdwa v154, v145, v144 dst_sel:DWORD dst_unused:UNUSED_PAD src0_sel:DWORD src1_sel:WORD_1
	v_or_b32_sdwa v155, v147, v146 dst_sel:DWORD dst_unused:UNUSED_PAD src0_sel:DWORD src1_sel:WORD_1
	global_store_dwordx2 v159, v[154:155], s[92:93]
	s_nop 1
	v_add_f32_dpp v124, v124, v124 quad_perm:[1,0,3,2] row_mask:0xf bank_mask:0xf
	v_add_f32_dpp v125, v125, v125 quad_perm:[1,0,3,2] row_mask:0xf bank_mask:0xf
	v_add_f32_dpp v126, v126, v126 quad_perm:[1,0,3,2] row_mask:0xf bank_mask:0xf
	v_add_f32_dpp v127, v127, v127 quad_perm:[1,0,3,2] row_mask:0xf bank_mask:0xf
	v_add_f32_dpp v124, v124, v124 quad_perm:[2,3,0,1] row_mask:0xf bank_mask:0xf
	v_add_f32_dpp v125, v125, v125 quad_perm:[2,3,0,1] row_mask:0xf bank_mask:0xf
	v_add_f32_dpp v126, v126, v126 quad_perm:[2,3,0,1] row_mask:0xf bank_mask:0xf
	v_add_f32_dpp v127, v127, v127 quad_perm:[2,3,0,1] row_mask:0xf bank_mask:0xf
	v_add_f32_dpp v124, v124, v124 row_half_mirror row_mask:0xf bank_mask:0xf
	v_add_f32_dpp v125, v125, v125 row_half_mirror row_mask:0xf bank_mask:0xf
	v_add_f32_dpp v126, v126, v126 row_half_mirror row_mask:0xf bank_mask:0xf
	v_add_f32_dpp v127, v127, v127 row_half_mirror row_mask:0xf bank_mask:0xf
	v_add_f32_dpp v124, v124, v124 row_mirror row_mask:0xf bank_mask:0xf
	v_add_f32_dpp v125, v125, v125 row_mirror row_mask:0xf bank_mask:0xf
	v_add_f32_dpp v126, v126, v126 row_mirror row_mask:0xf bank_mask:0xf
	v_add_f32_dpp v127, v127, v127 row_mirror row_mask:0xf bank_mask:0xf
	v_add_f32_dpp v124, v124, v124 row_bcast:15 row_mask:0xa bank_mask:0xf
	v_add_f32_dpp v125, v125, v125 row_bcast:15 row_mask:0xa bank_mask:0xf
	v_add_f32_dpp v126, v126, v126 row_bcast:15 row_mask:0xa bank_mask:0xf
	v_add_f32_dpp v127, v127, v127 row_bcast:15 row_mask:0xa bank_mask:0xf
	s_waitcnt vmcnt(19) lgkmcnt(6)
	v_pk_add_f32 v[20:21], v[20:21], v[80:81]
	v_pk_add_f32 v[22:23], v[22:23], v[82:83]
	s_waitcnt vmcnt(18) lgkmcnt(4)
	v_pk_add_f32 v[24:25], v[24:25], v[84:85]
	v_pk_add_f32 v[26:27], v[26:27], v[86:87]
	s_waitcnt vmcnt(17) lgkmcnt(2)
	v_pk_add_f32 v[28:29], v[28:29], v[112:113]
	v_pk_add_f32 v[30:31], v[30:31], v[114:115]
	s_waitcnt vmcnt(16) lgkmcnt(0)
	v_pk_add_f32 v[32:33], v[32:33], v[116:117]
	v_pk_add_f32 v[34:35], v[34:35], v[118:119]
	v_add_u32_e32 v88, 0x8100, v75
	ds_read2_b32 v[80:81], v88 offset1:1
	ds_read2_b32 v[82:83], v88 offset0:2 offset1:3
	v_add_u32_e32 v89, 0x9120, v75
	ds_read2_b32 v[84:85], v89 offset1:1
	ds_read2_b32 v[86:87], v89 offset0:2 offset1:3
	v_add_u32_e32 v88, 0xa140, v75
	ds_read2_b32 v[112:113], v88 offset1:1
	ds_read2_b32 v[114:115], v88 offset0:2 offset1:3
	v_add_u32_e32 v89, 0xb160, v75
	ds_read2_b32 v[116:117], v89 offset1:1
	ds_read2_b32 v[118:119], v89 offset0:2 offset1:3
	v_add_u32_e32 v65, 0x20000, v64
	global_store_dwordx4 v65, v[20:23], s[80:81]
	v_pk_mul_f32 v[140:141], v[20:21], v[20:21]
	v_pk_mul_f32 v[142:143], v[22:23], v[22:23]
	v_pk_mul_f32 v[144:145], v[20:21], v[120:121]
	v_pk_mul_f32 v[146:147], v[22:23], v[122:123]
	v_lshrrev_b32_e32 v158, 1, v65
	v_add_f32_e32 v128, v140, v141
	v_and_b32_sdwa v148, v144, v157 dst_sel:DWORD dst_unused:UNUSED_PAD src0_sel:WORD_1 src1_sel:DWORD
	v_and_b32_sdwa v149, v145, v157 dst_sel:DWORD dst_unused:UNUSED_PAD src0_sel:WORD_1 src1_sel:DWORD
	v_and_b32_sdwa v150, v146, v157 dst_sel:DWORD dst_unused:UNUSED_PAD src0_sel:WORD_1 src1_sel:DWORD
	v_and_b32_sdwa v151, v147, v157 dst_sel:DWORD dst_unused:UNUSED_PAD src0_sel:WORD_1 src1_sel:DWORD
	v_add_f32_e32 v128, v128, v142
	v_add3_u32 v144, v144, v148, s14
	v_add3_u32 v145, v145, v149, s14
	v_add3_u32 v146, v146, v150, s14
	v_add3_u32 v147, v147, v151, s14
	v_add_f32_e32 v128, v128, v143
	v_and_b32_e32 v145, 0xffff0000, v145
	v_and_b32_e32 v147, 0xffff0000, v147
	s_nop 0
	v_or_b32_sdwa v152, v145, v144 dst_sel:DWORD dst_unused:UNUSED_PAD src0_sel:DWORD src1_sel:WORD_1
	v_or_b32_sdwa v153, v147, v146 dst_sel:DWORD dst_unused:UNUSED_PAD src0_sel:DWORD src1_sel:WORD_1
	global_store_dwordx2 v158, v[152:153], s[92:93]
	v_add_u32_e32 v74, 0x28000, v64
	global_store_dwordx4 v74, v[24:27], s[80:81]
	v_pk_mul_f32 v[140:141], v[24:25], v[24:25]
	v_pk_mul_f32 v[142:143], v[26:27], v[26:27]
	v_pk_mul_f32 v[144:145], v[24:25], v[120:121]
	v_pk_mul_f32 v[146:147], v[26:27], v[122:123]
	v_lshrrev_b32_e32 v159, 1, v74
	v_add_f32_e32 v129, v140, v141
	v_and_b32_sdwa v148, v144, v157 dst_sel:DWORD dst_unused:UNUSED_PAD src0_sel:WORD_1 src1_sel:DWORD
	v_and_b32_sdwa v149, v145, v157 dst_sel:DWORD dst_unused:UNUSED_PAD src0_sel:WORD_1 src1_sel:DWORD
	v_and_b32_sdwa v150, v146, v157 dst_sel:DWORD dst_unused:UNUSED_PAD src0_sel:WORD_1 src1_sel:DWORD
	v_and_b32_sdwa v151, v147, v157 dst_sel:DWORD dst_unused:UNUSED_PAD src0_sel:WORD_1 src1_sel:DWORD
	v_add_f32_e32 v129, v129, v142
	v_add3_u32 v144, v144, v148, s14
	v_add3_u32 v145, v145, v149, s14
	v_add3_u32 v146, v146, v150, s14
	v_add3_u32 v147, v147, v151, s14
	v_add_f32_e32 v129, v129, v143
	v_and_b32_e32 v145, 0xffff0000, v145
	v_and_b32_e32 v147, 0xffff0000, v147
	s_nop 0
	v_or_b32_sdwa v154, v145, v144 dst_sel:DWORD dst_unused:UNUSED_PAD src0_sel:DWORD src1_sel:WORD_1
	v_or_b32_sdwa v155, v147, v146 dst_sel:DWORD dst_unused:UNUSED_PAD src0_sel:DWORD src1_sel:WORD_1
	global_store_dwordx2 v159, v[154:155], s[92:93]
	v_add_u32_e32 v65, 0x30000, v64
	global_store_dwordx4 v65, v[28:31], s[80:81]
	v_pk_mul_f32 v[140:141], v[28:29], v[28:29]
	v_pk_mul_f32 v[142:143], v[30:31], v[30:31]
	v_pk_mul_f32 v[144:145], v[28:29], v[120:121]
	v_pk_mul_f32 v[146:147], v[30:31], v[122:123]
	v_lshrrev_b32_e32 v158, 1, v65
	v_add_f32_e32 v130, v140, v141
	v_and_b32_sdwa v148, v144, v157 dst_sel:DWORD dst_unused:UNUSED_PAD src0_sel:WORD_1 src1_sel:DWORD
	v_and_b32_sdwa v149, v145, v157 dst_sel:DWORD dst_unused:UNUSED_PAD src0_sel:WORD_1 src1_sel:DWORD
	v_and_b32_sdwa v150, v146, v157 dst_sel:DWORD dst_unused:UNUSED_PAD src0_sel:WORD_1 src1_sel:DWORD
	v_and_b32_sdwa v151, v147, v157 dst_sel:DWORD dst_unused:UNUSED_PAD src0_sel:WORD_1 src1_sel:DWORD
	v_add_f32_e32 v130, v130, v142
	v_add3_u32 v144, v144, v148, s14
	v_add3_u32 v145, v145, v149, s14
	v_add3_u32 v146, v146, v150, s14
	v_add3_u32 v147, v147, v151, s14
	v_add_f32_e32 v130, v130, v143
	v_and_b32_e32 v145, 0xffff0000, v145
	v_and_b32_e32 v147, 0xffff0000, v147
	s_nop 0
	v_or_b32_sdwa v152, v145, v144 dst_sel:DWORD dst_unused:UNUSED_PAD src0_sel:DWORD src1_sel:WORD_1
	v_or_b32_sdwa v153, v147, v146 dst_sel:DWORD dst_unused:UNUSED_PAD src0_sel:DWORD src1_sel:WORD_1
	global_store_dwordx2 v158, v[152:153], s[92:93]
	v_add_u32_e32 v74, 0x38000, v64
	global_store_dwordx4 v74, v[32:35], s[80:81]
	v_pk_mul_f32 v[140:141], v[32:33], v[32:33]
	v_pk_mul_f32 v[142:143], v[34:35], v[34:35]
	v_pk_mul_f32 v[144:145], v[32:33], v[120:121]
	v_pk_mul_f32 v[146:147], v[34:35], v[122:123]
	v_lshrrev_b32_e32 v159, 1, v74
	v_add_f32_e32 v131, v140, v141
	v_and_b32_sdwa v148, v144, v157 dst_sel:DWORD dst_unused:UNUSED_PAD src0_sel:WORD_1 src1_sel:DWORD
	v_and_b32_sdwa v149, v145, v157 dst_sel:DWORD dst_unused:UNUSED_PAD src0_sel:WORD_1 src1_sel:DWORD
	v_and_b32_sdwa v150, v146, v157 dst_sel:DWORD dst_unused:UNUSED_PAD src0_sel:WORD_1 src1_sel:DWORD
	v_and_b32_sdwa v151, v147, v157 dst_sel:DWORD dst_unused:UNUSED_PAD src0_sel:WORD_1 src1_sel:DWORD
	v_add_f32_e32 v131, v131, v142
	v_add3_u32 v144, v144, v148, s14
	v_add3_u32 v145, v145, v149, s14
	v_add3_u32 v146, v146, v150, s14
	v_add3_u32 v147, v147, v151, s14
	v_add_f32_e32 v131, v131, v143
	v_and_b32_e32 v145, 0xffff0000, v145
	v_and_b32_e32 v147, 0xffff0000, v147
	s_nop 0
	v_or_b32_sdwa v154, v145, v144 dst_sel:DWORD dst_unused:UNUSED_PAD src0_sel:DWORD src1_sel:WORD_1
	v_or_b32_sdwa v155, v147, v146 dst_sel:DWORD dst_unused:UNUSED_PAD src0_sel:DWORD src1_sel:WORD_1
	global_store_dwordx2 v159, v[154:155], s[92:93]
	s_nop 1
	v_add_f32_dpp v128, v128, v128 quad_perm:[1,0,3,2] row_mask:0xf bank_mask:0xf
	v_add_f32_dpp v129, v129, v129 quad_perm:[1,0,3,2] row_mask:0xf bank_mask:0xf
	v_add_f32_dpp v130, v130, v130 quad_perm:[1,0,3,2] row_mask:0xf bank_mask:0xf
	v_add_f32_dpp v131, v131, v131 quad_perm:[1,0,3,2] row_mask:0xf bank_mask:0xf
	v_add_f32_dpp v128, v128, v128 quad_perm:[2,3,0,1] row_mask:0xf bank_mask:0xf
	v_add_f32_dpp v129, v129, v129 quad_perm:[2,3,0,1] row_mask:0xf bank_mask:0xf
	v_add_f32_dpp v130, v130, v130 quad_perm:[2,3,0,1] row_mask:0xf bank_mask:0xf
	v_add_f32_dpp v131, v131, v131 quad_perm:[2,3,0,1] row_mask:0xf bank_mask:0xf
	v_add_f32_dpp v128, v128, v128 row_half_mirror row_mask:0xf bank_mask:0xf
	v_add_f32_dpp v129, v129, v129 row_half_mirror row_mask:0xf bank_mask:0xf
	v_add_f32_dpp v130, v130, v130 row_half_mirror row_mask:0xf bank_mask:0xf
	v_add_f32_dpp v131, v131, v131 row_half_mirror row_mask:0xf bank_mask:0xf
	v_add_f32_dpp v128, v128, v128 row_mirror row_mask:0xf bank_mask:0xf
	v_add_f32_dpp v129, v129, v129 row_mirror row_mask:0xf bank_mask:0xf
	v_add_f32_dpp v130, v130, v130 row_mirror row_mask:0xf bank_mask:0xf
	v_add_f32_dpp v131, v131, v131 row_mirror row_mask:0xf bank_mask:0xf
	v_add_f32_dpp v128, v128, v128 row_bcast:15 row_mask:0xa bank_mask:0xf
	v_add_f32_dpp v129, v129, v129 row_bcast:15 row_mask:0xa bank_mask:0xf
	v_add_f32_dpp v130, v130, v130 row_bcast:15 row_mask:0xa bank_mask:0xf
	v_add_f32_dpp v131, v131, v131 row_bcast:15 row_mask:0xa bank_mask:0xf
	s_waitcnt vmcnt(23) lgkmcnt(6)
	v_pk_add_f32 v[36:37], v[36:37], v[80:81]
	v_pk_add_f32 v[38:39], v[38:39], v[82:83]
	s_waitcnt vmcnt(22) lgkmcnt(4)
	v_pk_add_f32 v[40:41], v[40:41], v[84:85]
	v_pk_add_f32 v[42:43], v[42:43], v[86:87]
	s_waitcnt vmcnt(21) lgkmcnt(2)
	v_pk_add_f32 v[44:45], v[44:45], v[112:113]
	v_pk_add_f32 v[46:47], v[46:47], v[114:115]
	s_waitcnt vmcnt(20) lgkmcnt(0)
	v_pk_add_f32 v[48:49], v[48:49], v[116:117]
	v_pk_add_f32 v[50:51], v[50:51], v[118:119]
	v_add_u32_e32 v88, 0xc180, v75
	ds_read2_b32 v[80:81], v88 offset1:1
	ds_read2_b32 v[82:83], v88 offset0:2 offset1:3
	v_add_u32_e32 v89, 0xd1a0, v75
	ds_read2_b32 v[84:85], v89 offset1:1
	ds_read2_b32 v[86:87], v89 offset0:2 offset1:3
	v_add_u32_e32 v88, 0xe1c0, v75
	ds_read2_b32 v[112:113], v88 offset1:1
	ds_read2_b32 v[114:115], v88 offset0:2 offset1:3
	v_add_u32_e32 v89, 0xf1e0, v75
	ds_read2_b32 v[116:117], v89 offset1:1
	ds_read2_b32 v[118:119], v89 offset0:2 offset1:3
	v_add_u32_e32 v65, 0x40000, v64
	global_store_dwordx4 v65, v[36:39], s[80:81]
	v_pk_mul_f32 v[140:141], v[36:37], v[36:37]
	v_pk_mul_f32 v[142:143], v[38:39], v[38:39]
	v_pk_mul_f32 v[144:145], v[36:37], v[120:121]
	v_pk_mul_f32 v[146:147], v[38:39], v[122:123]
	v_lshrrev_b32_e32 v158, 1, v65
	v_add_f32_e32 v132, v140, v141
	v_and_b32_sdwa v148, v144, v157 dst_sel:DWORD dst_unused:UNUSED_PAD src0_sel:WORD_1 src1_sel:DWORD
	v_and_b32_sdwa v149, v145, v157 dst_sel:DWORD dst_unused:UNUSED_PAD src0_sel:WORD_1 src1_sel:DWORD
	v_and_b32_sdwa v150, v146, v157 dst_sel:DWORD dst_unused:UNUSED_PAD src0_sel:WORD_1 src1_sel:DWORD
	v_and_b32_sdwa v151, v147, v157 dst_sel:DWORD dst_unused:UNUSED_PAD src0_sel:WORD_1 src1_sel:DWORD
	v_add_f32_e32 v132, v132, v142
	v_add3_u32 v144, v144, v148, s14
	v_add3_u32 v145, v145, v149, s14
	v_add3_u32 v146, v146, v150, s14
	v_add3_u32 v147, v147, v151, s14
	v_add_f32_e32 v132, v132, v143
	v_and_b32_e32 v145, 0xffff0000, v145
	v_and_b32_e32 v147, 0xffff0000, v147
	s_nop 0
	v_or_b32_sdwa v152, v145, v144 dst_sel:DWORD dst_unused:UNUSED_PAD src0_sel:DWORD src1_sel:WORD_1
	v_or_b32_sdwa v153, v147, v146 dst_sel:DWORD dst_unused:UNUSED_PAD src0_sel:DWORD src1_sel:WORD_1
	global_store_dwordx2 v158, v[152:153], s[92:93]
	v_add_u32_e32 v74, 0x48000, v64
	global_store_dwordx4 v74, v[40:43], s[80:81]
	v_pk_mul_f32 v[140:141], v[40:41], v[40:41]
	v_pk_mul_f32 v[142:143], v[42:43], v[42:43]
	v_pk_mul_f32 v[144:145], v[40:41], v[120:121]
	v_pk_mul_f32 v[146:147], v[42:43], v[122:123]
	v_lshrrev_b32_e32 v159, 1, v74
	v_add_f32_e32 v133, v140, v141
	v_and_b32_sdwa v148, v144, v157 dst_sel:DWORD dst_unused:UNUSED_PAD src0_sel:WORD_1 src1_sel:DWORD
	v_and_b32_sdwa v149, v145, v157 dst_sel:DWORD dst_unused:UNUSED_PAD src0_sel:WORD_1 src1_sel:DWORD
	v_and_b32_sdwa v150, v146, v157 dst_sel:DWORD dst_unused:UNUSED_PAD src0_sel:WORD_1 src1_sel:DWORD
	v_and_b32_sdwa v151, v147, v157 dst_sel:DWORD dst_unused:UNUSED_PAD src0_sel:WORD_1 src1_sel:DWORD
	v_add_f32_e32 v133, v133, v142
	v_add3_u32 v144, v144, v148, s14
	v_add3_u32 v145, v145, v149, s14
	v_add3_u32 v146, v146, v150, s14
	v_add3_u32 v147, v147, v151, s14
	v_add_f32_e32 v133, v133, v143
	v_and_b32_e32 v145, 0xffff0000, v145
	v_and_b32_e32 v147, 0xffff0000, v147
	s_nop 0
	v_or_b32_sdwa v154, v145, v144 dst_sel:DWORD dst_unused:UNUSED_PAD src0_sel:DWORD src1_sel:WORD_1
	v_or_b32_sdwa v155, v147, v146 dst_sel:DWORD dst_unused:UNUSED_PAD src0_sel:DWORD src1_sel:WORD_1
	global_store_dwordx2 v159, v[154:155], s[92:93]
	v_add_u32_e32 v65, 0x50000, v64
	global_store_dwordx4 v65, v[44:47], s[80:81]
	v_pk_mul_f32 v[140:141], v[44:45], v[44:45]
	v_pk_mul_f32 v[142:143], v[46:47], v[46:47]
	v_pk_mul_f32 v[144:145], v[44:45], v[120:121]
	v_pk_mul_f32 v[146:147], v[46:47], v[122:123]
	v_lshrrev_b32_e32 v158, 1, v65
	v_add_f32_e32 v134, v140, v141
	v_and_b32_sdwa v148, v144, v157 dst_sel:DWORD dst_unused:UNUSED_PAD src0_sel:WORD_1 src1_sel:DWORD
	v_and_b32_sdwa v149, v145, v157 dst_sel:DWORD dst_unused:UNUSED_PAD src0_sel:WORD_1 src1_sel:DWORD
	v_and_b32_sdwa v150, v146, v157 dst_sel:DWORD dst_unused:UNUSED_PAD src0_sel:WORD_1 src1_sel:DWORD
	v_and_b32_sdwa v151, v147, v157 dst_sel:DWORD dst_unused:UNUSED_PAD src0_sel:WORD_1 src1_sel:DWORD
	v_add_f32_e32 v134, v134, v142
	v_add3_u32 v144, v144, v148, s14
	v_add3_u32 v145, v145, v149, s14
	v_add3_u32 v146, v146, v150, s14
	v_add3_u32 v147, v147, v151, s14
	v_add_f32_e32 v134, v134, v143
	v_and_b32_e32 v145, 0xffff0000, v145
	v_and_b32_e32 v147, 0xffff0000, v147
	s_nop 0
	v_or_b32_sdwa v152, v145, v144 dst_sel:DWORD dst_unused:UNUSED_PAD src0_sel:DWORD src1_sel:WORD_1
	v_or_b32_sdwa v153, v147, v146 dst_sel:DWORD dst_unused:UNUSED_PAD src0_sel:DWORD src1_sel:WORD_1
	global_store_dwordx2 v158, v[152:153], s[92:93]
	v_add_u32_e32 v74, 0x58000, v64
	global_store_dwordx4 v74, v[48:51], s[80:81]
	v_pk_mul_f32 v[140:141], v[48:49], v[48:49]
	v_pk_mul_f32 v[142:143], v[50:51], v[50:51]
	v_pk_mul_f32 v[144:145], v[48:49], v[120:121]
	v_pk_mul_f32 v[146:147], v[50:51], v[122:123]
	v_lshrrev_b32_e32 v159, 1, v74
	v_add_f32_e32 v135, v140, v141
	v_and_b32_sdwa v148, v144, v157 dst_sel:DWORD dst_unused:UNUSED_PAD src0_sel:WORD_1 src1_sel:DWORD
	v_and_b32_sdwa v149, v145, v157 dst_sel:DWORD dst_unused:UNUSED_PAD src0_sel:WORD_1 src1_sel:DWORD
	v_and_b32_sdwa v150, v146, v157 dst_sel:DWORD dst_unused:UNUSED_PAD src0_sel:WORD_1 src1_sel:DWORD
	v_and_b32_sdwa v151, v147, v157 dst_sel:DWORD dst_unused:UNUSED_PAD src0_sel:WORD_1 src1_sel:DWORD
	v_add_f32_e32 v135, v135, v142
	v_add3_u32 v144, v144, v148, s14
	v_add3_u32 v145, v145, v149, s14
	v_add3_u32 v146, v146, v150, s14
	v_add3_u32 v147, v147, v151, s14
	v_add_f32_e32 v135, v135, v143
	v_and_b32_e32 v145, 0xffff0000, v145
	v_and_b32_e32 v147, 0xffff0000, v147
	s_nop 0
	v_or_b32_sdwa v154, v145, v144 dst_sel:DWORD dst_unused:UNUSED_PAD src0_sel:DWORD src1_sel:WORD_1
	v_or_b32_sdwa v155, v147, v146 dst_sel:DWORD dst_unused:UNUSED_PAD src0_sel:DWORD src1_sel:WORD_1
	global_store_dwordx2 v159, v[154:155], s[92:93]
	s_nop 1
	v_add_f32_dpp v132, v132, v132 quad_perm:[1,0,3,2] row_mask:0xf bank_mask:0xf
	v_add_f32_dpp v133, v133, v133 quad_perm:[1,0,3,2] row_mask:0xf bank_mask:0xf
	v_add_f32_dpp v134, v134, v134 quad_perm:[1,0,3,2] row_mask:0xf bank_mask:0xf
	v_add_f32_dpp v135, v135, v135 quad_perm:[1,0,3,2] row_mask:0xf bank_mask:0xf
	v_add_f32_dpp v132, v132, v132 quad_perm:[2,3,0,1] row_mask:0xf bank_mask:0xf
	v_add_f32_dpp v133, v133, v133 quad_perm:[2,3,0,1] row_mask:0xf bank_mask:0xf
	v_add_f32_dpp v134, v134, v134 quad_perm:[2,3,0,1] row_mask:0xf bank_mask:0xf
	v_add_f32_dpp v135, v135, v135 quad_perm:[2,3,0,1] row_mask:0xf bank_mask:0xf
	v_add_f32_dpp v132, v132, v132 row_half_mirror row_mask:0xf bank_mask:0xf
	v_add_f32_dpp v133, v133, v133 row_half_mirror row_mask:0xf bank_mask:0xf
	v_add_f32_dpp v134, v134, v134 row_half_mirror row_mask:0xf bank_mask:0xf
	v_add_f32_dpp v135, v135, v135 row_half_mirror row_mask:0xf bank_mask:0xf
	v_add_f32_dpp v132, v132, v132 row_mirror row_mask:0xf bank_mask:0xf
	v_add_f32_dpp v133, v133, v133 row_mirror row_mask:0xf bank_mask:0xf
	v_add_f32_dpp v134, v134, v134 row_mirror row_mask:0xf bank_mask:0xf
	v_add_f32_dpp v135, v135, v135 row_mirror row_mask:0xf bank_mask:0xf
	v_add_f32_dpp v132, v132, v132 row_bcast:15 row_mask:0xa bank_mask:0xf
	v_add_f32_dpp v133, v133, v133 row_bcast:15 row_mask:0xa bank_mask:0xf
	v_add_f32_dpp v134, v134, v134 row_bcast:15 row_mask:0xa bank_mask:0xf
	v_add_f32_dpp v135, v135, v135 row_bcast:15 row_mask:0xa bank_mask:0xf
	s_waitcnt vmcnt(27) lgkmcnt(6)
	v_pk_add_f32 v[52:53], v[52:53], v[80:81]
	v_pk_add_f32 v[54:55], v[54:55], v[82:83]
	s_waitcnt vmcnt(26) lgkmcnt(4)
	v_pk_add_f32 v[56:57], v[56:57], v[84:85]
	v_pk_add_f32 v[58:59], v[58:59], v[86:87]
	s_waitcnt vmcnt(25) lgkmcnt(2)
	v_pk_add_f32 v[60:61], v[60:61], v[112:113]
	v_pk_add_f32 v[62:63], v[62:63], v[114:115]
	s_waitcnt vmcnt(24) lgkmcnt(0)
	v_pk_add_f32 v[76:77], v[76:77], v[116:117]
	v_pk_add_f32 v[78:79], v[78:79], v[118:119]
	v_add_u32_e32 v65, 0x60000, v64
	global_store_dwordx4 v65, v[52:55], s[80:81]
	v_pk_mul_f32 v[140:141], v[52:53], v[52:53]
	v_pk_mul_f32 v[142:143], v[54:55], v[54:55]
	v_pk_mul_f32 v[144:145], v[52:53], v[120:121]
	v_pk_mul_f32 v[146:147], v[54:55], v[122:123]
	v_lshrrev_b32_e32 v158, 1, v65
	v_add_f32_e32 v136, v140, v141
	v_and_b32_sdwa v148, v144, v157 dst_sel:DWORD dst_unused:UNUSED_PAD src0_sel:WORD_1 src1_sel:DWORD
	v_and_b32_sdwa v149, v145, v157 dst_sel:DWORD dst_unused:UNUSED_PAD src0_sel:WORD_1 src1_sel:DWORD
	v_and_b32_sdwa v150, v146, v157 dst_sel:DWORD dst_unused:UNUSED_PAD src0_sel:WORD_1 src1_sel:DWORD
	v_and_b32_sdwa v151, v147, v157 dst_sel:DWORD dst_unused:UNUSED_PAD src0_sel:WORD_1 src1_sel:DWORD
	v_add_f32_e32 v136, v136, v142
	v_add3_u32 v144, v144, v148, s14
	v_add3_u32 v145, v145, v149, s14
	v_add3_u32 v146, v146, v150, s14
	v_add3_u32 v147, v147, v151, s14
	v_add_f32_e32 v136, v136, v143
	v_and_b32_e32 v145, 0xffff0000, v145
	v_and_b32_e32 v147, 0xffff0000, v147
	s_nop 0
	v_or_b32_sdwa v152, v145, v144 dst_sel:DWORD dst_unused:UNUSED_PAD src0_sel:DWORD src1_sel:WORD_1
	v_or_b32_sdwa v153, v147, v146 dst_sel:DWORD dst_unused:UNUSED_PAD src0_sel:DWORD src1_sel:WORD_1
	global_store_dwordx2 v158, v[152:153], s[92:93]
	v_add_u32_e32 v74, 0x68000, v64
	global_store_dwordx4 v74, v[56:59], s[80:81]
	v_pk_mul_f32 v[140:141], v[56:57], v[56:57]
	v_pk_mul_f32 v[142:143], v[58:59], v[58:59]
	v_pk_mul_f32 v[144:145], v[56:57], v[120:121]
	v_pk_mul_f32 v[146:147], v[58:59], v[122:123]
	v_lshrrev_b32_e32 v159, 1, v74
	v_add_f32_e32 v137, v140, v141
	v_and_b32_sdwa v148, v144, v157 dst_sel:DWORD dst_unused:UNUSED_PAD src0_sel:WORD_1 src1_sel:DWORD
	v_and_b32_sdwa v149, v145, v157 dst_sel:DWORD dst_unused:UNUSED_PAD src0_sel:WORD_1 src1_sel:DWORD
	v_and_b32_sdwa v150, v146, v157 dst_sel:DWORD dst_unused:UNUSED_PAD src0_sel:WORD_1 src1_sel:DWORD
	v_and_b32_sdwa v151, v147, v157 dst_sel:DWORD dst_unused:UNUSED_PAD src0_sel:WORD_1 src1_sel:DWORD
	v_add_f32_e32 v137, v137, v142
	v_add3_u32 v144, v144, v148, s14
	v_add3_u32 v145, v145, v149, s14
	v_add3_u32 v146, v146, v150, s14
	v_add3_u32 v147, v147, v151, s14
	v_add_f32_e32 v137, v137, v143
	v_and_b32_e32 v145, 0xffff0000, v145
	v_and_b32_e32 v147, 0xffff0000, v147
	s_nop 0
	v_or_b32_sdwa v154, v145, v144 dst_sel:DWORD dst_unused:UNUSED_PAD src0_sel:DWORD src1_sel:WORD_1
	v_or_b32_sdwa v155, v147, v146 dst_sel:DWORD dst_unused:UNUSED_PAD src0_sel:DWORD src1_sel:WORD_1
	global_store_dwordx2 v159, v[154:155], s[92:93]
	v_add_u32_e32 v65, 0x70000, v64
	global_store_dwordx4 v65, v[60:63], s[80:81]
	v_pk_mul_f32 v[140:141], v[60:61], v[60:61]
	v_pk_mul_f32 v[142:143], v[62:63], v[62:63]
	v_pk_mul_f32 v[144:145], v[60:61], v[120:121]
	v_pk_mul_f32 v[146:147], v[62:63], v[122:123]
	v_lshrrev_b32_e32 v158, 1, v65
	v_add_f32_e32 v138, v140, v141
	v_and_b32_sdwa v148, v144, v157 dst_sel:DWORD dst_unused:UNUSED_PAD src0_sel:WORD_1 src1_sel:DWORD
	v_and_b32_sdwa v149, v145, v157 dst_sel:DWORD dst_unused:UNUSED_PAD src0_sel:WORD_1 src1_sel:DWORD
	v_and_b32_sdwa v150, v146, v157 dst_sel:DWORD dst_unused:UNUSED_PAD src0_sel:WORD_1 src1_sel:DWORD
	v_and_b32_sdwa v151, v147, v157 dst_sel:DWORD dst_unused:UNUSED_PAD src0_sel:WORD_1 src1_sel:DWORD
	v_add_f32_e32 v138, v138, v142
	v_add3_u32 v144, v144, v148, s14
	v_add3_u32 v145, v145, v149, s14
	v_add3_u32 v146, v146, v150, s14
	v_add3_u32 v147, v147, v151, s14
	v_add_f32_e32 v138, v138, v143
	v_and_b32_e32 v145, 0xffff0000, v145
	v_and_b32_e32 v147, 0xffff0000, v147
	s_nop 0
	v_or_b32_sdwa v152, v145, v144 dst_sel:DWORD dst_unused:UNUSED_PAD src0_sel:DWORD src1_sel:WORD_1
	v_or_b32_sdwa v153, v147, v146 dst_sel:DWORD dst_unused:UNUSED_PAD src0_sel:DWORD src1_sel:WORD_1
	global_store_dwordx2 v158, v[152:153], s[92:93]
	v_add_u32_e32 v74, 0x78000, v64
	global_store_dwordx4 v74, v[76:79], s[80:81]
	v_pk_mul_f32 v[140:141], v[76:77], v[76:77]
	v_pk_mul_f32 v[142:143], v[78:79], v[78:79]
	v_pk_mul_f32 v[144:145], v[76:77], v[120:121]
	v_pk_mul_f32 v[146:147], v[78:79], v[122:123]
	v_lshrrev_b32_e32 v159, 1, v74
	v_add_f32_e32 v139, v140, v141
	v_and_b32_sdwa v148, v144, v157 dst_sel:DWORD dst_unused:UNUSED_PAD src0_sel:WORD_1 src1_sel:DWORD
	v_and_b32_sdwa v149, v145, v157 dst_sel:DWORD dst_unused:UNUSED_PAD src0_sel:WORD_1 src1_sel:DWORD
	v_and_b32_sdwa v150, v146, v157 dst_sel:DWORD dst_unused:UNUSED_PAD src0_sel:WORD_1 src1_sel:DWORD
	v_and_b32_sdwa v151, v147, v157 dst_sel:DWORD dst_unused:UNUSED_PAD src0_sel:WORD_1 src1_sel:DWORD
	v_add_f32_e32 v139, v139, v142
	v_add3_u32 v144, v144, v148, s14
	v_add3_u32 v145, v145, v149, s14
	v_add3_u32 v146, v146, v150, s14
	v_add3_u32 v147, v147, v151, s14
	v_add_f32_e32 v139, v139, v143
	v_and_b32_e32 v145, 0xffff0000, v145
	v_and_b32_e32 v147, 0xffff0000, v147
	s_nop 0
	v_or_b32_sdwa v154, v145, v144 dst_sel:DWORD dst_unused:UNUSED_PAD src0_sel:DWORD src1_sel:WORD_1
	v_or_b32_sdwa v155, v147, v146 dst_sel:DWORD dst_unused:UNUSED_PAD src0_sel:DWORD src1_sel:WORD_1
	global_store_dwordx2 v159, v[154:155], s[92:93]
	s_nop 1
	v_add_f32_dpp v136, v136, v136 quad_perm:[1,0,3,2] row_mask:0xf bank_mask:0xf
	v_add_f32_dpp v137, v137, v137 quad_perm:[1,0,3,2] row_mask:0xf bank_mask:0xf
	v_add_f32_dpp v138, v138, v138 quad_perm:[1,0,3,2] row_mask:0xf bank_mask:0xf
	v_add_f32_dpp v139, v139, v139 quad_perm:[1,0,3,2] row_mask:0xf bank_mask:0xf
	v_add_f32_dpp v136, v136, v136 quad_perm:[2,3,0,1] row_mask:0xf bank_mask:0xf
	v_add_f32_dpp v137, v137, v137 quad_perm:[2,3,0,1] row_mask:0xf bank_mask:0xf
	v_add_f32_dpp v138, v138, v138 quad_perm:[2,3,0,1] row_mask:0xf bank_mask:0xf
	v_add_f32_dpp v139, v139, v139 quad_perm:[2,3,0,1] row_mask:0xf bank_mask:0xf
	v_add_f32_dpp v136, v136, v136 row_half_mirror row_mask:0xf bank_mask:0xf
	v_add_f32_dpp v137, v137, v137 row_half_mirror row_mask:0xf bank_mask:0xf
	v_add_f32_dpp v138, v138, v138 row_half_mirror row_mask:0xf bank_mask:0xf
	v_add_f32_dpp v139, v139, v139 row_half_mirror row_mask:0xf bank_mask:0xf
	v_add_f32_dpp v136, v136, v136 row_mirror row_mask:0xf bank_mask:0xf
	v_add_f32_dpp v137, v137, v137 row_mirror row_mask:0xf bank_mask:0xf
	v_add_f32_dpp v138, v138, v138 row_mirror row_mask:0xf bank_mask:0xf
	v_add_f32_dpp v139, v139, v139 row_mirror row_mask:0xf bank_mask:0xf
	v_add_f32_dpp v136, v136, v136 row_bcast:15 row_mask:0xa bank_mask:0xf
	v_add_f32_dpp v137, v137, v137 row_bcast:15 row_mask:0xa bank_mask:0xf
	v_add_f32_dpp v138, v138, v138 row_bcast:15 row_mask:0xa bank_mask:0xf
	v_add_f32_dpp v139, v139, v139 row_bcast:15 row_mask:0xa bank_mask:0xf
	s_nop 1
	s_mov_b32 exec_lo, 0x80000000
	s_mov_b32 exec_hi, 0x80000000
	global_atomic_add_f32 v156, v124, s[10:11]
	global_atomic_add_f32 v156, v125, s[10:11] offset:32
	global_atomic_add_f32 v156, v126, s[10:11] offset:64
	global_atomic_add_f32 v156, v127, s[10:11] offset:96
	global_atomic_add_f32 v156, v128, s[10:11] offset:128
	global_atomic_add_f32 v156, v129, s[10:11] offset:160
	global_atomic_add_f32 v156, v130, s[10:11] offset:192
	global_atomic_add_f32 v156, v131, s[10:11] offset:224
	global_atomic_add_f32 v156, v132, s[10:11] offset:256
	global_atomic_add_f32 v156, v133, s[10:11] offset:288
	global_atomic_add_f32 v156, v134, s[10:11] offset:320
	global_atomic_add_f32 v156, v135, s[10:11] offset:352
	global_atomic_add_f32 v156, v136, s[10:11] offset:384
	global_atomic_add_f32 v156, v137, s[10:11] offset:416
	global_atomic_add_f32 v156, v138, s[10:11] offset:448
	global_atomic_add_f32 v156, v139, s[10:11] offset:480
	s_mov_b64 exec, -1
	s_branch .LBB0_299

.LBB0_365:
	s_nop 1
	ds_write2_b32 v153, v50, v34 offset1:32
	v_add_u32_e32 v34, 0x4000, v153
	s_nop 0
	ds_write2_b32 v34, v18, v2 offset0:32 offset1:64
	ds_write2_b32 v153, v51, v35 offset0:129 offset1:161
	ds_write2_b32 v34, v19, v3 offset0:161 offset1:193
	v_add_u32_e32 v2, 0x400, v153
	v_add_u32_e32 v3, 0x4400, v153
	ds_write2_b32 v2, v52, v36 offset0:2 offset1:34
	ds_write2_b32 v3, v20, v4 offset0:34 offset1:66
	ds_write2_b32 v2, v53, v37 offset0:131 offset1:163
	ds_write2_b32 v3, v21, v5 offset0:163 offset1:195
	v_add_u32_e32 v2, 0x1000, v153
	v_add_u32_e32 v3, 0x5000, v153
	ds_write2_b32 v2, v54, v38 offset0:8 offset1:40
	ds_write2_b32 v3, v22, v6 offset0:40 offset1:72
	ds_write2_b32 v2, v55, v39 offset0:137 offset1:169
	ds_write2_b32 v3, v23, v7 offset0:169 offset1:201
	v_add_u32_e32 v2, 0x1400, v153
	v_add_u32_e32 v3, 0x5400, v153
	ds_write2_b32 v2, v56, v40 offset0:10 offset1:42
	ds_write2_b32 v3, v24, v8 offset0:42 offset1:74
	ds_write2_b32 v2, v57, v41 offset0:139 offset1:171
	ds_write2_b32 v3, v25, v9 offset0:171 offset1:203
	v_add_u32_e32 v2, 0x2000, v153
	v_add_u32_e32 v3, 0x6000, v153
	ds_write2_b32 v2, v58, v42 offset0:16 offset1:48
	ds_write2_b32 v3, v26, v10 offset0:48 offset1:80
	ds_write2_b32 v2, v59, v43 offset0:145 offset1:177
	ds_write2_b32 v3, v27, v11 offset0:177 offset1:209
	v_add_u32_e32 v2, 0x2400, v153
	v_add_u32_e32 v3, 0x6400, v153
	ds_write2_b32 v2, v60, v44 offset0:18 offset1:50
	ds_write2_b32 v3, v28, v12 offset0:50 offset1:82
	ds_write2_b32 v2, v61, v45 offset0:147 offset1:179
	ds_write2_b32 v3, v29, v13 offset0:179 offset1:211
	v_add_u32_e32 v2, 0x3000, v153
	v_add_u32_e32 v3, 0x7000, v153
	v_or_b32_e32 v8, s33, v152
	ds_write2_b32 v2, v62, v46 offset0:24 offset1:56
	ds_write2_b32 v3, v30, v14 offset0:56 offset1:88
	ds_write2_b32 v2, v63, v47 offset0:153 offset1:185
	ds_write2_b32 v3, v31, v15 offset0:185 offset1:217
	v_add_u32_e32 v2, 0x3400, v153
	v_add_u32_e32 v3, 0x7400, v153
	v_lshlrev_b32_e32 v132, 2, v8
	ds_write2_b32 v2, v64, v48 offset0:26 offset1:58
	ds_write2_b32 v3, v32, v16 offset0:58 offset1:90
	ds_write2_b32 v2, v65, v49 offset0:155 offset1:187
	ds_write2_b32 v3, v33, v17 offset0:187 offset1:219
	s_waitcnt lgkmcnt(0)
	s_barrier
	v_mov_b32_e32 v2, v8
	v_lshl_add_u32 v3, s16, 7, v1
	v_lshlrev_b32_e32 v84, 12, v3
	v_lshl_add_u32 v84, v2, 2, v84
	v_lshlrev_b32_e32 v86, 2, v2
	global_load_dwordx4 v[92:95], v86, s[8:9]
	global_load_dwordx4 v[4:7], v84, s[80:81]
	v_add_u32_e32 v86, 0x8000, v84
	global_load_dwordx4 v[8:11], v86, s[80:81]
	v_add_u32_e32 v85, 0x10000, v84
	global_load_dwordx4 v[12:15], v85, s[80:81]
	v_add_u32_e32 v86, 0x18000, v84
	global_load_dwordx4 v[16:19], v86, s[80:81]
	v_add_u32_e32 v85, 0x20000, v84
	global_load_dwordx4 v[20:23], v85, s[80:81]
	v_add_u32_e32 v86, 0x28000, v84
	global_load_dwordx4 v[24:27], v86, s[80:81]
	v_add_u32_e32 v85, 0x30000, v84
	global_load_dwordx4 v[28:31], v85, s[80:81]
	v_add_u32_e32 v86, 0x38000, v84
	global_load_dwordx4 v[32:35], v86, s[80:81]
	v_add_u32_e32 v85, 0x40000, v84
	global_load_dwordx4 v[36:39], v85, s[80:81]
	v_add_u32_e32 v86, 0x48000, v84
	global_load_dwordx4 v[40:43], v86, s[80:81]
	v_add_u32_e32 v85, 0x50000, v84
	global_load_dwordx4 v[44:47], v85, s[80:81]
	v_add_u32_e32 v86, 0x58000, v84
	global_load_dwordx4 v[48:51], v86, s[80:81]
	v_add_u32_e32 v85, 0x60000, v84
	global_load_dwordx4 v[52:55], v85, s[80:81]
	v_add_u32_e32 v86, 0x68000, v84
	global_load_dwordx4 v[56:59], v86, s[80:81]
	v_add_u32_e32 v85, 0x70000, v84
	global_load_dwordx4 v[60:63], v85, s[80:81]
	v_add_u32_e32 v86, 0x78000, v84
	global_load_dwordx4 v[64:67], v86, s[80:81]
	v_and_b32_e32 v87, 7, v3
	v_mul_u32_u24_e32 v87, 0x204, v87
	v_and_b32_e32 v88, 0x7f, v2
	v_lshl_add_u32 v87, v88, 2, v87
	v_lshlrev_b32_e32 v126, 2, v3
	s_movk_i32 s12, 0x7fff
	v_mov_b32_e32 v127, 1
	ds_read2_b32 v[68:69], v87 offset1:1
	ds_read2_b32 v[70:71], v87 offset0:2 offset1:3
	v_add_u32_e32 v89, 0x1020, v87
	ds_read2_b32 v[72:73], v89 offset1:1
	ds_read2_b32 v[74:75], v89 offset0:2 offset1:3
	v_add_u32_e32 v88, 0x2040, v87
	ds_read2_b32 v[76:77], v88 offset1:1
	ds_read2_b32 v[78:79], v88 offset0:2 offset1:3
	v_add_u32_e32 v89, 0x3060, v87
	ds_read2_b32 v[80:81], v89 offset1:1
	ds_read2_b32 v[82:83], v89 offset0:2 offset1:3
	s_waitcnt vmcnt(15) lgkmcnt(6)
	v_pk_add_f32 v[4:5], v[4:5], v[68:69]
	v_pk_add_f32 v[6:7], v[6:7], v[70:71]
	s_waitcnt vmcnt(14) lgkmcnt(4)
	v_pk_add_f32 v[8:9], v[8:9], v[72:73]
	v_pk_add_f32 v[10:11], v[10:11], v[74:75]
	s_waitcnt vmcnt(13) lgkmcnt(2)
	v_pk_add_f32 v[12:13], v[12:13], v[76:77]
	v_pk_add_f32 v[14:15], v[14:15], v[78:79]
	s_waitcnt vmcnt(12) lgkmcnt(0)
	v_pk_add_f32 v[16:17], v[16:17], v[80:81]
	v_pk_add_f32 v[18:19], v[18:19], v[82:83]
	v_add_u32_e32 v88, 0x4080, v87
	ds_read2_b32 v[68:69], v88 offset1:1
	ds_read2_b32 v[70:71], v88 offset0:2 offset1:3
	v_add_u32_e32 v89, 0x50a0, v87
	ds_read2_b32 v[72:73], v89 offset1:1
	ds_read2_b32 v[74:75], v89 offset0:2 offset1:3
	v_add_u32_e32 v88, 0x60c0, v87
	ds_read2_b32 v[76:77], v88 offset1:1
	ds_read2_b32 v[78:79], v88 offset0:2 offset1:3
	v_add_u32_e32 v89, 0x70e0, v87
	ds_read2_b32 v[80:81], v89 offset1:1
	ds_read2_b32 v[82:83], v89 offset0:2 offset1:3
	global_store_dwordx4 v84, v[4:7], s[80:81]
	v_pk_mul_f32 v[110:111], v[4:5], v[4:5]
	v_pk_mul_f32 v[112:113], v[6:7], v[6:7]
	v_pk_mul_f32 v[114:115], v[4:5], v[92:93]
	v_pk_mul_f32 v[116:117], v[6:7], v[94:95]
	v_lshrrev_b32_e32 v142, 1, v84
	v_add_f32_e32 v90, v110, v111
	v_and_b32_sdwa v118, v114, v127 dst_sel:DWORD dst_unused:UNUSED_PAD src0_sel:WORD_1 src1_sel:DWORD
	v_and_b32_sdwa v119, v115, v127 dst_sel:DWORD dst_unused:UNUSED_PAD src0_sel:WORD_1 src1_sel:DWORD
	v_and_b32_sdwa v120, v116, v127 dst_sel:DWORD dst_unused:UNUSED_PAD src0_sel:WORD_1 src1_sel:DWORD
	v_and_b32_sdwa v121, v117, v127 dst_sel:DWORD dst_unused:UNUSED_PAD src0_sel:WORD_1 src1_sel:DWORD
	v_add_f32_e32 v90, v90, v112
	v_add3_u32 v114, v114, v118, s12
	v_add3_u32 v115, v115, v119, s12
	v_add3_u32 v116, v116, v120, s12
	v_add3_u32 v117, v117, v121, s12
	v_add_f32_e32 v90, v90, v113
	v_and_b32_e32 v115, 0xffff0000, v115
	v_and_b32_e32 v117, 0xffff0000, v117
	s_nop 0
	v_or_b32_sdwa v122, v115, v114 dst_sel:DWORD dst_unused:UNUSED_PAD src0_sel:DWORD src1_sel:WORD_1
	v_or_b32_sdwa v123, v117, v116 dst_sel:DWORD dst_unused:UNUSED_PAD src0_sel:DWORD src1_sel:WORD_1
	global_store_dwordx2 v142, v[122:123], s[92:93]
	v_add_u32_e32 v86, 0x8000, v84
	global_store_dwordx4 v86, v[8:11], s[80:81]
	v_pk_mul_f32 v[110:111], v[8:9], v[8:9]
	v_pk_mul_f32 v[112:113], v[10:11], v[10:11]
	v_pk_mul_f32 v[114:115], v[8:9], v[92:93]
	v_pk_mul_f32 v[116:117], v[10:11], v[94:95]
	v_lshrrev_b32_e32 v143, 1, v86
	v_add_f32_e32 v91, v110, v111
	v_and_b32_sdwa v118, v114, v127 dst_sel:DWORD dst_unused:UNUSED_PAD src0_sel:WORD_1 src1_sel:DWORD
	v_and_b32_sdwa v119, v115, v127 dst_sel:DWORD dst_unused:UNUSED_PAD src0_sel:WORD_1 src1_sel:DWORD
	v_and_b32_sdwa v120, v116, v127 dst_sel:DWORD dst_unused:UNUSED_PAD src0_sel:WORD_1 src1_sel:DWORD
	v_and_b32_sdwa v121, v117, v127 dst_sel:DWORD dst_unused:UNUSED_PAD src0_sel:WORD_1 src1_sel:DWORD
	v_add_f32_e32 v91, v91, v112
	v_add3_u32 v114, v114, v118, s12
	v_add3_u32 v115, v115, v119, s12
	v_add3_u32 v116, v116, v120, s12
	v_add3_u32 v117, v117, v121, s12
	v_add_f32_e32 v91, v91, v113
	v_and_b32_e32 v115, 0xffff0000, v115
	v_and_b32_e32 v117, 0xffff0000, v117
	s_nop 0
	v_or_b32_sdwa v124, v115, v114 dst_sel:DWORD dst_unused:UNUSED_PAD src0_sel:DWORD src1_sel:WORD_1
	v_or_b32_sdwa v125, v117, v116 dst_sel:DWORD dst_unused:UNUSED_PAD src0_sel:DWORD src1_sel:WORD_1
	global_store_dwordx2 v143, v[124:125], s[92:93]
	v_add_u32_e32 v85, 0x10000, v84
	global_store_dwordx4 v85, v[12:15], s[80:81]
	v_pk_mul_f32 v[110:111], v[12:13], v[12:13]
	v_pk_mul_f32 v[112:113], v[14:15], v[14:15]
	v_pk_mul_f32 v[114:115], v[12:13], v[92:93]
	v_pk_mul_f32 v[116:117], v[14:15], v[94:95]
	v_lshrrev_b32_e32 v142, 1, v85
	v_add_f32_e32 v96, v110, v111
	v_and_b32_sdwa v118, v114, v127 dst_sel:DWORD dst_unused:UNUSED_PAD src0_sel:WORD_1 src1_sel:DWORD
	v_and_b32_sdwa v119, v115, v127 dst_sel:DWORD dst_unused:UNUSED_PAD src0_sel:WORD_1 src1_sel:DWORD
	v_and_b32_sdwa v120, v116, v127 dst_sel:DWORD dst_unused:UNUSED_PAD src0_sel:WORD_1 src1_sel:DWORD
	v_and_b32_sdwa v121, v117, v127 dst_sel:DWORD dst_unused:UNUSED_PAD src0_sel:WORD_1 src1_sel:DWORD
	v_add_f32_e32 v96, v96, v112
	v_add3_u32 v114, v114, v118, s12
	v_add3_u32 v115, v115, v119, s12
	v_add3_u32 v116, v116, v120, s12
	v_add3_u32 v117, v117, v121, s12
	v_add_f32_e32 v96, v96, v113
	v_and_b32_e32 v115, 0xffff0000, v115
	v_and_b32_e32 v117, 0xffff0000, v117
	s_nop 0
	v_or_b32_sdwa v122, v115, v114 dst_sel:DWORD dst_unused:UNUSED_PAD src0_sel:DWORD src1_sel:WORD_1
	v_or_b32_sdwa v123, v117, v116 dst_sel:DWORD dst_unused:UNUSED_PAD src0_sel:DWORD src1_sel:WORD_1
	global_store_dwordx2 v142, v[122:123], s[92:93]
	v_add_u32_e32 v86, 0x18000, v84
	global_store_dwordx4 v86, v[16:19], s[80:81]
	v_pk_mul_f32 v[110:111], v[16:17], v[16:17]
	v_pk_mul_f32 v[112:113], v[18:19], v[18:19]
	v_pk_mul_f32 v[114:115], v[16:17], v[92:93]
	v_pk_mul_f32 v[116:117], v[18:19], v[94:95]
	v_lshrrev_b32_e32 v143, 1, v86
	v_add_f32_e32 v97, v110, v111
	v_and_b32_sdwa v118, v114, v127 dst_sel:DWORD dst_unused:UNUSED_PAD src0_sel:WORD_1 src1_sel:DWORD
	v_and_b32_sdwa v119, v115, v127 dst_sel:DWORD dst_unused:UNUSED_PAD src0_sel:WORD_1 src1_sel:DWORD
	v_and_b32_sdwa v120, v116, v127 dst_sel:DWORD dst_unused:UNUSED_PAD src0_sel:WORD_1 src1_sel:DWORD
	v_and_b32_sdwa v121, v117, v127 dst_sel:DWORD dst_unused:UNUSED_PAD src0_sel:WORD_1 src1_sel:DWORD
	v_add_f32_e32 v97, v97, v112
	v_add3_u32 v114, v114, v118, s12
	v_add3_u32 v115, v115, v119, s12
	v_add3_u32 v116, v116, v120, s12
	v_add3_u32 v117, v117, v121, s12
	v_add_f32_e32 v97, v97, v113
	v_and_b32_e32 v115, 0xffff0000, v115
	v_and_b32_e32 v117, 0xffff0000, v117
	s_nop 0
	v_or_b32_sdwa v124, v115, v114 dst_sel:DWORD dst_unused:UNUSED_PAD src0_sel:DWORD src1_sel:WORD_1
	v_or_b32_sdwa v125, v117, v116 dst_sel:DWORD dst_unused:UNUSED_PAD src0_sel:DWORD src1_sel:WORD_1
	global_store_dwordx2 v143, v[124:125], s[92:93]
	s_nop 1
	v_add_f32_dpp v90, v90, v90 quad_perm:[1,0,3,2] row_mask:0xf bank_mask:0xf
	v_add_f32_dpp v91, v91, v91 quad_perm:[1,0,3,2] row_mask:0xf bank_mask:0xf
	v_add_f32_dpp v96, v96, v96 quad_perm:[1,0,3,2] row_mask:0xf bank_mask:0xf
	v_add_f32_dpp v97, v97, v97 quad_perm:[1,0,3,2] row_mask:0xf bank_mask:0xf
	v_add_f32_dpp v90, v90, v90 quad_perm:[2,3,0,1] row_mask:0xf bank_mask:0xf
	v_add_f32_dpp v91, v91, v91 quad_perm:[2,3,0,1] row_mask:0xf bank_mask:0xf
	v_add_f32_dpp v96, v96, v96 quad_perm:[2,3,0,1] row_mask:0xf bank_mask:0xf
	v_add_f32_dpp v97, v97, v97 quad_perm:[2,3,0,1] row_mask:0xf bank_mask:0xf
	v_add_f32_dpp v90, v90, v90 row_half_mirror row_mask:0xf bank_mask:0xf
	v_add_f32_dpp v91, v91, v91 row_half_mirror row_mask:0xf bank_mask:0xf
	v_add_f32_dpp v96, v96, v96 row_half_mirror row_mask:0xf bank_mask:0xf
	v_add_f32_dpp v97, v97, v97 row_half_mirror row_mask:0xf bank_mask:0xf
	v_add_f32_dpp v90, v90, v90 row_mirror row_mask:0xf bank_mask:0xf
	v_add_f32_dpp v91, v91, v91 row_mirror row_mask:0xf bank_mask:0xf
	v_add_f32_dpp v96, v96, v96 row_mirror row_mask:0xf bank_mask:0xf
	v_add_f32_dpp v97, v97, v97 row_mirror row_mask:0xf bank_mask:0xf
	v_add_f32_dpp v90, v90, v90 row_bcast:15 row_mask:0xa bank_mask:0xf
	v_add_f32_dpp v91, v91, v91 row_bcast:15 row_mask:0xa bank_mask:0xf
	v_add_f32_dpp v96, v96, v96 row_bcast:15 row_mask:0xa bank_mask:0xf
	v_add_f32_dpp v97, v97, v97 row_bcast:15 row_mask:0xa bank_mask:0xf
	s_waitcnt vmcnt(19) lgkmcnt(6)
	v_pk_add_f32 v[20:21], v[20:21], v[68:69]
	v_pk_add_f32 v[22:23], v[22:23], v[70:71]
	s_waitcnt vmcnt(18) lgkmcnt(4)
	v_pk_add_f32 v[24:25], v[24:25], v[72:73]
	v_pk_add_f32 v[26:27], v[26:27], v[74:75]
	s_waitcnt vmcnt(17) lgkmcnt(2)
	v_pk_add_f32 v[28:29], v[28:29], v[76:77]
	v_pk_add_f32 v[30:31], v[30:31], v[78:79]
	s_waitcnt vmcnt(16) lgkmcnt(0)
	v_pk_add_f32 v[32:33], v[32:33], v[80:81]
	v_pk_add_f32 v[34:35], v[34:35], v[82:83]
	v_add_u32_e32 v88, 0x8100, v87
	ds_read2_b32 v[68:69], v88 offset1:1
	ds_read2_b32 v[70:71], v88 offset0:2 offset1:3
	v_add_u32_e32 v89, 0x9120, v87
	ds_read2_b32 v[72:73], v89 offset1:1
	ds_read2_b32 v[74:75], v89 offset0:2 offset1:3
	v_add_u32_e32 v88, 0xa140, v87
	ds_read2_b32 v[76:77], v88 offset1:1
	ds_read2_b32 v[78:79], v88 offset0:2 offset1:3
	v_add_u32_e32 v89, 0xb160, v87
	ds_read2_b32 v[80:81], v89 offset1:1
	ds_read2_b32 v[82:83], v89 offset0:2 offset1:3
	v_add_u32_e32 v85, 0x20000, v84
	global_store_dwordx4 v85, v[20:23], s[80:81]
	v_pk_mul_f32 v[110:111], v[20:21], v[20:21]
	v_pk_mul_f32 v[112:113], v[22:23], v[22:23]
	v_pk_mul_f32 v[114:115], v[20:21], v[92:93]
	v_pk_mul_f32 v[116:117], v[22:23], v[94:95]
	v_lshrrev_b32_e32 v142, 1, v85
	v_add_f32_e32 v98, v110, v111
	v_and_b32_sdwa v118, v114, v127 dst_sel:DWORD dst_unused:UNUSED_PAD src0_sel:WORD_1 src1_sel:DWORD
	v_and_b32_sdwa v119, v115, v127 dst_sel:DWORD dst_unused:UNUSED_PAD src0_sel:WORD_1 src1_sel:DWORD
	v_and_b32_sdwa v120, v116, v127 dst_sel:DWORD dst_unused:UNUSED_PAD src0_sel:WORD_1 src1_sel:DWORD
	v_and_b32_sdwa v121, v117, v127 dst_sel:DWORD dst_unused:UNUSED_PAD src0_sel:WORD_1 src1_sel:DWORD
	v_add_f32_e32 v98, v98, v112
	v_add3_u32 v114, v114, v118, s12
	v_add3_u32 v115, v115, v119, s12
	v_add3_u32 v116, v116, v120, s12
	v_add3_u32 v117, v117, v121, s12
	v_add_f32_e32 v98, v98, v113
	v_and_b32_e32 v115, 0xffff0000, v115
	v_and_b32_e32 v117, 0xffff0000, v117
	s_nop 0
	v_or_b32_sdwa v122, v115, v114 dst_sel:DWORD dst_unused:UNUSED_PAD src0_sel:DWORD src1_sel:WORD_1
	v_or_b32_sdwa v123, v117, v116 dst_sel:DWORD dst_unused:UNUSED_PAD src0_sel:DWORD src1_sel:WORD_1
	global_store_dwordx2 v142, v[122:123], s[92:93]
	v_add_u32_e32 v86, 0x28000, v84
	global_store_dwordx4 v86, v[24:27], s[80:81]
	v_pk_mul_f32 v[110:111], v[24:25], v[24:25]
	v_pk_mul_f32 v[112:113], v[26:27], v[26:27]
	v_pk_mul_f32 v[114:115], v[24:25], v[92:93]
	v_pk_mul_f32 v[116:117], v[26:27], v[94:95]
	v_lshrrev_b32_e32 v143, 1, v86
	v_add_f32_e32 v99, v110, v111
	v_and_b32_sdwa v118, v114, v127 dst_sel:DWORD dst_unused:UNUSED_PAD src0_sel:WORD_1 src1_sel:DWORD
	v_and_b32_sdwa v119, v115, v127 dst_sel:DWORD dst_unused:UNUSED_PAD src0_sel:WORD_1 src1_sel:DWORD
	v_and_b32_sdwa v120, v116, v127 dst_sel:DWORD dst_unused:UNUSED_PAD src0_sel:WORD_1 src1_sel:DWORD
	v_and_b32_sdwa v121, v117, v127 dst_sel:DWORD dst_unused:UNUSED_PAD src0_sel:WORD_1 src1_sel:DWORD
	v_add_f32_e32 v99, v99, v112
	v_add3_u32 v114, v114, v118, s12
	v_add3_u32 v115, v115, v119, s12
	v_add3_u32 v116, v116, v120, s12
	v_add3_u32 v117, v117, v121, s12
	v_add_f32_e32 v99, v99, v113
	v_and_b32_e32 v115, 0xffff0000, v115
	v_and_b32_e32 v117, 0xffff0000, v117
	s_nop 0
	v_or_b32_sdwa v124, v115, v114 dst_sel:DWORD dst_unused:UNUSED_PAD src0_sel:DWORD src1_sel:WORD_1
	v_or_b32_sdwa v125, v117, v116 dst_sel:DWORD dst_unused:UNUSED_PAD src0_sel:DWORD src1_sel:WORD_1
	global_store_dwordx2 v143, v[124:125], s[92:93]
	v_add_u32_e32 v85, 0x30000, v84
	global_store_dwordx4 v85, v[28:31], s[80:81]
	v_pk_mul_f32 v[110:111], v[28:29], v[28:29]
	v_pk_mul_f32 v[112:113], v[30:31], v[30:31]
	v_pk_mul_f32 v[114:115], v[28:29], v[92:93]
	v_pk_mul_f32 v[116:117], v[30:31], v[94:95]
	v_lshrrev_b32_e32 v142, 1, v85
	v_add_f32_e32 v100, v110, v111
	v_and_b32_sdwa v118, v114, v127 dst_sel:DWORD dst_unused:UNUSED_PAD src0_sel:WORD_1 src1_sel:DWORD
	v_and_b32_sdwa v119, v115, v127 dst_sel:DWORD dst_unused:UNUSED_PAD src0_sel:WORD_1 src1_sel:DWORD
	v_and_b32_sdwa v120, v116, v127 dst_sel:DWORD dst_unused:UNUSED_PAD src0_sel:WORD_1 src1_sel:DWORD
	v_and_b32_sdwa v121, v117, v127 dst_sel:DWORD dst_unused:UNUSED_PAD src0_sel:WORD_1 src1_sel:DWORD
	v_add_f32_e32 v100, v100, v112
	v_add3_u32 v114, v114, v118, s12
	v_add3_u32 v115, v115, v119, s12
	v_add3_u32 v116, v116, v120, s12
	v_add3_u32 v117, v117, v121, s12
	v_add_f32_e32 v100, v100, v113
	v_and_b32_e32 v115, 0xffff0000, v115
	v_and_b32_e32 v117, 0xffff0000, v117
	s_nop 0
	v_or_b32_sdwa v122, v115, v114 dst_sel:DWORD dst_unused:UNUSED_PAD src0_sel:DWORD src1_sel:WORD_1
	v_or_b32_sdwa v123, v117, v116 dst_sel:DWORD dst_unused:UNUSED_PAD src0_sel:DWORD src1_sel:WORD_1
	global_store_dwordx2 v142, v[122:123], s[92:93]
	v_add_u32_e32 v86, 0x38000, v84
	global_store_dwordx4 v86, v[32:35], s[80:81]
	v_pk_mul_f32 v[110:111], v[32:33], v[32:33]
	v_pk_mul_f32 v[112:113], v[34:35], v[34:35]
	v_pk_mul_f32 v[114:115], v[32:33], v[92:93]
	v_pk_mul_f32 v[116:117], v[34:35], v[94:95]
	v_lshrrev_b32_e32 v143, 1, v86
	v_add_f32_e32 v101, v110, v111
	v_and_b32_sdwa v118, v114, v127 dst_sel:DWORD dst_unused:UNUSED_PAD src0_sel:WORD_1 src1_sel:DWORD
	v_and_b32_sdwa v119, v115, v127 dst_sel:DWORD dst_unused:UNUSED_PAD src0_sel:WORD_1 src1_sel:DWORD
	v_and_b32_sdwa v120, v116, v127 dst_sel:DWORD dst_unused:UNUSED_PAD src0_sel:WORD_1 src1_sel:DWORD
	v_and_b32_sdwa v121, v117, v127 dst_sel:DWORD dst_unused:UNUSED_PAD src0_sel:WORD_1 src1_sel:DWORD
	v_add_f32_e32 v101, v101, v112
	v_add3_u32 v114, v114, v118, s12
	v_add3_u32 v115, v115, v119, s12
	v_add3_u32 v116, v116, v120, s12
	v_add3_u32 v117, v117, v121, s12
	v_add_f32_e32 v101, v101, v113
	v_and_b32_e32 v115, 0xffff0000, v115
	v_and_b32_e32 v117, 0xffff0000, v117
	s_nop 0
	v_or_b32_sdwa v124, v115, v114 dst_sel:DWORD dst_unused:UNUSED_PAD src0_sel:DWORD src1_sel:WORD_1
	v_or_b32_sdwa v125, v117, v116 dst_sel:DWORD dst_unused:UNUSED_PAD src0_sel:DWORD src1_sel:WORD_1
	global_store_dwordx2 v143, v[124:125], s[92:93]
	s_nop 1
	v_add_f32_dpp v98, v98, v98 quad_perm:[1,0,3,2] row_mask:0xf bank_mask:0xf
	v_add_f32_dpp v99, v99, v99 quad_perm:[1,0,3,2] row_mask:0xf bank_mask:0xf
	v_add_f32_dpp v100, v100, v100 quad_perm:[1,0,3,2] row_mask:0xf bank_mask:0xf
	v_add_f32_dpp v101, v101, v101 quad_perm:[1,0,3,2] row_mask:0xf bank_mask:0xf
	v_add_f32_dpp v98, v98, v98 quad_perm:[2,3,0,1] row_mask:0xf bank_mask:0xf
	v_add_f32_dpp v99, v99, v99 quad_perm:[2,3,0,1] row_mask:0xf bank_mask:0xf
	v_add_f32_dpp v100, v100, v100 quad_perm:[2,3,0,1] row_mask:0xf bank_mask:0xf
	v_add_f32_dpp v101, v101, v101 quad_perm:[2,3,0,1] row_mask:0xf bank_mask:0xf
	v_add_f32_dpp v98, v98, v98 row_half_mirror row_mask:0xf bank_mask:0xf
	v_add_f32_dpp v99, v99, v99 row_half_mirror row_mask:0xf bank_mask:0xf
	v_add_f32_dpp v100, v100, v100 row_half_mirror row_mask:0xf bank_mask:0xf
	v_add_f32_dpp v101, v101, v101 row_half_mirror row_mask:0xf bank_mask:0xf
	v_add_f32_dpp v98, v98, v98 row_mirror row_mask:0xf bank_mask:0xf
	v_add_f32_dpp v99, v99, v99 row_mirror row_mask:0xf bank_mask:0xf
	v_add_f32_dpp v100, v100, v100 row_mirror row_mask:0xf bank_mask:0xf
	v_add_f32_dpp v101, v101, v101 row_mirror row_mask:0xf bank_mask:0xf
	v_add_f32_dpp v98, v98, v98 row_bcast:15 row_mask:0xa bank_mask:0xf
	v_add_f32_dpp v99, v99, v99 row_bcast:15 row_mask:0xa bank_mask:0xf
	v_add_f32_dpp v100, v100, v100 row_bcast:15 row_mask:0xa bank_mask:0xf
	v_add_f32_dpp v101, v101, v101 row_bcast:15 row_mask:0xa bank_mask:0xf
	s_waitcnt vmcnt(23) lgkmcnt(6)
	v_pk_add_f32 v[36:37], v[36:37], v[68:69]
	v_pk_add_f32 v[38:39], v[38:39], v[70:71]
	s_waitcnt vmcnt(22) lgkmcnt(4)
	v_pk_add_f32 v[40:41], v[40:41], v[72:73]
	v_pk_add_f32 v[42:43], v[42:43], v[74:75]
	s_waitcnt vmcnt(21) lgkmcnt(2)
	v_pk_add_f32 v[44:45], v[44:45], v[76:77]
	v_pk_add_f32 v[46:47], v[46:47], v[78:79]
	s_waitcnt vmcnt(20) lgkmcnt(0)
	v_pk_add_f32 v[48:49], v[48:49], v[80:81]
	v_pk_add_f32 v[50:51], v[50:51], v[82:83]
	v_add_u32_e32 v88, 0xc180, v87
	ds_read2_b32 v[68:69], v88 offset1:1
	ds_read2_b32 v[70:71], v88 offset0:2 offset1:3
	v_add_u32_e32 v89, 0xd1a0, v87
	ds_read2_b32 v[72:73], v89 offset1:1
	ds_read2_b32 v[74:75], v89 offset0:2 offset1:3
	v_add_u32_e32 v88, 0xe1c0, v87
	ds_read2_b32 v[76:77], v88 offset1:1
	ds_read2_b32 v[78:79], v88 offset0:2 offset1:3
	v_add_u32_e32 v89, 0xf1e0, v87
	ds_read2_b32 v[80:81], v89 offset1:1
	ds_read2_b32 v[82:83], v89 offset0:2 offset1:3
	v_add_u32_e32 v85, 0x40000, v84
	global_store_dwordx4 v85, v[36:39], s[80:81]
	v_pk_mul_f32 v[110:111], v[36:37], v[36:37]
	v_pk_mul_f32 v[112:113], v[38:39], v[38:39]
	v_pk_mul_f32 v[114:115], v[36:37], v[92:93]
	v_pk_mul_f32 v[116:117], v[38:39], v[94:95]
	v_lshrrev_b32_e32 v142, 1, v85
	v_add_f32_e32 v102, v110, v111
	v_and_b32_sdwa v118, v114, v127 dst_sel:DWORD dst_unused:UNUSED_PAD src0_sel:WORD_1 src1_sel:DWORD
	v_and_b32_sdwa v119, v115, v127 dst_sel:DWORD dst_unused:UNUSED_PAD src0_sel:WORD_1 src1_sel:DWORD
	v_and_b32_sdwa v120, v116, v127 dst_sel:DWORD dst_unused:UNUSED_PAD src0_sel:WORD_1 src1_sel:DWORD
	v_and_b32_sdwa v121, v117, v127 dst_sel:DWORD dst_unused:UNUSED_PAD src0_sel:WORD_1 src1_sel:DWORD
	v_add_f32_e32 v102, v102, v112
	v_add3_u32 v114, v114, v118, s12
	v_add3_u32 v115, v115, v119, s12
	v_add3_u32 v116, v116, v120, s12
	v_add3_u32 v117, v117, v121, s12
	v_add_f32_e32 v102, v102, v113
	v_and_b32_e32 v115, 0xffff0000, v115
	v_and_b32_e32 v117, 0xffff0000, v117
	s_nop 0
	v_or_b32_sdwa v122, v115, v114 dst_sel:DWORD dst_unused:UNUSED_PAD src0_sel:DWORD src1_sel:WORD_1
	v_or_b32_sdwa v123, v117, v116 dst_sel:DWORD dst_unused:UNUSED_PAD src0_sel:DWORD src1_sel:WORD_1
	global_store_dwordx2 v142, v[122:123], s[92:93]
	v_add_u32_e32 v86, 0x48000, v84
	global_store_dwordx4 v86, v[40:43], s[80:81]
	v_pk_mul_f32 v[110:111], v[40:41], v[40:41]
	v_pk_mul_f32 v[112:113], v[42:43], v[42:43]
	v_pk_mul_f32 v[114:115], v[40:41], v[92:93]
	v_pk_mul_f32 v[116:117], v[42:43], v[94:95]
	v_lshrrev_b32_e32 v143, 1, v86
	v_add_f32_e32 v103, v110, v111
	v_and_b32_sdwa v118, v114, v127 dst_sel:DWORD dst_unused:UNUSED_PAD src0_sel:WORD_1 src1_sel:DWORD
	v_and_b32_sdwa v119, v115, v127 dst_sel:DWORD dst_unused:UNUSED_PAD src0_sel:WORD_1 src1_sel:DWORD
	v_and_b32_sdwa v120, v116, v127 dst_sel:DWORD dst_unused:UNUSED_PAD src0_sel:WORD_1 src1_sel:DWORD
	v_and_b32_sdwa v121, v117, v127 dst_sel:DWORD dst_unused:UNUSED_PAD src0_sel:WORD_1 src1_sel:DWORD
	v_add_f32_e32 v103, v103, v112
	v_add3_u32 v114, v114, v118, s12
	v_add3_u32 v115, v115, v119, s12
	v_add3_u32 v116, v116, v120, s12
	v_add3_u32 v117, v117, v121, s12
	v_add_f32_e32 v103, v103, v113
	v_and_b32_e32 v115, 0xffff0000, v115
	v_and_b32_e32 v117, 0xffff0000, v117
	s_nop 0
	v_or_b32_sdwa v124, v115, v114 dst_sel:DWORD dst_unused:UNUSED_PAD src0_sel:DWORD src1_sel:WORD_1
	v_or_b32_sdwa v125, v117, v116 dst_sel:DWORD dst_unused:UNUSED_PAD src0_sel:DWORD src1_sel:WORD_1
	global_store_dwordx2 v143, v[124:125], s[92:93]
	v_add_u32_e32 v85, 0x50000, v84
	global_store_dwordx4 v85, v[44:47], s[80:81]
	v_pk_mul_f32 v[110:111], v[44:45], v[44:45]
	v_pk_mul_f32 v[112:113], v[46:47], v[46:47]
	v_pk_mul_f32 v[114:115], v[44:45], v[92:93]
	v_pk_mul_f32 v[116:117], v[46:47], v[94:95]
	v_lshrrev_b32_e32 v142, 1, v85
	v_add_f32_e32 v104, v110, v111
	v_and_b32_sdwa v118, v114, v127 dst_sel:DWORD dst_unused:UNUSED_PAD src0_sel:WORD_1 src1_sel:DWORD
	v_and_b32_sdwa v119, v115, v127 dst_sel:DWORD dst_unused:UNUSED_PAD src0_sel:WORD_1 src1_sel:DWORD
	v_and_b32_sdwa v120, v116, v127 dst_sel:DWORD dst_unused:UNUSED_PAD src0_sel:WORD_1 src1_sel:DWORD
	v_and_b32_sdwa v121, v117, v127 dst_sel:DWORD dst_unused:UNUSED_PAD src0_sel:WORD_1 src1_sel:DWORD
	v_add_f32_e32 v104, v104, v112
	v_add3_u32 v114, v114, v118, s12
	v_add3_u32 v115, v115, v119, s12
	v_add3_u32 v116, v116, v120, s12
	v_add3_u32 v117, v117, v121, s12
	v_add_f32_e32 v104, v104, v113
	v_and_b32_e32 v115, 0xffff0000, v115
	v_and_b32_e32 v117, 0xffff0000, v117
	s_nop 0
	v_or_b32_sdwa v122, v115, v114 dst_sel:DWORD dst_unused:UNUSED_PAD src0_sel:DWORD src1_sel:WORD_1
	v_or_b32_sdwa v123, v117, v116 dst_sel:DWORD dst_unused:UNUSED_PAD src0_sel:DWORD src1_sel:WORD_1
	global_store_dwordx2 v142, v[122:123], s[92:93]
	v_add_u32_e32 v86, 0x58000, v84
	global_store_dwordx4 v86, v[48:51], s[80:81]
	v_pk_mul_f32 v[110:111], v[48:49], v[48:49]
	v_pk_mul_f32 v[112:113], v[50:51], v[50:51]
	v_pk_mul_f32 v[114:115], v[48:49], v[92:93]
	v_pk_mul_f32 v[116:117], v[50:51], v[94:95]
	v_lshrrev_b32_e32 v143, 1, v86
	v_add_f32_e32 v105, v110, v111
	v_and_b32_sdwa v118, v114, v127 dst_sel:DWORD dst_unused:UNUSED_PAD src0_sel:WORD_1 src1_sel:DWORD
	v_and_b32_sdwa v119, v115, v127 dst_sel:DWORD dst_unused:UNUSED_PAD src0_sel:WORD_1 src1_sel:DWORD
	v_and_b32_sdwa v120, v116, v127 dst_sel:DWORD dst_unused:UNUSED_PAD src0_sel:WORD_1 src1_sel:DWORD
	v_and_b32_sdwa v121, v117, v127 dst_sel:DWORD dst_unused:UNUSED_PAD src0_sel:WORD_1 src1_sel:DWORD
	v_add_f32_e32 v105, v105, v112
	v_add3_u32 v114, v114, v118, s12
	v_add3_u32 v115, v115, v119, s12
	v_add3_u32 v116, v116, v120, s12
	v_add3_u32 v117, v117, v121, s12
	v_add_f32_e32 v105, v105, v113
	v_and_b32_e32 v115, 0xffff0000, v115
	v_and_b32_e32 v117, 0xffff0000, v117
	s_nop 0
	v_or_b32_sdwa v124, v115, v114 dst_sel:DWORD dst_unused:UNUSED_PAD src0_sel:DWORD src1_sel:WORD_1
	v_or_b32_sdwa v125, v117, v116 dst_sel:DWORD dst_unused:UNUSED_PAD src0_sel:DWORD src1_sel:WORD_1
	global_store_dwordx2 v143, v[124:125], s[92:93]
	s_nop 1
	v_add_f32_dpp v102, v102, v102 quad_perm:[1,0,3,2] row_mask:0xf bank_mask:0xf
	v_add_f32_dpp v103, v103, v103 quad_perm:[1,0,3,2] row_mask:0xf bank_mask:0xf
	v_add_f32_dpp v104, v104, v104 quad_perm:[1,0,3,2] row_mask:0xf bank_mask:0xf
	v_add_f32_dpp v105, v105, v105 quad_perm:[1,0,3,2] row_mask:0xf bank_mask:0xf
	v_add_f32_dpp v102, v102, v102 quad_perm:[2,3,0,1] row_mask:0xf bank_mask:0xf
	v_add_f32_dpp v103, v103, v103 quad_perm:[2,3,0,1] row_mask:0xf bank_mask:0xf
	v_add_f32_dpp v104, v104, v104 quad_perm:[2,3,0,1] row_mask:0xf bank_mask:0xf
	v_add_f32_dpp v105, v105, v105 quad_perm:[2,3,0,1] row_mask:0xf bank_mask:0xf
	v_add_f32_dpp v102, v102, v102 row_half_mirror row_mask:0xf bank_mask:0xf
	v_add_f32_dpp v103, v103, v103 row_half_mirror row_mask:0xf bank_mask:0xf
	v_add_f32_dpp v104, v104, v104 row_half_mirror row_mask:0xf bank_mask:0xf
	v_add_f32_dpp v105, v105, v105 row_half_mirror row_mask:0xf bank_mask:0xf
	v_add_f32_dpp v102, v102, v102 row_mirror row_mask:0xf bank_mask:0xf
	v_add_f32_dpp v103, v103, v103 row_mirror row_mask:0xf bank_mask:0xf
	v_add_f32_dpp v104, v104, v104 row_mirror row_mask:0xf bank_mask:0xf
	v_add_f32_dpp v105, v105, v105 row_mirror row_mask:0xf bank_mask:0xf
	v_add_f32_dpp v102, v102, v102 row_bcast:15 row_mask:0xa bank_mask:0xf
	v_add_f32_dpp v103, v103, v103 row_bcast:15 row_mask:0xa bank_mask:0xf
	v_add_f32_dpp v104, v104, v104 row_bcast:15 row_mask:0xa bank_mask:0xf
	v_add_f32_dpp v105, v105, v105 row_bcast:15 row_mask:0xa bank_mask:0xf
	s_waitcnt vmcnt(27) lgkmcnt(6)
	v_pk_add_f32 v[52:53], v[52:53], v[68:69]
	v_pk_add_f32 v[54:55], v[54:55], v[70:71]
	s_waitcnt vmcnt(26) lgkmcnt(4)
	v_pk_add_f32 v[56:57], v[56:57], v[72:73]
	v_pk_add_f32 v[58:59], v[58:59], v[74:75]
	s_waitcnt vmcnt(25) lgkmcnt(2)
	v_pk_add_f32 v[60:61], v[60:61], v[76:77]
	v_pk_add_f32 v[62:63], v[62:63], v[78:79]
	s_waitcnt vmcnt(24) lgkmcnt(0)
	v_pk_add_f32 v[64:65], v[64:65], v[80:81]
	v_pk_add_f32 v[66:67], v[66:67], v[82:83]
	v_add_u32_e32 v85, 0x60000, v84
	global_store_dwordx4 v85, v[52:55], s[80:81]
	v_pk_mul_f32 v[110:111], v[52:53], v[52:53]
	v_pk_mul_f32 v[112:113], v[54:55], v[54:55]
	v_pk_mul_f32 v[114:115], v[52:53], v[92:93]
	v_pk_mul_f32 v[116:117], v[54:55], v[94:95]
	v_lshrrev_b32_e32 v142, 1, v85
	v_add_f32_e32 v106, v110, v111
	v_and_b32_sdwa v118, v114, v127 dst_sel:DWORD dst_unused:UNUSED_PAD src0_sel:WORD_1 src1_sel:DWORD
	v_and_b32_sdwa v119, v115, v127 dst_sel:DWORD dst_unused:UNUSED_PAD src0_sel:WORD_1 src1_sel:DWORD
	v_and_b32_sdwa v120, v116, v127 dst_sel:DWORD dst_unused:UNUSED_PAD src0_sel:WORD_1 src1_sel:DWORD
	v_and_b32_sdwa v121, v117, v127 dst_sel:DWORD dst_unused:UNUSED_PAD src0_sel:WORD_1 src1_sel:DWORD
	v_add_f32_e32 v106, v106, v112
	v_add3_u32 v114, v114, v118, s12
	v_add3_u32 v115, v115, v119, s12
	v_add3_u32 v116, v116, v120, s12
	v_add3_u32 v117, v117, v121, s12
	v_add_f32_e32 v106, v106, v113
	v_and_b32_e32 v115, 0xffff0000, v115
	v_and_b32_e32 v117, 0xffff0000, v117
	s_nop 0
	v_or_b32_sdwa v122, v115, v114 dst_sel:DWORD dst_unused:UNUSED_PAD src0_sel:DWORD src1_sel:WORD_1
	v_or_b32_sdwa v123, v117, v116 dst_sel:DWORD dst_unused:UNUSED_PAD src0_sel:DWORD src1_sel:WORD_1
	global_store_dwordx2 v142, v[122:123], s[92:93]
	v_add_u32_e32 v86, 0x68000, v84
	global_store_dwordx4 v86, v[56:59], s[80:81]
	v_pk_mul_f32 v[110:111], v[56:57], v[56:57]
	v_pk_mul_f32 v[112:113], v[58:59], v[58:59]
	v_pk_mul_f32 v[114:115], v[56:57], v[92:93]
	v_pk_mul_f32 v[116:117], v[58:59], v[94:95]
	v_lshrrev_b32_e32 v143, 1, v86
	v_add_f32_e32 v107, v110, v111
	v_and_b32_sdwa v118, v114, v127 dst_sel:DWORD dst_unused:UNUSED_PAD src0_sel:WORD_1 src1_sel:DWORD
	v_and_b32_sdwa v119, v115, v127 dst_sel:DWORD dst_unused:UNUSED_PAD src0_sel:WORD_1 src1_sel:DWORD
	v_and_b32_sdwa v120, v116, v127 dst_sel:DWORD dst_unused:UNUSED_PAD src0_sel:WORD_1 src1_sel:DWORD
	v_and_b32_sdwa v121, v117, v127 dst_sel:DWORD dst_unused:UNUSED_PAD src0_sel:WORD_1 src1_sel:DWORD
	v_add_f32_e32 v107, v107, v112
	v_add3_u32 v114, v114, v118, s12
	v_add3_u32 v115, v115, v119, s12
	v_add3_u32 v116, v116, v120, s12
	v_add3_u32 v117, v117, v121, s12
	v_add_f32_e32 v107, v107, v113
	v_and_b32_e32 v115, 0xffff0000, v115
	v_and_b32_e32 v117, 0xffff0000, v117
	s_nop 0
	v_or_b32_sdwa v124, v115, v114 dst_sel:DWORD dst_unused:UNUSED_PAD src0_sel:DWORD src1_sel:WORD_1
	v_or_b32_sdwa v125, v117, v116 dst_sel:DWORD dst_unused:UNUSED_PAD src0_sel:DWORD src1_sel:WORD_1
	global_store_dwordx2 v143, v[124:125], s[92:93]
	v_add_u32_e32 v85, 0x70000, v84
	global_store_dwordx4 v85, v[60:63], s[80:81]
	v_pk_mul_f32 v[110:111], v[60:61], v[60:61]
	v_pk_mul_f32 v[112:113], v[62:63], v[62:63]
	v_pk_mul_f32 v[114:115], v[60:61], v[92:93]
	v_pk_mul_f32 v[116:117], v[62:63], v[94:95]
	v_lshrrev_b32_e32 v142, 1, v85
	v_add_f32_e32 v108, v110, v111
	v_and_b32_sdwa v118, v114, v127 dst_sel:DWORD dst_unused:UNUSED_PAD src0_sel:WORD_1 src1_sel:DWORD
	v_and_b32_sdwa v119, v115, v127 dst_sel:DWORD dst_unused:UNUSED_PAD src0_sel:WORD_1 src1_sel:DWORD
	v_and_b32_sdwa v120, v116, v127 dst_sel:DWORD dst_unused:UNUSED_PAD src0_sel:WORD_1 src1_sel:DWORD
	v_and_b32_sdwa v121, v117, v127 dst_sel:DWORD dst_unused:UNUSED_PAD src0_sel:WORD_1 src1_sel:DWORD
	v_add_f32_e32 v108, v108, v112
	v_add3_u32 v114, v114, v118, s12
	v_add3_u32 v115, v115, v119, s12
	v_add3_u32 v116, v116, v120, s12
	v_add3_u32 v117, v117, v121, s12
	v_add_f32_e32 v108, v108, v113
	v_and_b32_e32 v115, 0xffff0000, v115
	v_and_b32_e32 v117, 0xffff0000, v117
	s_nop 0
	v_or_b32_sdwa v122, v115, v114 dst_sel:DWORD dst_unused:UNUSED_PAD src0_sel:DWORD src1_sel:WORD_1
	v_or_b32_sdwa v123, v117, v116 dst_sel:DWORD dst_unused:UNUSED_PAD src0_sel:DWORD src1_sel:WORD_1
	global_store_dwordx2 v142, v[122:123], s[92:93]
	v_add_u32_e32 v86, 0x78000, v84
	global_store_dwordx4 v86, v[64:67], s[80:81]
	v_pk_mul_f32 v[110:111], v[64:65], v[64:65]
	v_pk_mul_f32 v[112:113], v[66:67], v[66:67]
	v_pk_mul_f32 v[114:115], v[64:65], v[92:93]
	v_pk_mul_f32 v[116:117], v[66:67], v[94:95]
	v_lshrrev_b32_e32 v143, 1, v86
	v_add_f32_e32 v109, v110, v111
	v_and_b32_sdwa v118, v114, v127 dst_sel:DWORD dst_unused:UNUSED_PAD src0_sel:WORD_1 src1_sel:DWORD
	v_and_b32_sdwa v119, v115, v127 dst_sel:DWORD dst_unused:UNUSED_PAD src0_sel:WORD_1 src1_sel:DWORD
	v_and_b32_sdwa v120, v116, v127 dst_sel:DWORD dst_unused:UNUSED_PAD src0_sel:WORD_1 src1_sel:DWORD
	v_and_b32_sdwa v121, v117, v127 dst_sel:DWORD dst_unused:UNUSED_PAD src0_sel:WORD_1 src1_sel:DWORD
	v_add_f32_e32 v109, v109, v112
	v_add3_u32 v114, v114, v118, s12
	v_add3_u32 v115, v115, v119, s12
	v_add3_u32 v116, v116, v120, s12
	v_add3_u32 v117, v117, v121, s12
	v_add_f32_e32 v109, v109, v113
	v_and_b32_e32 v115, 0xffff0000, v115
	v_and_b32_e32 v117, 0xffff0000, v117
	s_nop 0
	v_or_b32_sdwa v124, v115, v114 dst_sel:DWORD dst_unused:UNUSED_PAD src0_sel:DWORD src1_sel:WORD_1
	v_or_b32_sdwa v125, v117, v116 dst_sel:DWORD dst_unused:UNUSED_PAD src0_sel:DWORD src1_sel:WORD_1
	global_store_dwordx2 v143, v[124:125], s[92:93]
	s_nop 1
	v_add_f32_dpp v106, v106, v106 quad_perm:[1,0,3,2] row_mask:0xf bank_mask:0xf
	v_add_f32_dpp v107, v107, v107 quad_perm:[1,0,3,2] row_mask:0xf bank_mask:0xf
	v_add_f32_dpp v108, v108, v108 quad_perm:[1,0,3,2] row_mask:0xf bank_mask:0xf
	v_add_f32_dpp v109, v109, v109 quad_perm:[1,0,3,2] row_mask:0xf bank_mask:0xf
	v_add_f32_dpp v106, v106, v106 quad_perm:[2,3,0,1] row_mask:0xf bank_mask:0xf
	v_add_f32_dpp v107, v107, v107 quad_perm:[2,3,0,1] row_mask:0xf bank_mask:0xf
	v_add_f32_dpp v108, v108, v108 quad_perm:[2,3,0,1] row_mask:0xf bank_mask:0xf
	v_add_f32_dpp v109, v109, v109 quad_perm:[2,3,0,1] row_mask:0xf bank_mask:0xf
	v_add_f32_dpp v106, v106, v106 row_half_mirror row_mask:0xf bank_mask:0xf
	v_add_f32_dpp v107, v107, v107 row_half_mirror row_mask:0xf bank_mask:0xf
	v_add_f32_dpp v108, v108, v108 row_half_mirror row_mask:0xf bank_mask:0xf
	v_add_f32_dpp v109, v109, v109 row_half_mirror row_mask:0xf bank_mask:0xf
	v_add_f32_dpp v106, v106, v106 row_mirror row_mask:0xf bank_mask:0xf
	v_add_f32_dpp v107, v107, v107 row_mirror row_mask:0xf bank_mask:0xf
	v_add_f32_dpp v108, v108, v108 row_mirror row_mask:0xf bank_mask:0xf
	v_add_f32_dpp v109, v109, v109 row_mirror row_mask:0xf bank_mask:0xf
	v_add_f32_dpp v106, v106, v106 row_bcast:15 row_mask:0xa bank_mask:0xf
	v_add_f32_dpp v107, v107, v107 row_bcast:15 row_mask:0xa bank_mask:0xf
	v_add_f32_dpp v108, v108, v108 row_bcast:15 row_mask:0xa bank_mask:0xf
	v_add_f32_dpp v109, v109, v109 row_bcast:15 row_mask:0xa bank_mask:0xf
	s_nop 1
	s_mov_b32 exec_lo, 0x80000000
	s_mov_b32 exec_hi, 0x80000000
	global_atomic_add_f32 v126, v90, s[10:11]
	global_atomic_add_f32 v126, v91, s[10:11] offset:32
	global_atomic_add_f32 v126, v96, s[10:11] offset:64
	global_atomic_add_f32 v126, v97, s[10:11] offset:96
	global_atomic_add_f32 v126, v98, s[10:11] offset:128
	global_atomic_add_f32 v126, v99, s[10:11] offset:160
	global_atomic_add_f32 v126, v100, s[10:11] offset:192
	global_atomic_add_f32 v126, v101, s[10:11] offset:224
	global_atomic_add_f32 v126, v102, s[10:11] offset:256
	global_atomic_add_f32 v126, v103, s[10:11] offset:288
	global_atomic_add_f32 v126, v104, s[10:11] offset:320
	global_atomic_add_f32 v126, v105, s[10:11] offset:352
	global_atomic_add_f32 v126, v106, s[10:11] offset:384
	global_atomic_add_f32 v126, v107, s[10:11] offset:416
	global_atomic_add_f32 v126, v108, s[10:11] offset:448
	global_atomic_add_f32 v126, v109, s[10:11] offset:480
	s_mov_b64 exec, -1
	s_branch .LBB0_356

.LBB0_563:
	s_and_b32 s4, s15, 0x1ffffc0
	s_lshl_b32 s5, s15, 3
	s_and_b32 s5, s5, 56
	s_or_b32 s4, s4, s3
	s_or_b32 s4, s4, s5
	s_lshl_b32 s12, s4, 7
	s_lshl_b32 s4, s15, 4
	s_and_b32 s23, s4, 0x380
	s_lshl_b64 s[4:5], s[12:13], 11
	v_lshl_add_u64 v[74:75], v[70:71], 0, s[4:5]
	v_add_co_u32_e64 v78, s[4:5], s19, v74
	s_lshl_b32 s12, s23, 11
	s_nop 0
	v_addc_co_u32_e64 v79, s[4:5], 0, v75, s[4:5]
	v_add_co_u32_e64 v80, s[4:5], s20, v74
	v_lshl_add_u64 v[76:77], v[72:73], 0, s[12:13]
	s_nop 0
	v_addc_co_u32_e64 v81, s[4:5], 0, v75, s[4:5]
	v_add_co_u32_e64 v82, s[4:5], s21, v74
	global_load_dwordx4 v[2:5], v[74:75], off
	global_load_dwordx4 v[6:9], v[78:79], off
	v_addc_co_u32_e64 v83, s[4:5], 0, v75, s[4:5]
	global_load_dwordx4 v[10:13], v[80:81], off
	global_load_dwordx4 v[14:17], v[82:83], off
	global_load_dwordx4 v[18:21], v[76:77], off
	v_add_co_u32_e64 v84, s[4:5], s19, v76
	s_nop 1
	v_addc_co_u32_e64 v85, s[4:5], 0, v77, s[4:5]
	v_add_co_u32_e64 v86, s[4:5], s20, v76
	global_load_dwordx4 v[22:25], v[84:85], off
	s_nop 0
	v_addc_co_u32_e64 v87, s[4:5], 0, v77, s[4:5]
	global_load_dwordx4 v[26:29], v[86:87], off
	v_add_co_u32_e64 v88, s[4:5], s21, v76
	s_nop 1
	v_addc_co_u32_e64 v89, s[4:5], 0, v77, s[4:5]
	global_load_dwordx4 v[30:33], v[88:89], off
	global_load_dwordx4 v[118:121], v[74:75], off offset:128
	global_load_dwordx4 v[122:125], v[76:77], off offset:128
	global_load_dwordx4 v[126:129], v[78:79], off offset:128
	global_load_dwordx4 v[130:133], v[80:81], off offset:128
	global_load_dwordx4 v[134:137], v[82:83], off offset:128
	global_load_dwordx4 v[138:141], v[84:85], off offset:128
	global_load_dwordx4 v[142:145], v[86:87], off offset:128
	global_load_dwordx4 v[146:149], v[88:89], off offset:128
	s_lshl_b32 s4, s15, 7
	s_and_b32 s4, s4, 0xffffe000
	s_lshl_b32 s5, s16, 7
	s_or_b32 s4, s4, s18
	s_and_b32 s5, s5, 0x1c00
	s_or_b32 s4, s5, s4
	v_add_u32_e32 v116, s4, v1
	s_waitcnt vmcnt(15)
	ds_write_b128 v90, v[2:5]
	s_waitcnt vmcnt(11)
	ds_write_b128 v90, v[18:21] offset:36864
	ds_write_b128 v90, v[6:9] offset:4608
	ds_write_b128 v90, v[10:13] offset:9216
	ds_write_b128 v90, v[14:17] offset:13824
	s_waitcnt vmcnt(10)
	ds_write_b128 v90, v[22:25] offset:41472
	s_waitcnt vmcnt(9)
	ds_write_b128 v90, v[26:29] offset:46080
	s_waitcnt vmcnt(8)
	ds_write_b128 v90, v[30:33] offset:50688
	s_waitcnt lgkmcnt(0)
	s_barrier
	global_load_dwordx4 v[150:153], v[78:79], off offset:256
	global_load_dwordx4 v[154:157], v[80:81], off offset:256
	global_load_dwordx4 v[158:161], v[74:75], off offset:256
	global_load_dwordx4 v[162:165], v[76:77], off offset:256
	global_load_dwordx4 v[166:169], v[82:83], off offset:256
	global_load_dwordx4 v[170:173], v[84:85], off offset:256
	global_load_dwordx4 v[174:177], v[86:87], off offset:256
	global_load_dwordx4 v[178:181], v[88:89], off offset:256
	ds_read_b128 v[18:21], v66
	ds_read_b128 v[34:37], v67 offset:36864
	ds_read_b128 v[182:185], v66 offset:32
	ds_read_b128 v[186:189], v67 offset:36896
	ds_read_b128 v[50:53], v67 offset:41472
	ds_read_b128 v[190:193], v67 offset:41504
	ds_read_b128 v[54:57], v66 offset:4608
	ds_read_b128 v[194:197], v66 offset:4640
	s_waitcnt lgkmcnt(6)
	v_mfma_f32_32x32x16_bf16 v[2:17], v[18:21], v[34:37], 0
	s_waitcnt lgkmcnt(3)
	v_mfma_f32_32x32x16_bf16 v[18:33], v[18:21], v[50:53], 0
	s_waitcnt lgkmcnt(1)
	v_mfma_f32_32x32x16_bf16 v[34:49], v[54:57], v[34:37], 0
	v_mfma_f32_32x32x16_bf16 v[50:65], v[54:57], v[50:53], 0
	v_mfma_f32_32x32x16_bf16 v[2:17], v[182:185], v[186:189], v[2:17]
	v_mfma_f32_32x32x16_bf16 v[18:33], v[182:185], v[190:193], v[18:33]
	s_waitcnt lgkmcnt(0)
	v_mfma_f32_32x32x16_bf16 v[34:49], v[194:197], v[186:189], v[34:49]
	v_mfma_f32_32x32x16_bf16 v[50:65], v[194:197], v[190:193], v[50:65]
	ds_read_b128 v[182:185], v66 offset:64
	ds_read_b128 v[186:189], v67 offset:36928
	ds_read_b128 v[190:193], v66 offset:96
	ds_read_b128 v[194:197], v67 offset:36960
	ds_read_b128 v[198:201], v67 offset:41536
	ds_read_b128 v[202:205], v67 offset:41568
	s_waitcnt lgkmcnt(4)
	v_mfma_f32_32x32x16_bf16 v[2:17], v[182:185], v[186:189], v[2:17]
	s_waitcnt lgkmcnt(1)
	v_mfma_f32_32x32x16_bf16 v[18:33], v[182:185], v[198:201], v[18:33]
	ds_read_b128 v[182:185], v66 offset:4672
	ds_read_b128 v[206:209], v66 offset:4704
	s_waitcnt vmcnt(15)
	ds_write_b128 v90, v[118:121] offset:18432
	s_waitcnt vmcnt(13)
	ds_write_b128 v90, v[126:129] offset:23040
	s_waitcnt vmcnt(12)
	ds_write_b128 v90, v[130:133] offset:27648
	s_waitcnt vmcnt(11)
	ds_write_b128 v90, v[134:137] offset:32256
	ds_write_b128 v90, v[122:125] offset:55296
	s_waitcnt vmcnt(10)
	ds_write_b128 v90, v[138:141] offset:59904
	s_waitcnt vmcnt(9)
	ds_write_b128 v90, v[142:145] offset:64512
	s_waitcnt vmcnt(8)
	ds_write_b128 v91, v[146:149] offset:32256
	s_waitcnt lgkmcnt(0)
	s_barrier
	global_load_dwordx4 v[118:121], v[78:79], off offset:384
	global_load_dwordx4 v[122:125], v[80:81], off offset:384
	global_load_dwordx4 v[126:129], v[74:75], off offset:384
	global_load_dwordx4 v[130:133], v[76:77], off offset:384
	global_load_dwordx4 v[134:137], v[82:83], off offset:384
	global_load_dwordx4 v[138:141], v[84:85], off offset:384
	global_load_dwordx4 v[142:145], v[86:87], off offset:384
	global_load_dwordx4 v[146:149], v[88:89], off offset:384
	v_mfma_f32_32x32x16_bf16 v[34:49], v[182:185], v[186:189], v[34:49]
	v_mfma_f32_32x32x16_bf16 v[50:65], v[182:185], v[198:201], v[50:65]
	v_mfma_f32_32x32x16_bf16 v[2:17], v[190:193], v[194:197], v[2:17]
	v_mfma_f32_32x32x16_bf16 v[18:33], v[190:193], v[202:205], v[18:33]
	v_mfma_f32_32x32x16_bf16 v[34:49], v[206:209], v[194:197], v[34:49]
	v_mfma_f32_32x32x16_bf16 v[50:65], v[206:209], v[202:205], v[50:65]
	ds_read_b128 v[182:185], v66 offset:18432
	ds_read_b128 v[186:189], v67 offset:55296
	ds_read_b128 v[190:193], v66 offset:18464
	ds_read_b128 v[194:197], v67 offset:55328
	ds_read_b128 v[198:201], v67 offset:59904
	ds_read_b128 v[202:205], v67 offset:59936
	s_waitcnt lgkmcnt(4)
	v_mfma_f32_32x32x16_bf16 v[2:17], v[182:185], v[186:189], v[2:17]
	s_waitcnt lgkmcnt(1)
	v_mfma_f32_32x32x16_bf16 v[18:33], v[182:185], v[198:201], v[18:33]
	ds_read_b128 v[182:185], v66 offset:23040
	ds_read_b128 v[206:209], v66 offset:23072
	s_waitcnt lgkmcnt(1)
	v_mfma_f32_32x32x16_bf16 v[34:49], v[182:185], v[186:189], v[34:49]
	v_mfma_f32_32x32x16_bf16 v[50:65], v[182:185], v[198:201], v[50:65]
	v_mfma_f32_32x32x16_bf16 v[2:17], v[190:193], v[194:197], v[2:17]
	v_mfma_f32_32x32x16_bf16 v[18:33], v[190:193], v[202:205], v[18:33]
	s_waitcnt lgkmcnt(0)
	v_mfma_f32_32x32x16_bf16 v[34:49], v[206:209], v[194:197], v[34:49]
	ds_read_b128 v[182:185], v66 offset:18496
	ds_read_b128 v[186:189], v67 offset:55360
	ds_read_b128 v[190:193], v66 offset:18528
	ds_read_b128 v[194:197], v67 offset:55392
	v_mfma_f32_32x32x16_bf16 v[50:65], v[206:209], v[202:205], v[50:65]
	ds_read_b128 v[198:201], v67 offset:59968
	ds_read_b128 v[202:205], v67 offset:60000
	s_waitcnt lgkmcnt(4)
	v_mfma_f32_32x32x16_bf16 v[2:17], v[182:185], v[186:189], v[2:17]
	s_waitcnt lgkmcnt(1)
	v_mfma_f32_32x32x16_bf16 v[18:33], v[182:185], v[198:201], v[18:33]
	ds_read_b128 v[182:185], v66 offset:23104
	ds_read_b128 v[206:209], v66 offset:23136
	s_waitcnt vmcnt(13)
	ds_write_b128 v90, v[158:161]
	ds_write_b128 v90, v[150:153] offset:4608
	ds_write_b128 v90, v[154:157] offset:9216
	s_waitcnt vmcnt(11)
	ds_write_b128 v90, v[166:169] offset:13824
	ds_write_b128 v90, v[162:165] offset:36864
	s_waitcnt vmcnt(10)
	ds_write_b128 v90, v[170:173] offset:41472
	s_waitcnt vmcnt(9)
	ds_write_b128 v90, v[174:177] offset:46080
	s_waitcnt vmcnt(8)
	ds_write_b128 v90, v[178:181] offset:50688
	s_waitcnt lgkmcnt(0)
	s_barrier
	global_load_dwordx4 v[150:153], v[78:79], off offset:512
	global_load_dwordx4 v[154:157], v[80:81], off offset:512
	global_load_dwordx4 v[158:161], v[74:75], off offset:512
	global_load_dwordx4 v[162:165], v[76:77], off offset:512
	global_load_dwordx4 v[166:169], v[82:83], off offset:512
	global_load_dwordx4 v[170:173], v[84:85], off offset:512
	global_load_dwordx4 v[174:177], v[86:87], off offset:512
	global_load_dwordx4 v[178:181], v[88:89], off offset:512
	v_mfma_f32_32x32x16_bf16 v[34:49], v[182:185], v[186:189], v[34:49]
	v_mfma_f32_32x32x16_bf16 v[50:65], v[182:185], v[198:201], v[50:65]
	v_mfma_f32_32x32x16_bf16 v[2:17], v[190:193], v[194:197], v[2:17]
	v_mfma_f32_32x32x16_bf16 v[18:33], v[190:193], v[202:205], v[18:33]
	v_mfma_f32_32x32x16_bf16 v[34:49], v[206:209], v[194:197], v[34:49]
	v_mfma_f32_32x32x16_bf16 v[50:65], v[206:209], v[202:205], v[50:65]
	ds_read_b128 v[182:185], v66
	ds_read_b128 v[186:189], v67 offset:36864
	ds_read_b128 v[190:193], v66 offset:32
	ds_read_b128 v[194:197], v67 offset:36896
	ds_read_b128 v[198:201], v67 offset:41472
	ds_read_b128 v[202:205], v67 offset:41504
	s_waitcnt lgkmcnt(4)
	v_mfma_f32_32x32x16_bf16 v[2:17], v[182:185], v[186:189], v[2:17]
	s_waitcnt lgkmcnt(1)
	v_mfma_f32_32x32x16_bf16 v[18:33], v[182:185], v[198:201], v[18:33]
	ds_read_b128 v[182:185], v66 offset:4608
	ds_read_b128 v[206:209], v66 offset:4640
	s_waitcnt lgkmcnt(1)
	v_mfma_f32_32x32x16_bf16 v[34:49], v[182:185], v[186:189], v[34:49]
	v_mfma_f32_32x32x16_bf16 v[50:65], v[182:185], v[198:201], v[50:65]
	v_mfma_f32_32x32x16_bf16 v[2:17], v[190:193], v[194:197], v[2:17]
	v_mfma_f32_32x32x16_bf16 v[18:33], v[190:193], v[202:205], v[18:33]
	s_waitcnt lgkmcnt(0)
	v_mfma_f32_32x32x16_bf16 v[34:49], v[206:209], v[194:197], v[34:49]
	ds_read_b128 v[182:185], v66 offset:64
	ds_read_b128 v[186:189], v67 offset:36928
	ds_read_b128 v[190:193], v66 offset:96
	ds_read_b128 v[194:197], v67 offset:36960
	v_mfma_f32_32x32x16_bf16 v[50:65], v[206:209], v[202:205], v[50:65]
	ds_read_b128 v[198:201], v67 offset:41536
	ds_read_b128 v[202:205], v67 offset:41568
	s_waitcnt lgkmcnt(4)
	v_mfma_f32_32x32x16_bf16 v[2:17], v[182:185], v[186:189], v[2:17]
	s_waitcnt lgkmcnt(1)
	v_mfma_f32_32x32x16_bf16 v[18:33], v[182:185], v[198:201], v[18:33]
	ds_read_b128 v[182:185], v66 offset:4672
	ds_read_b128 v[206:209], v66 offset:4704
	s_waitcnt vmcnt(13)
	ds_write_b128 v90, v[126:129] offset:18432
	ds_write_b128 v90, v[118:121] offset:23040
	ds_write_b128 v90, v[122:125] offset:27648
	s_waitcnt vmcnt(11)
	ds_write_b128 v90, v[134:137] offset:32256
	ds_write_b128 v90, v[130:133] offset:55296
	s_waitcnt vmcnt(10)
	ds_write_b128 v90, v[138:141] offset:59904
	s_waitcnt vmcnt(9)
	ds_write_b128 v90, v[142:145] offset:64512
	s_waitcnt vmcnt(8)
	ds_write_b128 v91, v[146:149] offset:32256
	s_waitcnt lgkmcnt(0)
	s_barrier
	global_load_dwordx4 v[118:121], v[78:79], off offset:640
	global_load_dwordx4 v[122:125], v[80:81], off offset:640
	global_load_dwordx4 v[126:129], v[74:75], off offset:640
	global_load_dwordx4 v[130:133], v[76:77], off offset:640
	global_load_dwordx4 v[134:137], v[82:83], off offset:640
	global_load_dwordx4 v[138:141], v[84:85], off offset:640
	global_load_dwordx4 v[142:145], v[86:87], off offset:640
	global_load_dwordx4 v[146:149], v[88:89], off offset:640
	v_mfma_f32_32x32x16_bf16 v[34:49], v[182:185], v[186:189], v[34:49]
	v_mfma_f32_32x32x16_bf16 v[50:65], v[182:185], v[198:201], v[50:65]
	v_mfma_f32_32x32x16_bf16 v[2:17], v[190:193], v[194:197], v[2:17]
	v_mfma_f32_32x32x16_bf16 v[18:33], v[190:193], v[202:205], v[18:33]
	v_mfma_f32_32x32x16_bf16 v[34:49], v[206:209], v[194:197], v[34:49]
	v_mfma_f32_32x32x16_bf16 v[50:65], v[206:209], v[202:205], v[50:65]
	ds_read_b128 v[182:185], v66 offset:18432
	ds_read_b128 v[186:189], v67 offset:55296
	ds_read_b128 v[190:193], v66 offset:18464
	ds_read_b128 v[194:197], v67 offset:55328
	ds_read_b128 v[198:201], v67 offset:59904
	ds_read_b128 v[202:205], v67 offset:59936
	s_waitcnt lgkmcnt(4)
	v_mfma_f32_32x32x16_bf16 v[2:17], v[182:185], v[186:189], v[2:17]
	s_waitcnt lgkmcnt(1)
	v_mfma_f32_32x32x16_bf16 v[18:33], v[182:185], v[198:201], v[18:33]
	ds_read_b128 v[182:185], v66 offset:23040
	ds_read_b128 v[206:209], v66 offset:23072
	s_waitcnt lgkmcnt(1)
	v_mfma_f32_32x32x16_bf16 v[34:49], v[182:185], v[186:189], v[34:49]
	v_mfma_f32_32x32x16_bf16 v[50:65], v[182:185], v[198:201], v[50:65]
	v_mfma_f32_32x32x16_bf16 v[2:17], v[190:193], v[194:197], v[2:17]
	v_mfma_f32_32x32x16_bf16 v[18:33], v[190:193], v[202:205], v[18:33]
	s_waitcnt lgkmcnt(0)
	v_mfma_f32_32x32x16_bf16 v[34:49], v[206:209], v[194:197], v[34:49]
	ds_read_b128 v[182:185], v66 offset:18496
	ds_read_b128 v[186:189], v67 offset:55360
	ds_read_b128 v[190:193], v66 offset:18528
	ds_read_b128 v[194:197], v67 offset:55392
	v_mfma_f32_32x32x16_bf16 v[50:65], v[206:209], v[202:205], v[50:65]
	ds_read_b128 v[198:201], v67 offset:59968
	ds_read_b128 v[202:205], v67 offset:60000
	s_waitcnt lgkmcnt(4)
	v_mfma_f32_32x32x16_bf16 v[2:17], v[182:185], v[186:189], v[2:17]
	s_waitcnt lgkmcnt(1)
	v_mfma_f32_32x32x16_bf16 v[18:33], v[182:185], v[198:201], v[18:33]
	ds_read_b128 v[182:185], v66 offset:23104
	ds_read_b128 v[206:209], v66 offset:23136
	s_waitcnt vmcnt(13)
	ds_write_b128 v90, v[158:161]
	ds_write_b128 v90, v[150:153] offset:4608
	ds_write_b128 v90, v[154:157] offset:9216
	s_waitcnt vmcnt(11)
	ds_write_b128 v90, v[166:169] offset:13824
	ds_write_b128 v90, v[162:165] offset:36864
	s_waitcnt vmcnt(10)
	ds_write_b128 v90, v[170:173] offset:41472
	s_waitcnt vmcnt(9)
	ds_write_b128 v90, v[174:177] offset:46080
	s_waitcnt vmcnt(8)
	ds_write_b128 v90, v[178:181] offset:50688
	s_waitcnt lgkmcnt(0)
	s_barrier
	global_load_dwordx4 v[150:153], v[78:79], off offset:768
	global_load_dwordx4 v[154:157], v[80:81], off offset:768
	global_load_dwordx4 v[158:161], v[74:75], off offset:768
	global_load_dwordx4 v[162:165], v[76:77], off offset:768
	global_load_dwordx4 v[166:169], v[82:83], off offset:768
	global_load_dwordx4 v[170:173], v[84:85], off offset:768
	global_load_dwordx4 v[174:177], v[86:87], off offset:768
	global_load_dwordx4 v[178:181], v[88:89], off offset:768
	v_mfma_f32_32x32x16_bf16 v[34:49], v[182:185], v[186:189], v[34:49]
	v_mfma_f32_32x32x16_bf16 v[50:65], v[182:185], v[198:201], v[50:65]
	v_mfma_f32_32x32x16_bf16 v[2:17], v[190:193], v[194:197], v[2:17]
	v_mfma_f32_32x32x16_bf16 v[18:33], v[190:193], v[202:205], v[18:33]
	v_mfma_f32_32x32x16_bf16 v[34:49], v[206:209], v[194:197], v[34:49]
	v_mfma_f32_32x32x16_bf16 v[50:65], v[206:209], v[202:205], v[50:65]
	ds_read_b128 v[182:185], v66
	ds_read_b128 v[186:189], v67 offset:36864
	ds_read_b128 v[190:193], v66 offset:32
	ds_read_b128 v[194:197], v67 offset:36896
	ds_read_b128 v[198:201], v67 offset:41472
	ds_read_b128 v[202:205], v67 offset:41504
	s_waitcnt lgkmcnt(4)
	v_mfma_f32_32x32x16_bf16 v[2:17], v[182:185], v[186:189], v[2:17]
	s_waitcnt lgkmcnt(1)
	v_mfma_f32_32x32x16_bf16 v[18:33], v[182:185], v[198:201], v[18:33]
	ds_read_b128 v[182:185], v66 offset:4608
	ds_read_b128 v[206:209], v66 offset:4640
	s_waitcnt lgkmcnt(1)
	v_mfma_f32_32x32x16_bf16 v[34:49], v[182:185], v[186:189], v[34:49]
	v_mfma_f32_32x32x16_bf16 v[50:65], v[182:185], v[198:201], v[50:65]
	v_mfma_f32_32x32x16_bf16 v[2:17], v[190:193], v[194:197], v[2:17]
	v_mfma_f32_32x32x16_bf16 v[18:33], v[190:193], v[202:205], v[18:33]
	s_waitcnt lgkmcnt(0)
	v_mfma_f32_32x32x16_bf16 v[34:49], v[206:209], v[194:197], v[34:49]
	ds_read_b128 v[182:185], v66 offset:64
	ds_read_b128 v[186:189], v67 offset:36928
	ds_read_b128 v[190:193], v66 offset:96
	ds_read_b128 v[194:197], v67 offset:36960
	v_mfma_f32_32x32x16_bf16 v[50:65], v[206:209], v[202:205], v[50:65]
	ds_read_b128 v[198:201], v67 offset:41536
	ds_read_b128 v[202:205], v67 offset:41568
	s_waitcnt lgkmcnt(4)
	v_mfma_f32_32x32x16_bf16 v[2:17], v[182:185], v[186:189], v[2:17]
	s_waitcnt lgkmcnt(1)
	v_mfma_f32_32x32x16_bf16 v[18:33], v[182:185], v[198:201], v[18:33]
	ds_read_b128 v[182:185], v66 offset:4672
	ds_read_b128 v[206:209], v66 offset:4704
	s_waitcnt vmcnt(13)
	ds_write_b128 v90, v[126:129] offset:18432
	ds_write_b128 v90, v[118:121] offset:23040
	ds_write_b128 v90, v[122:125] offset:27648
	s_waitcnt vmcnt(11)
	ds_write_b128 v90, v[134:137] offset:32256
	ds_write_b128 v90, v[130:133] offset:55296
	s_waitcnt vmcnt(10)
	ds_write_b128 v90, v[138:141] offset:59904
	s_waitcnt vmcnt(9)
	ds_write_b128 v90, v[142:145] offset:64512
	s_waitcnt vmcnt(8)
	ds_write_b128 v91, v[146:149] offset:32256
	s_waitcnt lgkmcnt(0)
	s_barrier
	global_load_dwordx4 v[118:121], v[78:79], off offset:896
	global_load_dwordx4 v[122:125], v[80:81], off offset:896
	global_load_dwordx4 v[126:129], v[74:75], off offset:896
	global_load_dwordx4 v[130:133], v[76:77], off offset:896
	global_load_dwordx4 v[134:137], v[82:83], off offset:896
	global_load_dwordx4 v[138:141], v[84:85], off offset:896
	global_load_dwordx4 v[142:145], v[86:87], off offset:896
	global_load_dwordx4 v[146:149], v[88:89], off offset:896
	v_mfma_f32_32x32x16_bf16 v[34:49], v[182:185], v[186:189], v[34:49]
	v_mfma_f32_32x32x16_bf16 v[50:65], v[182:185], v[198:201], v[50:65]
	v_mfma_f32_32x32x16_bf16 v[2:17], v[190:193], v[194:197], v[2:17]
	v_mfma_f32_32x32x16_bf16 v[18:33], v[190:193], v[202:205], v[18:33]
	v_mfma_f32_32x32x16_bf16 v[34:49], v[206:209], v[194:197], v[34:49]
	v_mfma_f32_32x32x16_bf16 v[50:65], v[206:209], v[202:205], v[50:65]
	ds_read_b128 v[182:185], v66 offset:18432
	ds_read_b128 v[186:189], v67 offset:55296
	ds_read_b128 v[190:193], v66 offset:18464
	ds_read_b128 v[194:197], v67 offset:55328
	ds_read_b128 v[198:201], v67 offset:59904
	ds_read_b128 v[202:205], v67 offset:59936
	s_waitcnt lgkmcnt(4)
	v_mfma_f32_32x32x16_bf16 v[2:17], v[182:185], v[186:189], v[2:17]
	s_waitcnt lgkmcnt(1)
	v_mfma_f32_32x32x16_bf16 v[18:33], v[182:185], v[198:201], v[18:33]
	ds_read_b128 v[182:185], v66 offset:23040
	ds_read_b128 v[206:209], v66 offset:23072
	s_waitcnt lgkmcnt(1)
	v_mfma_f32_32x32x16_bf16 v[34:49], v[182:185], v[186:189], v[34:49]
	v_mfma_f32_32x32x16_bf16 v[50:65], v[182:185], v[198:201], v[50:65]
	v_mfma_f32_32x32x16_bf16 v[2:17], v[190:193], v[194:197], v[2:17]
	v_mfma_f32_32x32x16_bf16 v[18:33], v[190:193], v[202:205], v[18:33]
	s_waitcnt lgkmcnt(0)
	v_mfma_f32_32x32x16_bf16 v[34:49], v[206:209], v[194:197], v[34:49]
	ds_read_b128 v[182:185], v66 offset:18496
	ds_read_b128 v[186:189], v67 offset:55360
	ds_read_b128 v[190:193], v66 offset:18528
	ds_read_b128 v[194:197], v67 offset:55392
	v_mfma_f32_32x32x16_bf16 v[50:65], v[206:209], v[202:205], v[50:65]
	ds_read_b128 v[198:201], v67 offset:59968
	ds_read_b128 v[202:205], v67 offset:60000
	s_waitcnt lgkmcnt(4)
	v_mfma_f32_32x32x16_bf16 v[2:17], v[182:185], v[186:189], v[2:17]
	s_waitcnt lgkmcnt(1)
	v_mfma_f32_32x32x16_bf16 v[18:33], v[182:185], v[198:201], v[18:33]
	ds_read_b128 v[182:185], v66 offset:23104
	ds_read_b128 v[206:209], v66 offset:23136
	s_waitcnt vmcnt(13)
	ds_write_b128 v90, v[158:161]
	ds_write_b128 v90, v[150:153] offset:4608
	ds_write_b128 v90, v[154:157] offset:9216
	s_waitcnt vmcnt(11)
	ds_write_b128 v90, v[166:169] offset:13824
	ds_write_b128 v90, v[162:165] offset:36864
	s_waitcnt vmcnt(10)
	ds_write_b128 v90, v[170:173] offset:41472
	s_waitcnt vmcnt(9)
	ds_write_b128 v90, v[174:177] offset:46080
	s_waitcnt vmcnt(8)
	ds_write_b128 v90, v[178:181] offset:50688
	s_waitcnt lgkmcnt(0)
	s_barrier
	global_load_dwordx4 v[150:153], v[78:79], off offset:1024
	global_load_dwordx4 v[154:157], v[80:81], off offset:1024
	global_load_dwordx4 v[158:161], v[74:75], off offset:1024
	global_load_dwordx4 v[162:165], v[76:77], off offset:1024
	global_load_dwordx4 v[166:169], v[82:83], off offset:1024
	global_load_dwordx4 v[170:173], v[84:85], off offset:1024
	global_load_dwordx4 v[174:177], v[86:87], off offset:1024
	global_load_dwordx4 v[178:181], v[88:89], off offset:1024
	v_mfma_f32_32x32x16_bf16 v[34:49], v[182:185], v[186:189], v[34:49]
	v_mfma_f32_32x32x16_bf16 v[50:65], v[182:185], v[198:201], v[50:65]
	v_mfma_f32_32x32x16_bf16 v[2:17], v[190:193], v[194:197], v[2:17]
	v_mfma_f32_32x32x16_bf16 v[18:33], v[190:193], v[202:205], v[18:33]
	v_mfma_f32_32x32x16_bf16 v[34:49], v[206:209], v[194:197], v[34:49]
	v_mfma_f32_32x32x16_bf16 v[50:65], v[206:209], v[202:205], v[50:65]
	ds_read_b128 v[182:185], v66
	ds_read_b128 v[186:189], v67 offset:36864
	ds_read_b128 v[190:193], v66 offset:32
	ds_read_b128 v[194:197], v67 offset:36896
	ds_read_b128 v[198:201], v67 offset:41472
	ds_read_b128 v[202:205], v67 offset:41504
	s_waitcnt lgkmcnt(4)
	v_mfma_f32_32x32x16_bf16 v[2:17], v[182:185], v[186:189], v[2:17]
	s_waitcnt lgkmcnt(1)
	v_mfma_f32_32x32x16_bf16 v[18:33], v[182:185], v[198:201], v[18:33]
	ds_read_b128 v[182:185], v66 offset:4608
	ds_read_b128 v[206:209], v66 offset:4640
	s_waitcnt lgkmcnt(1)
	v_mfma_f32_32x32x16_bf16 v[34:49], v[182:185], v[186:189], v[34:49]
	v_mfma_f32_32x32x16_bf16 v[50:65], v[182:185], v[198:201], v[50:65]
	v_mfma_f32_32x32x16_bf16 v[2:17], v[190:193], v[194:197], v[2:17]
	v_mfma_f32_32x32x16_bf16 v[18:33], v[190:193], v[202:205], v[18:33]
	s_waitcnt lgkmcnt(0)
	v_mfma_f32_32x32x16_bf16 v[34:49], v[206:209], v[194:197], v[34:49]
	ds_read_b128 v[182:185], v66 offset:64
	ds_read_b128 v[186:189], v67 offset:36928
	ds_read_b128 v[190:193], v66 offset:96
	ds_read_b128 v[194:197], v67 offset:36960
	v_mfma_f32_32x32x16_bf16 v[50:65], v[206:209], v[202:205], v[50:65]
	ds_read_b128 v[198:201], v67 offset:41536
	ds_read_b128 v[202:205], v67 offset:41568
	s_waitcnt lgkmcnt(4)
	v_mfma_f32_32x32x16_bf16 v[2:17], v[182:185], v[186:189], v[2:17]
	s_waitcnt lgkmcnt(1)
	v_mfma_f32_32x32x16_bf16 v[18:33], v[182:185], v[198:201], v[18:33]
	ds_read_b128 v[182:185], v66 offset:4672
	ds_read_b128 v[206:209], v66 offset:4704
	s_waitcnt vmcnt(13)
	ds_write_b128 v90, v[126:129] offset:18432
	ds_write_b128 v90, v[118:121] offset:23040
	ds_write_b128 v90, v[122:125] offset:27648
	s_waitcnt vmcnt(11)
	ds_write_b128 v90, v[134:137] offset:32256
	ds_write_b128 v90, v[130:133] offset:55296
	s_waitcnt vmcnt(10)
	ds_write_b128 v90, v[138:141] offset:59904
	s_waitcnt vmcnt(9)
	ds_write_b128 v90, v[142:145] offset:64512
	s_waitcnt vmcnt(8)
	ds_write_b128 v91, v[146:149] offset:32256
	s_waitcnt lgkmcnt(0)
	s_barrier
	global_load_dwordx4 v[118:121], v[78:79], off offset:1152
	global_load_dwordx4 v[122:125], v[80:81], off offset:1152
	global_load_dwordx4 v[126:129], v[74:75], off offset:1152
	global_load_dwordx4 v[130:133], v[76:77], off offset:1152
	global_load_dwordx4 v[134:137], v[82:83], off offset:1152
	global_load_dwordx4 v[138:141], v[84:85], off offset:1152
	global_load_dwordx4 v[142:145], v[86:87], off offset:1152
	global_load_dwordx4 v[146:149], v[88:89], off offset:1152
	v_mfma_f32_32x32x16_bf16 v[34:49], v[182:185], v[186:189], v[34:49]
	v_mfma_f32_32x32x16_bf16 v[50:65], v[182:185], v[198:201], v[50:65]
	v_mfma_f32_32x32x16_bf16 v[2:17], v[190:193], v[194:197], v[2:17]
	v_mfma_f32_32x32x16_bf16 v[18:33], v[190:193], v[202:205], v[18:33]
	v_mfma_f32_32x32x16_bf16 v[34:49], v[206:209], v[194:197], v[34:49]
	v_mfma_f32_32x32x16_bf16 v[50:65], v[206:209], v[202:205], v[50:65]
	ds_read_b128 v[182:185], v66 offset:18432
	ds_read_b128 v[186:189], v67 offset:55296
	ds_read_b128 v[190:193], v66 offset:18464
	ds_read_b128 v[194:197], v67 offset:55328
	ds_read_b128 v[198:201], v67 offset:59904
	ds_read_b128 v[202:205], v67 offset:59936
	s_waitcnt lgkmcnt(4)
	v_mfma_f32_32x32x16_bf16 v[2:17], v[182:185], v[186:189], v[2:17]
	s_waitcnt lgkmcnt(1)
	v_mfma_f32_32x32x16_bf16 v[18:33], v[182:185], v[198:201], v[18:33]
	ds_read_b128 v[182:185], v66 offset:23040
	ds_read_b128 v[206:209], v66 offset:23072
	s_waitcnt lgkmcnt(1)
	v_mfma_f32_32x32x16_bf16 v[34:49], v[182:185], v[186:189], v[34:49]
	v_mfma_f32_32x32x16_bf16 v[50:65], v[182:185], v[198:201], v[50:65]
	v_mfma_f32_32x32x16_bf16 v[2:17], v[190:193], v[194:197], v[2:17]
	v_mfma_f32_32x32x16_bf16 v[18:33], v[190:193], v[202:205], v[18:33]
	s_waitcnt lgkmcnt(0)
	v_mfma_f32_32x32x16_bf16 v[34:49], v[206:209], v[194:197], v[34:49]
	ds_read_b128 v[182:185], v66 offset:18496
	ds_read_b128 v[186:189], v67 offset:55360
	ds_read_b128 v[190:193], v66 offset:18528
	ds_read_b128 v[194:197], v67 offset:55392
	v_mfma_f32_32x32x16_bf16 v[50:65], v[206:209], v[202:205], v[50:65]
	ds_read_b128 v[198:201], v67 offset:59968
	ds_read_b128 v[202:205], v67 offset:60000
	s_waitcnt lgkmcnt(4)
	v_mfma_f32_32x32x16_bf16 v[2:17], v[182:185], v[186:189], v[2:17]
	s_waitcnt lgkmcnt(1)
	v_mfma_f32_32x32x16_bf16 v[18:33], v[182:185], v[198:201], v[18:33]
	ds_read_b128 v[182:185], v66 offset:23104
	ds_read_b128 v[206:209], v66 offset:23136
	s_waitcnt vmcnt(13)
	ds_write_b128 v90, v[158:161]
	ds_write_b128 v90, v[150:153] offset:4608
	ds_write_b128 v90, v[154:157] offset:9216
	s_waitcnt vmcnt(11)
	ds_write_b128 v90, v[166:169] offset:13824
	ds_write_b128 v90, v[162:165] offset:36864
	s_waitcnt vmcnt(10)
	ds_write_b128 v90, v[170:173] offset:41472
	s_waitcnt vmcnt(9)
	ds_write_b128 v90, v[174:177] offset:46080
	s_waitcnt vmcnt(8)
	ds_write_b128 v90, v[178:181] offset:50688
	s_waitcnt lgkmcnt(0)
	s_barrier
	global_load_dwordx4 v[150:153], v[78:79], off offset:1280
	global_load_dwordx4 v[154:157], v[80:81], off offset:1280
	global_load_dwordx4 v[158:161], v[74:75], off offset:1280
	global_load_dwordx4 v[162:165], v[76:77], off offset:1280
	global_load_dwordx4 v[166:169], v[82:83], off offset:1280
	global_load_dwordx4 v[170:173], v[84:85], off offset:1280
	global_load_dwordx4 v[174:177], v[86:87], off offset:1280
	global_load_dwordx4 v[178:181], v[88:89], off offset:1280
	v_mfma_f32_32x32x16_bf16 v[34:49], v[182:185], v[186:189], v[34:49]
	v_mfma_f32_32x32x16_bf16 v[50:65], v[182:185], v[198:201], v[50:65]
	v_mfma_f32_32x32x16_bf16 v[2:17], v[190:193], v[194:197], v[2:17]
	v_mfma_f32_32x32x16_bf16 v[18:33], v[190:193], v[202:205], v[18:33]
	v_mfma_f32_32x32x16_bf16 v[34:49], v[206:209], v[194:197], v[34:49]
	v_mfma_f32_32x32x16_bf16 v[50:65], v[206:209], v[202:205], v[50:65]
	ds_read_b128 v[182:185], v66
	ds_read_b128 v[186:189], v67 offset:36864
	ds_read_b128 v[190:193], v66 offset:32
	ds_read_b128 v[194:197], v67 offset:36896
	ds_read_b128 v[198:201], v67 offset:41472
	ds_read_b128 v[202:205], v67 offset:41504
	s_waitcnt lgkmcnt(4)
	v_mfma_f32_32x32x16_bf16 v[2:17], v[182:185], v[186:189], v[2:17]
	s_waitcnt lgkmcnt(1)
	v_mfma_f32_32x32x16_bf16 v[18:33], v[182:185], v[198:201], v[18:33]
	ds_read_b128 v[182:185], v66 offset:4608
	ds_read_b128 v[206:209], v66 offset:4640
	s_waitcnt lgkmcnt(1)
	v_mfma_f32_32x32x16_bf16 v[34:49], v[182:185], v[186:189], v[34:49]
	v_mfma_f32_32x32x16_bf16 v[50:65], v[182:185], v[198:201], v[50:65]
	v_mfma_f32_32x32x16_bf16 v[2:17], v[190:193], v[194:197], v[2:17]
	v_mfma_f32_32x32x16_bf16 v[18:33], v[190:193], v[202:205], v[18:33]
	s_waitcnt lgkmcnt(0)
	v_mfma_f32_32x32x16_bf16 v[34:49], v[206:209], v[194:197], v[34:49]
	ds_read_b128 v[182:185], v66 offset:64
	ds_read_b128 v[186:189], v67 offset:36928
	ds_read_b128 v[190:193], v66 offset:96
	ds_read_b128 v[194:197], v67 offset:36960
	v_mfma_f32_32x32x16_bf16 v[50:65], v[206:209], v[202:205], v[50:65]
	ds_read_b128 v[198:201], v67 offset:41536
	ds_read_b128 v[202:205], v67 offset:41568
	s_waitcnt lgkmcnt(4)
	v_mfma_f32_32x32x16_bf16 v[2:17], v[182:185], v[186:189], v[2:17]
	s_waitcnt lgkmcnt(1)
	v_mfma_f32_32x32x16_bf16 v[18:33], v[182:185], v[198:201], v[18:33]
	ds_read_b128 v[182:185], v66 offset:4672
	ds_read_b128 v[206:209], v66 offset:4704
	s_waitcnt vmcnt(13)
	ds_write_b128 v90, v[126:129] offset:18432
	ds_write_b128 v90, v[118:121] offset:23040
	ds_write_b128 v90, v[122:125] offset:27648
	s_waitcnt vmcnt(11)
	ds_write_b128 v90, v[134:137] offset:32256
	ds_write_b128 v90, v[130:133] offset:55296
	s_waitcnt vmcnt(10)
	ds_write_b128 v90, v[138:141] offset:59904
	s_waitcnt vmcnt(9)
	ds_write_b128 v90, v[142:145] offset:64512
	s_waitcnt vmcnt(8)
	ds_write_b128 v91, v[146:149] offset:32256
	s_waitcnt lgkmcnt(0)
	s_barrier
	global_load_dwordx4 v[118:121], v[78:79], off offset:1408
	global_load_dwordx4 v[122:125], v[80:81], off offset:1408
	global_load_dwordx4 v[126:129], v[74:75], off offset:1408
	global_load_dwordx4 v[130:133], v[76:77], off offset:1408
	global_load_dwordx4 v[134:137], v[82:83], off offset:1408
	global_load_dwordx4 v[138:141], v[84:85], off offset:1408
	global_load_dwordx4 v[142:145], v[86:87], off offset:1408
	global_load_dwordx4 v[146:149], v[88:89], off offset:1408
	v_mfma_f32_32x32x16_bf16 v[34:49], v[182:185], v[186:189], v[34:49]
	v_mfma_f32_32x32x16_bf16 v[50:65], v[182:185], v[198:201], v[50:65]
	v_mfma_f32_32x32x16_bf16 v[2:17], v[190:193], v[194:197], v[2:17]
	v_mfma_f32_32x32x16_bf16 v[18:33], v[190:193], v[202:205], v[18:33]
	v_mfma_f32_32x32x16_bf16 v[34:49], v[206:209], v[194:197], v[34:49]
	v_mfma_f32_32x32x16_bf16 v[50:65], v[206:209], v[202:205], v[50:65]
	ds_read_b128 v[182:185], v66 offset:18432
	ds_read_b128 v[186:189], v67 offset:55296
	ds_read_b128 v[190:193], v66 offset:18464
	ds_read_b128 v[194:197], v67 offset:55328
	ds_read_b128 v[198:201], v67 offset:59904
	ds_read_b128 v[202:205], v67 offset:59936
	s_waitcnt lgkmcnt(4)
	v_mfma_f32_32x32x16_bf16 v[2:17], v[182:185], v[186:189], v[2:17]
	s_waitcnt lgkmcnt(1)
	v_mfma_f32_32x32x16_bf16 v[18:33], v[182:185], v[198:201], v[18:33]
	ds_read_b128 v[182:185], v66 offset:23040
	ds_read_b128 v[206:209], v66 offset:23072
	s_waitcnt lgkmcnt(1)
	v_mfma_f32_32x32x16_bf16 v[34:49], v[182:185], v[186:189], v[34:49]
	v_mfma_f32_32x32x16_bf16 v[50:65], v[182:185], v[198:201], v[50:65]
	v_mfma_f32_32x32x16_bf16 v[2:17], v[190:193], v[194:197], v[2:17]
	v_mfma_f32_32x32x16_bf16 v[18:33], v[190:193], v[202:205], v[18:33]
	s_waitcnt lgkmcnt(0)
	v_mfma_f32_32x32x16_bf16 v[34:49], v[206:209], v[194:197], v[34:49]
	ds_read_b128 v[182:185], v66 offset:18496
	ds_read_b128 v[186:189], v67 offset:55360
	ds_read_b128 v[190:193], v66 offset:18528
	ds_read_b128 v[194:197], v67 offset:55392
	v_mfma_f32_32x32x16_bf16 v[50:65], v[206:209], v[202:205], v[50:65]
	ds_read_b128 v[198:201], v67 offset:59968
	ds_read_b128 v[202:205], v67 offset:60000
	s_waitcnt lgkmcnt(4)
	v_mfma_f32_32x32x16_bf16 v[2:17], v[182:185], v[186:189], v[2:17]
	s_waitcnt lgkmcnt(1)
	v_mfma_f32_32x32x16_bf16 v[18:33], v[182:185], v[198:201], v[18:33]
	ds_read_b128 v[182:185], v66 offset:23104
	ds_read_b128 v[206:209], v66 offset:23136
	s_waitcnt vmcnt(13)
	ds_write_b128 v90, v[158:161]
	ds_write_b128 v90, v[150:153] offset:4608
	ds_write_b128 v90, v[154:157] offset:9216
	s_waitcnt vmcnt(11)
	ds_write_b128 v90, v[166:169] offset:13824
	ds_write_b128 v90, v[162:165] offset:36864
	s_waitcnt vmcnt(10)
	ds_write_b128 v90, v[170:173] offset:41472
	s_waitcnt vmcnt(9)
	ds_write_b128 v90, v[174:177] offset:46080
	s_waitcnt vmcnt(8)
	ds_write_b128 v90, v[178:181] offset:50688
	s_waitcnt lgkmcnt(0)
	s_barrier
	global_load_dwordx4 v[150:153], v[78:79], off offset:1536
	global_load_dwordx4 v[154:157], v[80:81], off offset:1536
	global_load_dwordx4 v[158:161], v[74:75], off offset:1536
	global_load_dwordx4 v[162:165], v[76:77], off offset:1536
	global_load_dwordx4 v[166:169], v[82:83], off offset:1536
	global_load_dwordx4 v[170:173], v[84:85], off offset:1536
	global_load_dwordx4 v[174:177], v[86:87], off offset:1536
	global_load_dwordx4 v[178:181], v[88:89], off offset:1536
	v_mfma_f32_32x32x16_bf16 v[34:49], v[182:185], v[186:189], v[34:49]
	v_mfma_f32_32x32x16_bf16 v[50:65], v[182:185], v[198:201], v[50:65]
	v_mfma_f32_32x32x16_bf16 v[2:17], v[190:193], v[194:197], v[2:17]
	v_mfma_f32_32x32x16_bf16 v[18:33], v[190:193], v[202:205], v[18:33]
	v_mfma_f32_32x32x16_bf16 v[34:49], v[206:209], v[194:197], v[34:49]
	v_mfma_f32_32x32x16_bf16 v[50:65], v[206:209], v[202:205], v[50:65]
	ds_read_b128 v[182:185], v66
	ds_read_b128 v[186:189], v67 offset:36864
	ds_read_b128 v[190:193], v66 offset:32
	ds_read_b128 v[194:197], v67 offset:36896
	ds_read_b128 v[198:201], v67 offset:41472
	ds_read_b128 v[202:205], v67 offset:41504
	s_waitcnt lgkmcnt(4)
	v_mfma_f32_32x32x16_bf16 v[2:17], v[182:185], v[186:189], v[2:17]
	s_waitcnt lgkmcnt(1)
	v_mfma_f32_32x32x16_bf16 v[18:33], v[182:185], v[198:201], v[18:33]
	ds_read_b128 v[182:185], v66 offset:4608
	ds_read_b128 v[206:209], v66 offset:4640
	s_waitcnt lgkmcnt(1)
	v_mfma_f32_32x32x16_bf16 v[34:49], v[182:185], v[186:189], v[34:49]
	v_mfma_f32_32x32x16_bf16 v[50:65], v[182:185], v[198:201], v[50:65]
	v_mfma_f32_32x32x16_bf16 v[2:17], v[190:193], v[194:197], v[2:17]
	v_mfma_f32_32x32x16_bf16 v[18:33], v[190:193], v[202:205], v[18:33]
	s_waitcnt lgkmcnt(0)
	v_mfma_f32_32x32x16_bf16 v[34:49], v[206:209], v[194:197], v[34:49]
	ds_read_b128 v[182:185], v66 offset:64
	ds_read_b128 v[186:189], v67 offset:36928
	ds_read_b128 v[190:193], v66 offset:96
	ds_read_b128 v[194:197], v67 offset:36960
	v_mfma_f32_32x32x16_bf16 v[50:65], v[206:209], v[202:205], v[50:65]
	ds_read_b128 v[198:201], v67 offset:41536
	ds_read_b128 v[202:205], v67 offset:41568
	s_waitcnt lgkmcnt(4)
	v_mfma_f32_32x32x16_bf16 v[2:17], v[182:185], v[186:189], v[2:17]
	s_waitcnt lgkmcnt(1)
	v_mfma_f32_32x32x16_bf16 v[18:33], v[182:185], v[198:201], v[18:33]
	ds_read_b128 v[182:185], v66 offset:4672
	ds_read_b128 v[206:209], v66 offset:4704
	s_waitcnt vmcnt(13)
	ds_write_b128 v90, v[126:129] offset:18432
	ds_write_b128 v90, v[118:121] offset:23040
	ds_write_b128 v90, v[122:125] offset:27648
	s_waitcnt vmcnt(11)
	ds_write_b128 v90, v[134:137] offset:32256
	ds_write_b128 v90, v[130:133] offset:55296
	s_waitcnt vmcnt(10)
	ds_write_b128 v90, v[138:141] offset:59904
	s_waitcnt vmcnt(9)
	ds_write_b128 v90, v[142:145] offset:64512
	s_waitcnt vmcnt(8)
	ds_write_b128 v91, v[146:149] offset:32256
	s_waitcnt lgkmcnt(0)
	s_barrier
	global_load_dwordx4 v[118:121], v[78:79], off offset:1664
	global_load_dwordx4 v[122:125], v[80:81], off offset:1664
	global_load_dwordx4 v[126:129], v[74:75], off offset:1664
	global_load_dwordx4 v[130:133], v[76:77], off offset:1664
	global_load_dwordx4 v[134:137], v[82:83], off offset:1664
	global_load_dwordx4 v[138:141], v[84:85], off offset:1664
	global_load_dwordx4 v[142:145], v[86:87], off offset:1664
	global_load_dwordx4 v[146:149], v[88:89], off offset:1664
	v_mfma_f32_32x32x16_bf16 v[34:49], v[182:185], v[186:189], v[34:49]
	v_mfma_f32_32x32x16_bf16 v[50:65], v[182:185], v[198:201], v[50:65]
	v_mfma_f32_32x32x16_bf16 v[2:17], v[190:193], v[194:197], v[2:17]
	v_mfma_f32_32x32x16_bf16 v[18:33], v[190:193], v[202:205], v[18:33]
	v_mfma_f32_32x32x16_bf16 v[34:49], v[206:209], v[194:197], v[34:49]
	v_mfma_f32_32x32x16_bf16 v[50:65], v[206:209], v[202:205], v[50:65]
	ds_read_b128 v[182:185], v66 offset:18432
	ds_read_b128 v[186:189], v67 offset:55296
	ds_read_b128 v[190:193], v66 offset:18464
	ds_read_b128 v[194:197], v67 offset:55328
	ds_read_b128 v[198:201], v67 offset:59904
	ds_read_b128 v[202:205], v67 offset:59936
	s_waitcnt lgkmcnt(4)
	v_mfma_f32_32x32x16_bf16 v[2:17], v[182:185], v[186:189], v[2:17]
	s_waitcnt lgkmcnt(1)
	v_mfma_f32_32x32x16_bf16 v[18:33], v[182:185], v[198:201], v[18:33]
	ds_read_b128 v[182:185], v66 offset:23040
	ds_read_b128 v[206:209], v66 offset:23072
	s_waitcnt lgkmcnt(1)
	v_mfma_f32_32x32x16_bf16 v[34:49], v[182:185], v[186:189], v[34:49]
	v_mfma_f32_32x32x16_bf16 v[50:65], v[182:185], v[198:201], v[50:65]
	v_mfma_f32_32x32x16_bf16 v[2:17], v[190:193], v[194:197], v[2:17]
	v_mfma_f32_32x32x16_bf16 v[18:33], v[190:193], v[202:205], v[18:33]
	s_waitcnt lgkmcnt(0)
	v_mfma_f32_32x32x16_bf16 v[34:49], v[206:209], v[194:197], v[34:49]
	ds_read_b128 v[182:185], v66 offset:18496
	ds_read_b128 v[186:189], v67 offset:55360
	ds_read_b128 v[190:193], v66 offset:18528
	ds_read_b128 v[194:197], v67 offset:55392
	v_mfma_f32_32x32x16_bf16 v[50:65], v[206:209], v[202:205], v[50:65]
	ds_read_b128 v[198:201], v67 offset:59968
	ds_read_b128 v[202:205], v67 offset:60000
	s_waitcnt lgkmcnt(4)
	v_mfma_f32_32x32x16_bf16 v[2:17], v[182:185], v[186:189], v[2:17]
	s_waitcnt lgkmcnt(1)
	v_mfma_f32_32x32x16_bf16 v[18:33], v[182:185], v[198:201], v[18:33]
	ds_read_b128 v[182:185], v66 offset:23104
	ds_read_b128 v[206:209], v66 offset:23136
	s_waitcnt vmcnt(13)
	ds_write_b128 v90, v[158:161]
	ds_write_b128 v90, v[150:153] offset:4608
	ds_write_b128 v90, v[154:157] offset:9216
	s_waitcnt vmcnt(11)
	ds_write_b128 v90, v[166:169] offset:13824
	ds_write_b128 v90, v[162:165] offset:36864
	s_waitcnt vmcnt(10)
	ds_write_b128 v90, v[170:173] offset:41472
	s_waitcnt vmcnt(9)
	ds_write_b128 v90, v[174:177] offset:46080
	s_waitcnt vmcnt(8)
	ds_write_b128 v90, v[178:181] offset:50688
	s_waitcnt lgkmcnt(0)
	s_barrier
	global_load_dwordx4 v[150:153], v[78:79], off offset:1792
	global_load_dwordx4 v[154:157], v[80:81], off offset:1792
	global_load_dwordx4 v[158:161], v[74:75], off offset:1792
	global_load_dwordx4 v[162:165], v[76:77], off offset:1792
	global_load_dwordx4 v[166:169], v[82:83], off offset:1792
	global_load_dwordx4 v[170:173], v[84:85], off offset:1792
	global_load_dwordx4 v[174:177], v[86:87], off offset:1792
	global_load_dwordx4 v[178:181], v[88:89], off offset:1792
	v_mfma_f32_32x32x16_bf16 v[34:49], v[182:185], v[186:189], v[34:49]
	v_mfma_f32_32x32x16_bf16 v[50:65], v[182:185], v[198:201], v[50:65]
	v_mfma_f32_32x32x16_bf16 v[2:17], v[190:193], v[194:197], v[2:17]
	v_mfma_f32_32x32x16_bf16 v[18:33], v[190:193], v[202:205], v[18:33]
	v_mfma_f32_32x32x16_bf16 v[34:49], v[206:209], v[194:197], v[34:49]
	v_mfma_f32_32x32x16_bf16 v[50:65], v[206:209], v[202:205], v[50:65]
	ds_read_b128 v[182:185], v66
	ds_read_b128 v[186:189], v67 offset:36864
	ds_read_b128 v[190:193], v66 offset:32
	ds_read_b128 v[194:197], v67 offset:36896
	ds_read_b128 v[198:201], v67 offset:41472
	ds_read_b128 v[202:205], v67 offset:41504
	s_waitcnt lgkmcnt(4)
	v_mfma_f32_32x32x16_bf16 v[2:17], v[182:185], v[186:189], v[2:17]
	s_waitcnt lgkmcnt(1)
	v_mfma_f32_32x32x16_bf16 v[18:33], v[182:185], v[198:201], v[18:33]
	ds_read_b128 v[182:185], v66 offset:4608
	ds_read_b128 v[206:209], v66 offset:4640
	s_waitcnt lgkmcnt(1)
	v_mfma_f32_32x32x16_bf16 v[34:49], v[182:185], v[186:189], v[34:49]
	v_mfma_f32_32x32x16_bf16 v[50:65], v[182:185], v[198:201], v[50:65]
	v_mfma_f32_32x32x16_bf16 v[2:17], v[190:193], v[194:197], v[2:17]
	v_mfma_f32_32x32x16_bf16 v[18:33], v[190:193], v[202:205], v[18:33]
	s_waitcnt lgkmcnt(0)
	v_mfma_f32_32x32x16_bf16 v[34:49], v[206:209], v[194:197], v[34:49]
	ds_read_b128 v[182:185], v66 offset:64
	ds_read_b128 v[186:189], v67 offset:36928
	ds_read_b128 v[190:193], v66 offset:96
	ds_read_b128 v[194:197], v67 offset:36960
	v_mfma_f32_32x32x16_bf16 v[50:65], v[206:209], v[202:205], v[50:65]
	ds_read_b128 v[198:201], v67 offset:41536
	ds_read_b128 v[202:205], v67 offset:41568
	s_waitcnt lgkmcnt(4)
	v_mfma_f32_32x32x16_bf16 v[2:17], v[182:185], v[186:189], v[2:17]
	s_waitcnt lgkmcnt(1)
	v_mfma_f32_32x32x16_bf16 v[18:33], v[182:185], v[198:201], v[18:33]
	ds_read_b128 v[182:185], v66 offset:4672
	ds_read_b128 v[206:209], v66 offset:4704
	s_waitcnt vmcnt(13)
	ds_write_b128 v90, v[126:129] offset:18432
	ds_write_b128 v90, v[118:121] offset:23040
	ds_write_b128 v90, v[122:125] offset:27648
	s_waitcnt vmcnt(11)
	ds_write_b128 v90, v[134:137] offset:32256
	ds_write_b128 v90, v[130:133] offset:55296
	s_waitcnt vmcnt(10)
	ds_write_b128 v90, v[138:141] offset:59904
	s_waitcnt vmcnt(9)
	ds_write_b128 v90, v[142:145] offset:64512
	s_waitcnt vmcnt(8)
	ds_write_b128 v91, v[146:149] offset:32256
	s_waitcnt lgkmcnt(0)
	s_barrier
	global_load_dwordx4 v[118:121], v[78:79], off offset:1920
	s_nop 0
	global_load_dwordx4 v[78:81], v[80:81], off offset:1920
	s_nop 0
	global_load_dwordx4 v[122:125], v[74:75], off offset:1920
	s_nop 0
	global_load_dwordx4 v[74:77], v[76:77], off offset:1920
	s_nop 0
	global_load_dwordx4 v[126:129], v[82:83], off offset:1920
	s_nop 0
	global_load_dwordx4 v[82:85], v[84:85], off offset:1920
	s_nop 0
	global_load_dwordx4 v[130:133], v[86:87], off offset:1920
	s_nop 0
	global_load_dwordx4 v[86:89], v[88:89], off offset:1920
	v_mfma_f32_32x32x16_bf16 v[34:49], v[182:185], v[186:189], v[34:49]
	v_mfma_f32_32x32x16_bf16 v[50:65], v[182:185], v[198:201], v[50:65]
	v_mfma_f32_32x32x16_bf16 v[2:17], v[190:193], v[194:197], v[2:17]
	v_mfma_f32_32x32x16_bf16 v[18:33], v[190:193], v[202:205], v[18:33]
	v_mfma_f32_32x32x16_bf16 v[34:49], v[206:209], v[194:197], v[34:49]
	v_mfma_f32_32x32x16_bf16 v[50:65], v[206:209], v[202:205], v[50:65]
	ds_read_b128 v[134:137], v66 offset:18432
	ds_read_b128 v[138:141], v67 offset:55296
	ds_read_b128 v[142:145], v66 offset:18464
	ds_read_b128 v[146:149], v67 offset:55328
	ds_read_b128 v[182:185], v67 offset:59904
	ds_read_b128 v[186:189], v67 offset:59936
	s_waitcnt lgkmcnt(4)
	v_mfma_f32_32x32x16_bf16 v[2:17], v[134:137], v[138:141], v[2:17]
	s_waitcnt lgkmcnt(1)
	v_mfma_f32_32x32x16_bf16 v[18:33], v[134:137], v[182:185], v[18:33]
	ds_read_b128 v[134:137], v66 offset:23040
	ds_read_b128 v[190:193], v66 offset:23072
	s_waitcnt lgkmcnt(1)
	v_mfma_f32_32x32x16_bf16 v[34:49], v[134:137], v[138:141], v[34:49]
	v_mfma_f32_32x32x16_bf16 v[50:65], v[134:137], v[182:185], v[50:65]
	v_mfma_f32_32x32x16_bf16 v[2:17], v[142:145], v[146:149], v[2:17]
	v_mfma_f32_32x32x16_bf16 v[18:33], v[142:145], v[186:189], v[18:33]
	s_waitcnt lgkmcnt(0)
	v_mfma_f32_32x32x16_bf16 v[34:49], v[190:193], v[146:149], v[34:49]
	ds_read_b128 v[134:137], v66 offset:18496
	ds_read_b128 v[138:141], v67 offset:55360
	ds_read_b128 v[142:145], v66 offset:18528
	ds_read_b128 v[146:149], v67 offset:55392
	v_mfma_f32_32x32x16_bf16 v[50:65], v[190:193], v[186:189], v[50:65]
	ds_read_b128 v[182:185], v67 offset:59968
	ds_read_b128 v[186:189], v67 offset:60000
	s_waitcnt lgkmcnt(4)
	v_mfma_f32_32x32x16_bf16 v[2:17], v[134:137], v[138:141], v[2:17]
	s_waitcnt lgkmcnt(1)
	v_mfma_f32_32x32x16_bf16 v[18:33], v[134:137], v[182:185], v[18:33]
	ds_read_b128 v[134:137], v66 offset:23104
	ds_read_b128 v[190:193], v66 offset:23136
	s_waitcnt vmcnt(13)
	ds_write_b128 v90, v[158:161]
	ds_write_b128 v90, v[150:153] offset:4608
	ds_write_b128 v90, v[154:157] offset:9216
	s_waitcnt vmcnt(11)
	ds_write_b128 v90, v[166:169] offset:13824
	ds_write_b128 v90, v[162:165] offset:36864
	s_waitcnt vmcnt(10)
	ds_write_b128 v90, v[170:173] offset:41472
	s_waitcnt vmcnt(9)
	ds_write_b128 v90, v[174:177] offset:46080
	s_waitcnt vmcnt(8)
	ds_write_b128 v90, v[178:181] offset:50688
	s_waitcnt lgkmcnt(0)
	s_barrier
	v_mfma_f32_32x32x16_bf16 v[34:49], v[134:137], v[138:141], v[34:49]
	v_mfma_f32_32x32x16_bf16 v[50:65], v[134:137], v[182:185], v[50:65]
	v_mfma_f32_32x32x16_bf16 v[2:17], v[142:145], v[146:149], v[2:17]
	v_mfma_f32_32x32x16_bf16 v[18:33], v[142:145], v[186:189], v[18:33]
	v_mfma_f32_32x32x16_bf16 v[34:49], v[190:193], v[146:149], v[34:49]
	v_mfma_f32_32x32x16_bf16 v[50:65], v[190:193], v[186:189], v[50:65]
	ds_read_b128 v[134:137], v66
	ds_read_b128 v[138:141], v67 offset:36864
	ds_read_b128 v[142:145], v66 offset:32
	ds_read_b128 v[146:149], v67 offset:36896
	ds_read_b128 v[150:153], v67 offset:41472
	ds_read_b128 v[154:157], v67 offset:41504
	s_waitcnt lgkmcnt(4)
	v_mfma_f32_32x32x16_bf16 v[2:17], v[134:137], v[138:141], v[2:17]
	s_waitcnt lgkmcnt(1)
	v_mfma_f32_32x32x16_bf16 v[18:33], v[134:137], v[150:153], v[18:33]
	ds_read_b128 v[134:137], v66 offset:4608
	ds_read_b128 v[158:161], v66 offset:4640
	s_waitcnt lgkmcnt(1)
	v_mfma_f32_32x32x16_bf16 v[34:49], v[134:137], v[138:141], v[34:49]
	v_mfma_f32_32x32x16_bf16 v[50:65], v[134:137], v[150:153], v[50:65]
	v_mfma_f32_32x32x16_bf16 v[2:17], v[142:145], v[146:149], v[2:17]
	v_mfma_f32_32x32x16_bf16 v[18:33], v[142:145], v[154:157], v[18:33]
	s_waitcnt lgkmcnt(0)
	v_mfma_f32_32x32x16_bf16 v[34:49], v[158:161], v[146:149], v[34:49]
	ds_read_b128 v[134:137], v66 offset:64
	ds_read_b128 v[138:141], v67 offset:36928
	ds_read_b128 v[142:145], v66 offset:96
	ds_read_b128 v[146:149], v67 offset:36960
	v_mfma_f32_32x32x16_bf16 v[50:65], v[158:161], v[154:157], v[50:65]
	ds_read_b128 v[150:153], v67 offset:41536
	ds_read_b128 v[154:157], v67 offset:41568
	s_waitcnt lgkmcnt(4)
	v_mfma_f32_32x32x16_bf16 v[2:17], v[134:137], v[138:141], v[2:17]
	s_waitcnt lgkmcnt(1)
	v_mfma_f32_32x32x16_bf16 v[18:33], v[134:137], v[150:153], v[18:33]
	ds_read_b128 v[134:137], v66 offset:4672
	ds_read_b128 v[158:161], v66 offset:4704
	s_waitcnt vmcnt(5)
	ds_write_b128 v90, v[122:125] offset:18432
	ds_write_b128 v90, v[118:121] offset:23040
	ds_write_b128 v90, v[78:81] offset:27648
	s_waitcnt vmcnt(3)
	ds_write_b128 v90, v[126:129] offset:32256
	ds_write_b128 v90, v[74:77] offset:55296
	s_waitcnt vmcnt(2)
	ds_write_b128 v90, v[82:85] offset:59904
	s_waitcnt vmcnt(1)
	ds_write_b128 v90, v[130:133] offset:64512
	s_waitcnt vmcnt(0)
	ds_write_b128 v91, v[86:89] offset:32256
	s_waitcnt lgkmcnt(0)
	s_barrier
	v_mfma_f32_32x32x16_bf16 v[34:49], v[134:137], v[138:141], v[34:49]
	v_mfma_f32_32x32x16_bf16 v[50:65], v[134:137], v[150:153], v[50:65]
	v_mfma_f32_32x32x16_bf16 v[2:17], v[142:145], v[146:149], v[2:17]
	v_mfma_f32_32x32x16_bf16 v[18:33], v[142:145], v[154:157], v[18:33]
	v_mfma_f32_32x32x16_bf16 v[34:49], v[158:161], v[146:149], v[34:49]
	v_mfma_f32_32x32x16_bf16 v[50:65], v[158:161], v[154:157], v[50:65]
	ds_read_b128 v[74:77], v66 offset:18432
	ds_read_b128 v[78:81], v67 offset:55296
	ds_read_b128 v[82:85], v66 offset:18464
	ds_read_b128 v[86:89], v67 offset:55328
	ds_read_b128 v[118:121], v67 offset:59904
	ds_read_b128 v[122:125], v67 offset:59936
	s_mov_b32 s12, 0
	s_waitcnt lgkmcnt(4)
	v_mfma_f32_32x32x16_bf16 v[2:17], v[74:77], v[78:81], v[2:17]
	s_waitcnt lgkmcnt(1)
	v_mfma_f32_32x32x16_bf16 v[18:33], v[74:77], v[118:121], v[18:33]
	ds_read_b128 v[74:77], v66 offset:23040
	ds_read_b128 v[126:129], v66 offset:23072
	s_waitcnt lgkmcnt(1)
	v_mfma_f32_32x32x16_bf16 v[34:49], v[74:77], v[78:81], v[34:49]
	v_mfma_f32_32x32x16_bf16 v[50:65], v[74:77], v[118:121], v[50:65]
	v_mfma_f32_32x32x16_bf16 v[2:17], v[82:85], v[86:89], v[2:17]
	v_mfma_f32_32x32x16_bf16 v[18:33], v[82:85], v[122:125], v[18:33]
	s_waitcnt lgkmcnt(0)
	v_mfma_f32_32x32x16_bf16 v[34:49], v[126:129], v[86:89], v[34:49]
	ds_read_b128 v[74:77], v66 offset:18496
	ds_read_b128 v[78:81], v67 offset:55360
	ds_read_b128 v[82:85], v66 offset:18528
	ds_read_b128 v[86:89], v67 offset:55392
	v_mfma_f32_32x32x16_bf16 v[50:65], v[126:129], v[122:125], v[50:65]
	ds_read_b128 v[118:121], v67 offset:59968
	ds_read_b128 v[122:125], v67 offset:60000
	s_waitcnt lgkmcnt(4)
	v_mfma_f32_32x32x16_bf16 v[2:17], v[74:77], v[78:81], v[2:17]
	s_waitcnt lgkmcnt(1)
	v_mfma_f32_32x32x16_bf16 v[18:33], v[74:77], v[118:121], v[18:33]
	ds_read_b128 v[74:77], v66 offset:23104
	ds_read_b128 v[126:129], v66 offset:23136
	s_waitcnt lgkmcnt(0)
	s_barrier
	v_mfma_f32_32x32x16_bf16 v[34:49], v[74:77], v[78:81], v[34:49]
	v_mfma_f32_32x32x16_bf16 v[50:65], v[74:77], v[118:121], v[50:65]
	v_mfma_f32_32x32x16_bf16 v[2:17], v[82:85], v[86:89], v[2:17]
	v_mfma_f32_32x32x16_bf16 v[18:33], v[82:85], v[122:125], v[18:33]
	v_mfma_f32_32x32x16_bf16 v[34:49], v[126:129], v[86:89], v[34:49]
	s_nop 10
	ds_write2_b32 v93, v2, v18 offset1:32
	v_mfma_f32_32x32x16_bf16 v[50:65], v[126:129], v[122:125], v[50:65]
	s_nop 11
	ds_write2_b32 v100, v34, v50 offset0:32 offset1:64
	ds_write2_b32 v93, v3, v19 offset0:129 offset1:161
	ds_write2_b32 v100, v35, v51 offset0:161 offset1:193
	ds_write2_b32 v101, v4, v20 offset0:2 offset1:34
	ds_write2_b32 v102, v36, v52 offset0:34 offset1:66
	ds_write2_b32 v101, v5, v21 offset0:131 offset1:163
	ds_write2_b32 v102, v37, v53 offset0:163 offset1:195
	ds_write2_b32 v103, v6, v22 offset0:8 offset1:40
	ds_write2_b32 v104, v38, v54 offset0:40 offset1:72
	ds_write2_b32 v103, v7, v23 offset0:137 offset1:169
	ds_write2_b32 v104, v39, v55 offset0:169 offset1:201
	ds_write2_b32 v105, v8, v24 offset0:10 offset1:42
	ds_write2_b32 v106, v40, v56 offset0:42 offset1:74
	ds_write2_b32 v105, v9, v25 offset0:139 offset1:171
	ds_write2_b32 v106, v41, v57 offset0:171 offset1:203
	ds_write2_b32 v107, v10, v26 offset0:16 offset1:48
	ds_write2_b32 v108, v42, v58 offset0:48 offset1:80
	ds_write2_b32 v107, v11, v27 offset0:145 offset1:177
	ds_write2_b32 v108, v43, v59 offset0:177 offset1:209
	ds_write2_b32 v109, v12, v28 offset0:18 offset1:50
	ds_write2_b32 v110, v44, v60 offset0:50 offset1:82
	ds_write2_b32 v109, v13, v29 offset0:147 offset1:179
	ds_write2_b32 v110, v45, v61 offset0:179 offset1:211
	ds_write2_b32 v111, v14, v30 offset0:24 offset1:56
	ds_write2_b32 v112, v46, v62 offset0:56 offset1:88
	ds_write2_b32 v111, v15, v31 offset0:153 offset1:185
	ds_write2_b32 v112, v47, v63 offset0:185 offset1:217
	ds_write2_b32 v113, v16, v32 offset0:26 offset1:58
	ds_write2_b32 v114, v48, v64 offset0:58 offset1:90
	ds_write2_b32 v113, v17, v33 offset0:155 offset1:187
	ds_write2_b32 v114, v49, v65 offset0:187 offset1:219
	v_or_b32_e32 v8, s23, v92
	v_lshlrev_b32_e32 v68, 2, v8
	s_waitcnt lgkmcnt(0)
	s_barrier
	v_mov_b32_e32 v2, v8
	v_mov_b32_e32 v3, v116
	v_lshlrev_b32_e32 v64, 12, v3
	v_lshl_add_u32 v64, v2, 2, v64
	v_lshlrev_b32_e32 v74, 2, v2
	global_load_dwordx4 v[128:131], v74, s[8:9]
	global_load_dwordx4 v[4:7], v64, s[80:81]
	v_add_u32_e32 v74, 0x8000, v64
	global_load_dwordx4 v[8:11], v74, s[80:81]
	v_add_u32_e32 v65, 0x10000, v64
	global_load_dwordx4 v[12:15], v65, s[80:81]
	v_add_u32_e32 v74, 0x18000, v64
	global_load_dwordx4 v[16:19], v74, s[80:81]
	v_add_u32_e32 v65, 0x20000, v64
	global_load_dwordx4 v[20:23], v65, s[80:81]
	v_add_u32_e32 v74, 0x28000, v64
	global_load_dwordx4 v[24:27], v74, s[80:81]
	v_add_u32_e32 v65, 0x30000, v64
	global_load_dwordx4 v[28:31], v65, s[80:81]
	v_add_u32_e32 v74, 0x38000, v64
	global_load_dwordx4 v[32:35], v74, s[80:81]
	v_add_u32_e32 v65, 0x40000, v64
	global_load_dwordx4 v[36:39], v65, s[80:81]
	v_add_u32_e32 v74, 0x48000, v64
	global_load_dwordx4 v[40:43], v74, s[80:81]
	v_add_u32_e32 v65, 0x50000, v64
	global_load_dwordx4 v[44:47], v65, s[80:81]
	v_add_u32_e32 v74, 0x58000, v64
	global_load_dwordx4 v[48:51], v74, s[80:81]
	v_add_u32_e32 v65, 0x60000, v64
	global_load_dwordx4 v[52:55], v65, s[80:81]
	v_add_u32_e32 v74, 0x68000, v64
	global_load_dwordx4 v[56:59], v74, s[80:81]
	v_add_u32_e32 v65, 0x70000, v64
	global_load_dwordx4 v[60:63], v65, s[80:81]
	v_add_u32_e32 v74, 0x78000, v64
	global_load_dwordx4 v[76:79], v74, s[80:81]
	v_and_b32_e32 v75, 7, v3
	v_mul_u32_u24_e32 v75, 0x204, v75
	v_and_b32_e32 v88, 0x7f, v2
	v_lshl_add_u32 v75, v88, 2, v75
	v_lshlrev_b32_e32 v162, 2, v3
	s_movk_i32 s12, 0x7fff
	v_mov_b32_e32 v163, 1
	ds_read2_b32 v[80:81], v75 offset1:1
	ds_read2_b32 v[82:83], v75 offset0:2 offset1:3
	v_add_u32_e32 v89, 0x1020, v75
	ds_read2_b32 v[84:85], v89 offset1:1
	ds_read2_b32 v[86:87], v89 offset0:2 offset1:3
	v_add_u32_e32 v88, 0x2040, v75
	ds_read2_b32 v[118:119], v88 offset1:1
	ds_read2_b32 v[120:121], v88 offset0:2 offset1:3
	v_add_u32_e32 v89, 0x3060, v75
	ds_read2_b32 v[122:123], v89 offset1:1
	ds_read2_b32 v[124:125], v89 offset0:2 offset1:3
	s_waitcnt vmcnt(15) lgkmcnt(6)
	v_pk_add_f32 v[4:5], v[4:5], v[80:81]
	v_pk_add_f32 v[6:7], v[6:7], v[82:83]
	s_waitcnt vmcnt(14) lgkmcnt(4)
	v_pk_add_f32 v[8:9], v[8:9], v[84:85]
	v_pk_add_f32 v[10:11], v[10:11], v[86:87]
	s_waitcnt vmcnt(13) lgkmcnt(2)
	v_pk_add_f32 v[12:13], v[12:13], v[118:119]
	v_pk_add_f32 v[14:15], v[14:15], v[120:121]
	s_waitcnt vmcnt(12) lgkmcnt(0)
	v_pk_add_f32 v[16:17], v[16:17], v[122:123]
	v_pk_add_f32 v[18:19], v[18:19], v[124:125]
	v_add_u32_e32 v88, 0x4080, v75
	ds_read2_b32 v[80:81], v88 offset1:1
	ds_read2_b32 v[82:83], v88 offset0:2 offset1:3
	v_add_u32_e32 v89, 0x50a0, v75
	ds_read2_b32 v[84:85], v89 offset1:1
	ds_read2_b32 v[86:87], v89 offset0:2 offset1:3
	v_add_u32_e32 v88, 0x60c0, v75
	ds_read2_b32 v[118:119], v88 offset1:1
	ds_read2_b32 v[120:121], v88 offset0:2 offset1:3
	v_add_u32_e32 v89, 0x70e0, v75
	ds_read2_b32 v[122:123], v89 offset1:1
	ds_read2_b32 v[124:125], v89 offset0:2 offset1:3
	global_store_dwordx4 v64, v[4:7], s[80:81]
	v_pk_mul_f32 v[146:147], v[4:5], v[4:5]
	v_pk_mul_f32 v[148:149], v[6:7], v[6:7]
	v_pk_mul_f32 v[150:151], v[4:5], v[128:129]
	v_pk_mul_f32 v[152:153], v[6:7], v[130:131]
	v_lshrrev_b32_e32 v164, 1, v64
	v_add_f32_e32 v126, v146, v147
	v_and_b32_sdwa v154, v150, v163 dst_sel:DWORD dst_unused:UNUSED_PAD src0_sel:WORD_1 src1_sel:DWORD
	v_and_b32_sdwa v155, v151, v163 dst_sel:DWORD dst_unused:UNUSED_PAD src0_sel:WORD_1 src1_sel:DWORD
	v_and_b32_sdwa v156, v152, v163 dst_sel:DWORD dst_unused:UNUSED_PAD src0_sel:WORD_1 src1_sel:DWORD
	v_and_b32_sdwa v157, v153, v163 dst_sel:DWORD dst_unused:UNUSED_PAD src0_sel:WORD_1 src1_sel:DWORD
	v_add_f32_e32 v126, v126, v148
	v_add3_u32 v150, v150, v154, s12
	v_add3_u32 v151, v151, v155, s12
	v_add3_u32 v152, v152, v156, s12
	v_add3_u32 v153, v153, v157, s12
	v_add_f32_e32 v126, v126, v149
	v_and_b32_e32 v151, 0xffff0000, v151
	v_and_b32_e32 v153, 0xffff0000, v153
	s_nop 0
	v_or_b32_sdwa v158, v151, v150 dst_sel:DWORD dst_unused:UNUSED_PAD src0_sel:DWORD src1_sel:WORD_1
	v_or_b32_sdwa v159, v153, v152 dst_sel:DWORD dst_unused:UNUSED_PAD src0_sel:DWORD src1_sel:WORD_1
	global_store_dwordx2 v164, v[158:159], s[92:93]
	v_add_u32_e32 v74, 0x8000, v64
	global_store_dwordx4 v74, v[8:11], s[80:81]
	v_pk_mul_f32 v[146:147], v[8:9], v[8:9]
	v_pk_mul_f32 v[148:149], v[10:11], v[10:11]
	v_pk_mul_f32 v[150:151], v[8:9], v[128:129]
	v_pk_mul_f32 v[152:153], v[10:11], v[130:131]
	v_lshrrev_b32_e32 v165, 1, v74
	v_add_f32_e32 v127, v146, v147
	v_and_b32_sdwa v154, v150, v163 dst_sel:DWORD dst_unused:UNUSED_PAD src0_sel:WORD_1 src1_sel:DWORD
	v_and_b32_sdwa v155, v151, v163 dst_sel:DWORD dst_unused:UNUSED_PAD src0_sel:WORD_1 src1_sel:DWORD
	v_and_b32_sdwa v156, v152, v163 dst_sel:DWORD dst_unused:UNUSED_PAD src0_sel:WORD_1 src1_sel:DWORD
	v_and_b32_sdwa v157, v153, v163 dst_sel:DWORD dst_unused:UNUSED_PAD src0_sel:WORD_1 src1_sel:DWORD
	v_add_f32_e32 v127, v127, v148
	v_add3_u32 v150, v150, v154, s12
	v_add3_u32 v151, v151, v155, s12
	v_add3_u32 v152, v152, v156, s12
	v_add3_u32 v153, v153, v157, s12
	v_add_f32_e32 v127, v127, v149
	v_and_b32_e32 v151, 0xffff0000, v151
	v_and_b32_e32 v153, 0xffff0000, v153
	s_nop 0
	v_or_b32_sdwa v160, v151, v150 dst_sel:DWORD dst_unused:UNUSED_PAD src0_sel:DWORD src1_sel:WORD_1
	v_or_b32_sdwa v161, v153, v152 dst_sel:DWORD dst_unused:UNUSED_PAD src0_sel:DWORD src1_sel:WORD_1
	global_store_dwordx2 v165, v[160:161], s[92:93]
	v_add_u32_e32 v65, 0x10000, v64
	global_store_dwordx4 v65, v[12:15], s[80:81]
	v_pk_mul_f32 v[146:147], v[12:13], v[12:13]
	v_pk_mul_f32 v[148:149], v[14:15], v[14:15]
	v_pk_mul_f32 v[150:151], v[12:13], v[128:129]
	v_pk_mul_f32 v[152:153], v[14:15], v[130:131]
	v_lshrrev_b32_e32 v164, 1, v65
	v_add_f32_e32 v132, v146, v147
	v_and_b32_sdwa v154, v150, v163 dst_sel:DWORD dst_unused:UNUSED_PAD src0_sel:WORD_1 src1_sel:DWORD
	v_and_b32_sdwa v155, v151, v163 dst_sel:DWORD dst_unused:UNUSED_PAD src0_sel:WORD_1 src1_sel:DWORD
	v_and_b32_sdwa v156, v152, v163 dst_sel:DWORD dst_unused:UNUSED_PAD src0_sel:WORD_1 src1_sel:DWORD
	v_and_b32_sdwa v157, v153, v163 dst_sel:DWORD dst_unused:UNUSED_PAD src0_sel:WORD_1 src1_sel:DWORD
	v_add_f32_e32 v132, v132, v148
	v_add3_u32 v150, v150, v154, s12
	v_add3_u32 v151, v151, v155, s12
	v_add3_u32 v152, v152, v156, s12
	v_add3_u32 v153, v153, v157, s12
	v_add_f32_e32 v132, v132, v149
	v_and_b32_e32 v151, 0xffff0000, v151
	v_and_b32_e32 v153, 0xffff0000, v153
	s_nop 0
	v_or_b32_sdwa v158, v151, v150 dst_sel:DWORD dst_unused:UNUSED_PAD src0_sel:DWORD src1_sel:WORD_1
	v_or_b32_sdwa v159, v153, v152 dst_sel:DWORD dst_unused:UNUSED_PAD src0_sel:DWORD src1_sel:WORD_1
	global_store_dwordx2 v164, v[158:159], s[92:93]
	v_add_u32_e32 v74, 0x18000, v64
	global_store_dwordx4 v74, v[16:19], s[80:81]
	v_pk_mul_f32 v[146:147], v[16:17], v[16:17]
	v_pk_mul_f32 v[148:149], v[18:19], v[18:19]
	v_pk_mul_f32 v[150:151], v[16:17], v[128:129]
	v_pk_mul_f32 v[152:153], v[18:19], v[130:131]
	v_lshrrev_b32_e32 v165, 1, v74
	v_add_f32_e32 v133, v146, v147
	v_and_b32_sdwa v154, v150, v163 dst_sel:DWORD dst_unused:UNUSED_PAD src0_sel:WORD_1 src1_sel:DWORD
	v_and_b32_sdwa v155, v151, v163 dst_sel:DWORD dst_unused:UNUSED_PAD src0_sel:WORD_1 src1_sel:DWORD
	v_and_b32_sdwa v156, v152, v163 dst_sel:DWORD dst_unused:UNUSED_PAD src0_sel:WORD_1 src1_sel:DWORD
	v_and_b32_sdwa v157, v153, v163 dst_sel:DWORD dst_unused:UNUSED_PAD src0_sel:WORD_1 src1_sel:DWORD
	v_add_f32_e32 v133, v133, v148
	v_add3_u32 v150, v150, v154, s12
	v_add3_u32 v151, v151, v155, s12
	v_add3_u32 v152, v152, v156, s12
	v_add3_u32 v153, v153, v157, s12
	v_add_f32_e32 v133, v133, v149
	v_and_b32_e32 v151, 0xffff0000, v151
	v_and_b32_e32 v153, 0xffff0000, v153
	s_nop 0
	v_or_b32_sdwa v160, v151, v150 dst_sel:DWORD dst_unused:UNUSED_PAD src0_sel:DWORD src1_sel:WORD_1
	v_or_b32_sdwa v161, v153, v152 dst_sel:DWORD dst_unused:UNUSED_PAD src0_sel:DWORD src1_sel:WORD_1
	global_store_dwordx2 v165, v[160:161], s[92:93]
	s_nop 1
	v_add_f32_dpp v126, v126, v126 quad_perm:[1,0,3,2] row_mask:0xf bank_mask:0xf
	v_add_f32_dpp v127, v127, v127 quad_perm:[1,0,3,2] row_mask:0xf bank_mask:0xf
	v_add_f32_dpp v132, v132, v132 quad_perm:[1,0,3,2] row_mask:0xf bank_mask:0xf
	v_add_f32_dpp v133, v133, v133 quad_perm:[1,0,3,2] row_mask:0xf bank_mask:0xf
	v_add_f32_dpp v126, v126, v126 quad_perm:[2,3,0,1] row_mask:0xf bank_mask:0xf
	v_add_f32_dpp v127, v127, v127 quad_perm:[2,3,0,1] row_mask:0xf bank_mask:0xf
	v_add_f32_dpp v132, v132, v132 quad_perm:[2,3,0,1] row_mask:0xf bank_mask:0xf
	v_add_f32_dpp v133, v133, v133 quad_perm:[2,3,0,1] row_mask:0xf bank_mask:0xf
	v_add_f32_dpp v126, v126, v126 row_half_mirror row_mask:0xf bank_mask:0xf
	v_add_f32_dpp v127, v127, v127 row_half_mirror row_mask:0xf bank_mask:0xf
	v_add_f32_dpp v132, v132, v132 row_half_mirror row_mask:0xf bank_mask:0xf
	v_add_f32_dpp v133, v133, v133 row_half_mirror row_mask:0xf bank_mask:0xf
	v_add_f32_dpp v126, v126, v126 row_mirror row_mask:0xf bank_mask:0xf
	v_add_f32_dpp v127, v127, v127 row_mirror row_mask:0xf bank_mask:0xf
	v_add_f32_dpp v132, v132, v132 row_mirror row_mask:0xf bank_mask:0xf
	v_add_f32_dpp v133, v133, v133 row_mirror row_mask:0xf bank_mask:0xf
	v_add_f32_dpp v126, v126, v126 row_bcast:15 row_mask:0xa bank_mask:0xf
	v_add_f32_dpp v127, v127, v127 row_bcast:15 row_mask:0xa bank_mask:0xf
	v_add_f32_dpp v132, v132, v132 row_bcast:15 row_mask:0xa bank_mask:0xf
	v_add_f32_dpp v133, v133, v133 row_bcast:15 row_mask:0xa bank_mask:0xf
	s_waitcnt vmcnt(19) lgkmcnt(6)
	v_pk_add_f32 v[20:21], v[20:21], v[80:81]
	v_pk_add_f32 v[22:23], v[22:23], v[82:83]
	s_waitcnt vmcnt(18) lgkmcnt(4)
	v_pk_add_f32 v[24:25], v[24:25], v[84:85]
	v_pk_add_f32 v[26:27], v[26:27], v[86:87]
	s_waitcnt vmcnt(17) lgkmcnt(2)
	v_pk_add_f32 v[28:29], v[28:29], v[118:119]
	v_pk_add_f32 v[30:31], v[30:31], v[120:121]
	s_waitcnt vmcnt(16) lgkmcnt(0)
	v_pk_add_f32 v[32:33], v[32:33], v[122:123]
	v_pk_add_f32 v[34:35], v[34:35], v[124:125]
	v_add_u32_e32 v88, 0x8100, v75
	ds_read2_b32 v[80:81], v88 offset1:1
	ds_read2_b32 v[82:83], v88 offset0:2 offset1:3
	v_add_u32_e32 v89, 0x9120, v75
	ds_read2_b32 v[84:85], v89 offset1:1
	ds_read2_b32 v[86:87], v89 offset0:2 offset1:3
	v_add_u32_e32 v88, 0xa140, v75
	ds_read2_b32 v[118:119], v88 offset1:1
	ds_read2_b32 v[120:121], v88 offset0:2 offset1:3
	v_add_u32_e32 v89, 0xb160, v75
	ds_read2_b32 v[122:123], v89 offset1:1
	ds_read2_b32 v[124:125], v89 offset0:2 offset1:3
	v_add_u32_e32 v65, 0x20000, v64
	global_store_dwordx4 v65, v[20:23], s[80:81]
	v_pk_mul_f32 v[146:147], v[20:21], v[20:21]
	v_pk_mul_f32 v[148:149], v[22:23], v[22:23]
	v_pk_mul_f32 v[150:151], v[20:21], v[128:129]
	v_pk_mul_f32 v[152:153], v[22:23], v[130:131]
	v_lshrrev_b32_e32 v164, 1, v65
	v_add_f32_e32 v134, v146, v147
	v_and_b32_sdwa v154, v150, v163 dst_sel:DWORD dst_unused:UNUSED_PAD src0_sel:WORD_1 src1_sel:DWORD
	v_and_b32_sdwa v155, v151, v163 dst_sel:DWORD dst_unused:UNUSED_PAD src0_sel:WORD_1 src1_sel:DWORD
	v_and_b32_sdwa v156, v152, v163 dst_sel:DWORD dst_unused:UNUSED_PAD src0_sel:WORD_1 src1_sel:DWORD
	v_and_b32_sdwa v157, v153, v163 dst_sel:DWORD dst_unused:UNUSED_PAD src0_sel:WORD_1 src1_sel:DWORD
	v_add_f32_e32 v134, v134, v148
	v_add3_u32 v150, v150, v154, s12
	v_add3_u32 v151, v151, v155, s12
	v_add3_u32 v152, v152, v156, s12
	v_add3_u32 v153, v153, v157, s12
	v_add_f32_e32 v134, v134, v149
	v_and_b32_e32 v151, 0xffff0000, v151
	v_and_b32_e32 v153, 0xffff0000, v153
	s_nop 0
	v_or_b32_sdwa v158, v151, v150 dst_sel:DWORD dst_unused:UNUSED_PAD src0_sel:DWORD src1_sel:WORD_1
	v_or_b32_sdwa v159, v153, v152 dst_sel:DWORD dst_unused:UNUSED_PAD src0_sel:DWORD src1_sel:WORD_1
	global_store_dwordx2 v164, v[158:159], s[92:93]
	v_add_u32_e32 v74, 0x28000, v64
	global_store_dwordx4 v74, v[24:27], s[80:81]
	v_pk_mul_f32 v[146:147], v[24:25], v[24:25]
	v_pk_mul_f32 v[148:149], v[26:27], v[26:27]
	v_pk_mul_f32 v[150:151], v[24:25], v[128:129]
	v_pk_mul_f32 v[152:153], v[26:27], v[130:131]
	v_lshrrev_b32_e32 v165, 1, v74
	v_add_f32_e32 v135, v146, v147
	v_and_b32_sdwa v154, v150, v163 dst_sel:DWORD dst_unused:UNUSED_PAD src0_sel:WORD_1 src1_sel:DWORD
	v_and_b32_sdwa v155, v151, v163 dst_sel:DWORD dst_unused:UNUSED_PAD src0_sel:WORD_1 src1_sel:DWORD
	v_and_b32_sdwa v156, v152, v163 dst_sel:DWORD dst_unused:UNUSED_PAD src0_sel:WORD_1 src1_sel:DWORD
	v_and_b32_sdwa v157, v153, v163 dst_sel:DWORD dst_unused:UNUSED_PAD src0_sel:WORD_1 src1_sel:DWORD
	v_add_f32_e32 v135, v135, v148
	v_add3_u32 v150, v150, v154, s12
	v_add3_u32 v151, v151, v155, s12
	v_add3_u32 v152, v152, v156, s12
	v_add3_u32 v153, v153, v157, s12
	v_add_f32_e32 v135, v135, v149
	v_and_b32_e32 v151, 0xffff0000, v151
	v_and_b32_e32 v153, 0xffff0000, v153
	s_nop 0
	v_or_b32_sdwa v160, v151, v150 dst_sel:DWORD dst_unused:UNUSED_PAD src0_sel:DWORD src1_sel:WORD_1
	v_or_b32_sdwa v161, v153, v152 dst_sel:DWORD dst_unused:UNUSED_PAD src0_sel:DWORD src1_sel:WORD_1
	global_store_dwordx2 v165, v[160:161], s[92:93]
	v_add_u32_e32 v65, 0x30000, v64
	global_store_dwordx4 v65, v[28:31], s[80:81]
	v_pk_mul_f32 v[146:147], v[28:29], v[28:29]
	v_pk_mul_f32 v[148:149], v[30:31], v[30:31]
	v_pk_mul_f32 v[150:151], v[28:29], v[128:129]
	v_pk_mul_f32 v[152:153], v[30:31], v[130:131]
	v_lshrrev_b32_e32 v164, 1, v65
	v_add_f32_e32 v136, v146, v147
	v_and_b32_sdwa v154, v150, v163 dst_sel:DWORD dst_unused:UNUSED_PAD src0_sel:WORD_1 src1_sel:DWORD
	v_and_b32_sdwa v155, v151, v163 dst_sel:DWORD dst_unused:UNUSED_PAD src0_sel:WORD_1 src1_sel:DWORD
	v_and_b32_sdwa v156, v152, v163 dst_sel:DWORD dst_unused:UNUSED_PAD src0_sel:WORD_1 src1_sel:DWORD
	v_and_b32_sdwa v157, v153, v163 dst_sel:DWORD dst_unused:UNUSED_PAD src0_sel:WORD_1 src1_sel:DWORD
	v_add_f32_e32 v136, v136, v148
	v_add3_u32 v150, v150, v154, s12
	v_add3_u32 v151, v151, v155, s12
	v_add3_u32 v152, v152, v156, s12
	v_add3_u32 v153, v153, v157, s12
	v_add_f32_e32 v136, v136, v149
	v_and_b32_e32 v151, 0xffff0000, v151
	v_and_b32_e32 v153, 0xffff0000, v153
	s_nop 0
	v_or_b32_sdwa v158, v151, v150 dst_sel:DWORD dst_unused:UNUSED_PAD src0_sel:DWORD src1_sel:WORD_1
	v_or_b32_sdwa v159, v153, v152 dst_sel:DWORD dst_unused:UNUSED_PAD src0_sel:DWORD src1_sel:WORD_1
	global_store_dwordx2 v164, v[158:159], s[92:93]
	v_add_u32_e32 v74, 0x38000, v64
	global_store_dwordx4 v74, v[32:35], s[80:81]
	v_pk_mul_f32 v[146:147], v[32:33], v[32:33]
	v_pk_mul_f32 v[148:149], v[34:35], v[34:35]
	v_pk_mul_f32 v[150:151], v[32:33], v[128:129]
	v_pk_mul_f32 v[152:153], v[34:35], v[130:131]
	v_lshrrev_b32_e32 v165, 1, v74
	v_add_f32_e32 v137, v146, v147
	v_and_b32_sdwa v154, v150, v163 dst_sel:DWORD dst_unused:UNUSED_PAD src0_sel:WORD_1 src1_sel:DWORD
	v_and_b32_sdwa v155, v151, v163 dst_sel:DWORD dst_unused:UNUSED_PAD src0_sel:WORD_1 src1_sel:DWORD
	v_and_b32_sdwa v156, v152, v163 dst_sel:DWORD dst_unused:UNUSED_PAD src0_sel:WORD_1 src1_sel:DWORD
	v_and_b32_sdwa v157, v153, v163 dst_sel:DWORD dst_unused:UNUSED_PAD src0_sel:WORD_1 src1_sel:DWORD
	v_add_f32_e32 v137, v137, v148
	v_add3_u32 v150, v150, v154, s12
	v_add3_u32 v151, v151, v155, s12
	v_add3_u32 v152, v152, v156, s12
	v_add3_u32 v153, v153, v157, s12
	v_add_f32_e32 v137, v137, v149
	v_and_b32_e32 v151, 0xffff0000, v151
	v_and_b32_e32 v153, 0xffff0000, v153
	s_nop 0
	v_or_b32_sdwa v160, v151, v150 dst_sel:DWORD dst_unused:UNUSED_PAD src0_sel:DWORD src1_sel:WORD_1
	v_or_b32_sdwa v161, v153, v152 dst_sel:DWORD dst_unused:UNUSED_PAD src0_sel:DWORD src1_sel:WORD_1
	global_store_dwordx2 v165, v[160:161], s[92:93]
	s_nop 1
	v_add_f32_dpp v134, v134, v134 quad_perm:[1,0,3,2] row_mask:0xf bank_mask:0xf
	v_add_f32_dpp v135, v135, v135 quad_perm:[1,0,3,2] row_mask:0xf bank_mask:0xf
	v_add_f32_dpp v136, v136, v136 quad_perm:[1,0,3,2] row_mask:0xf bank_mask:0xf
	v_add_f32_dpp v137, v137, v137 quad_perm:[1,0,3,2] row_mask:0xf bank_mask:0xf
	v_add_f32_dpp v134, v134, v134 quad_perm:[2,3,0,1] row_mask:0xf bank_mask:0xf
	v_add_f32_dpp v135, v135, v135 quad_perm:[2,3,0,1] row_mask:0xf bank_mask:0xf
	v_add_f32_dpp v136, v136, v136 quad_perm:[2,3,0,1] row_mask:0xf bank_mask:0xf
	v_add_f32_dpp v137, v137, v137 quad_perm:[2,3,0,1] row_mask:0xf bank_mask:0xf
	v_add_f32_dpp v134, v134, v134 row_half_mirror row_mask:0xf bank_mask:0xf
	v_add_f32_dpp v135, v135, v135 row_half_mirror row_mask:0xf bank_mask:0xf
	v_add_f32_dpp v136, v136, v136 row_half_mirror row_mask:0xf bank_mask:0xf
	v_add_f32_dpp v137, v137, v137 row_half_mirror row_mask:0xf bank_mask:0xf
	v_add_f32_dpp v134, v134, v134 row_mirror row_mask:0xf bank_mask:0xf
	v_add_f32_dpp v135, v135, v135 row_mirror row_mask:0xf bank_mask:0xf
	v_add_f32_dpp v136, v136, v136 row_mirror row_mask:0xf bank_mask:0xf
	v_add_f32_dpp v137, v137, v137 row_mirror row_mask:0xf bank_mask:0xf
	v_add_f32_dpp v134, v134, v134 row_bcast:15 row_mask:0xa bank_mask:0xf
	v_add_f32_dpp v135, v135, v135 row_bcast:15 row_mask:0xa bank_mask:0xf
	v_add_f32_dpp v136, v136, v136 row_bcast:15 row_mask:0xa bank_mask:0xf
	v_add_f32_dpp v137, v137, v137 row_bcast:15 row_mask:0xa bank_mask:0xf
	s_waitcnt vmcnt(23) lgkmcnt(6)
	v_pk_add_f32 v[36:37], v[36:37], v[80:81]
	v_pk_add_f32 v[38:39], v[38:39], v[82:83]
	s_waitcnt vmcnt(22) lgkmcnt(4)
	v_pk_add_f32 v[40:41], v[40:41], v[84:85]
	v_pk_add_f32 v[42:43], v[42:43], v[86:87]
	s_waitcnt vmcnt(21) lgkmcnt(2)
	v_pk_add_f32 v[44:45], v[44:45], v[118:119]
	v_pk_add_f32 v[46:47], v[46:47], v[120:121]
	s_waitcnt vmcnt(20) lgkmcnt(0)
	v_pk_add_f32 v[48:49], v[48:49], v[122:123]
	v_pk_add_f32 v[50:51], v[50:51], v[124:125]
	v_add_u32_e32 v88, 0xc180, v75
	ds_read2_b32 v[80:81], v88 offset1:1
	ds_read2_b32 v[82:83], v88 offset0:2 offset1:3
	v_add_u32_e32 v89, 0xd1a0, v75
	ds_read2_b32 v[84:85], v89 offset1:1
	ds_read2_b32 v[86:87], v89 offset0:2 offset1:3
	v_add_u32_e32 v88, 0xe1c0, v75
	ds_read2_b32 v[118:119], v88 offset1:1
	ds_read2_b32 v[120:121], v88 offset0:2 offset1:3
	v_add_u32_e32 v89, 0xf1e0, v75
	ds_read2_b32 v[122:123], v89 offset1:1
	ds_read2_b32 v[124:125], v89 offset0:2 offset1:3
	v_add_u32_e32 v65, 0x40000, v64
	global_store_dwordx4 v65, v[36:39], s[80:81]
	v_pk_mul_f32 v[146:147], v[36:37], v[36:37]
	v_pk_mul_f32 v[148:149], v[38:39], v[38:39]
	v_pk_mul_f32 v[150:151], v[36:37], v[128:129]
	v_pk_mul_f32 v[152:153], v[38:39], v[130:131]
	v_lshrrev_b32_e32 v164, 1, v65
	v_add_f32_e32 v138, v146, v147
	v_and_b32_sdwa v154, v150, v163 dst_sel:DWORD dst_unused:UNUSED_PAD src0_sel:WORD_1 src1_sel:DWORD
	v_and_b32_sdwa v155, v151, v163 dst_sel:DWORD dst_unused:UNUSED_PAD src0_sel:WORD_1 src1_sel:DWORD
	v_and_b32_sdwa v156, v152, v163 dst_sel:DWORD dst_unused:UNUSED_PAD src0_sel:WORD_1 src1_sel:DWORD
	v_and_b32_sdwa v157, v153, v163 dst_sel:DWORD dst_unused:UNUSED_PAD src0_sel:WORD_1 src1_sel:DWORD
	v_add_f32_e32 v138, v138, v148
	v_add3_u32 v150, v150, v154, s12
	v_add3_u32 v151, v151, v155, s12
	v_add3_u32 v152, v152, v156, s12
	v_add3_u32 v153, v153, v157, s12
	v_add_f32_e32 v138, v138, v149
	v_and_b32_e32 v151, 0xffff0000, v151
	v_and_b32_e32 v153, 0xffff0000, v153
	s_nop 0
	v_or_b32_sdwa v158, v151, v150 dst_sel:DWORD dst_unused:UNUSED_PAD src0_sel:DWORD src1_sel:WORD_1
	v_or_b32_sdwa v159, v153, v152 dst_sel:DWORD dst_unused:UNUSED_PAD src0_sel:DWORD src1_sel:WORD_1
	global_store_dwordx2 v164, v[158:159], s[92:93]
	v_add_u32_e32 v74, 0x48000, v64
	global_store_dwordx4 v74, v[40:43], s[80:81]
	v_pk_mul_f32 v[146:147], v[40:41], v[40:41]
	v_pk_mul_f32 v[148:149], v[42:43], v[42:43]
	v_pk_mul_f32 v[150:151], v[40:41], v[128:129]
	v_pk_mul_f32 v[152:153], v[42:43], v[130:131]
	v_lshrrev_b32_e32 v165, 1, v74
	v_add_f32_e32 v139, v146, v147
	v_and_b32_sdwa v154, v150, v163 dst_sel:DWORD dst_unused:UNUSED_PAD src0_sel:WORD_1 src1_sel:DWORD
	v_and_b32_sdwa v155, v151, v163 dst_sel:DWORD dst_unused:UNUSED_PAD src0_sel:WORD_1 src1_sel:DWORD
	v_and_b32_sdwa v156, v152, v163 dst_sel:DWORD dst_unused:UNUSED_PAD src0_sel:WORD_1 src1_sel:DWORD
	v_and_b32_sdwa v157, v153, v163 dst_sel:DWORD dst_unused:UNUSED_PAD src0_sel:WORD_1 src1_sel:DWORD
	v_add_f32_e32 v139, v139, v148
	v_add3_u32 v150, v150, v154, s12
	v_add3_u32 v151, v151, v155, s12
	v_add3_u32 v152, v152, v156, s12
	v_add3_u32 v153, v153, v157, s12
	v_add_f32_e32 v139, v139, v149
	v_and_b32_e32 v151, 0xffff0000, v151
	v_and_b32_e32 v153, 0xffff0000, v153
	s_nop 0
	v_or_b32_sdwa v160, v151, v150 dst_sel:DWORD dst_unused:UNUSED_PAD src0_sel:DWORD src1_sel:WORD_1
	v_or_b32_sdwa v161, v153, v152 dst_sel:DWORD dst_unused:UNUSED_PAD src0_sel:DWORD src1_sel:WORD_1
	global_store_dwordx2 v165, v[160:161], s[92:93]
	v_add_u32_e32 v65, 0x50000, v64
	global_store_dwordx4 v65, v[44:47], s[80:81]
	v_pk_mul_f32 v[146:147], v[44:45], v[44:45]
	v_pk_mul_f32 v[148:149], v[46:47], v[46:47]
	v_pk_mul_f32 v[150:151], v[44:45], v[128:129]
	v_pk_mul_f32 v[152:153], v[46:47], v[130:131]
	v_lshrrev_b32_e32 v164, 1, v65
	v_add_f32_e32 v140, v146, v147
	v_and_b32_sdwa v154, v150, v163 dst_sel:DWORD dst_unused:UNUSED_PAD src0_sel:WORD_1 src1_sel:DWORD
	v_and_b32_sdwa v155, v151, v163 dst_sel:DWORD dst_unused:UNUSED_PAD src0_sel:WORD_1 src1_sel:DWORD
	v_and_b32_sdwa v156, v152, v163 dst_sel:DWORD dst_unused:UNUSED_PAD src0_sel:WORD_1 src1_sel:DWORD
	v_and_b32_sdwa v157, v153, v163 dst_sel:DWORD dst_unused:UNUSED_PAD src0_sel:WORD_1 src1_sel:DWORD
	v_add_f32_e32 v140, v140, v148
	v_add3_u32 v150, v150, v154, s12
	v_add3_u32 v151, v151, v155, s12
	v_add3_u32 v152, v152, v156, s12
	v_add3_u32 v153, v153, v157, s12
	v_add_f32_e32 v140, v140, v149
	v_and_b32_e32 v151, 0xffff0000, v151
	v_and_b32_e32 v153, 0xffff0000, v153
	s_nop 0
	v_or_b32_sdwa v158, v151, v150 dst_sel:DWORD dst_unused:UNUSED_PAD src0_sel:DWORD src1_sel:WORD_1
	v_or_b32_sdwa v159, v153, v152 dst_sel:DWORD dst_unused:UNUSED_PAD src0_sel:DWORD src1_sel:WORD_1
	global_store_dwordx2 v164, v[158:159], s[92:93]
	v_add_u32_e32 v74, 0x58000, v64
	global_store_dwordx4 v74, v[48:51], s[80:81]
	v_pk_mul_f32 v[146:147], v[48:49], v[48:49]
	v_pk_mul_f32 v[148:149], v[50:51], v[50:51]
	v_pk_mul_f32 v[150:151], v[48:49], v[128:129]
	v_pk_mul_f32 v[152:153], v[50:51], v[130:131]
	v_lshrrev_b32_e32 v165, 1, v74
	v_add_f32_e32 v141, v146, v147
	v_and_b32_sdwa v154, v150, v163 dst_sel:DWORD dst_unused:UNUSED_PAD src0_sel:WORD_1 src1_sel:DWORD
	v_and_b32_sdwa v155, v151, v163 dst_sel:DWORD dst_unused:UNUSED_PAD src0_sel:WORD_1 src1_sel:DWORD
	v_and_b32_sdwa v156, v152, v163 dst_sel:DWORD dst_unused:UNUSED_PAD src0_sel:WORD_1 src1_sel:DWORD
	v_and_b32_sdwa v157, v153, v163 dst_sel:DWORD dst_unused:UNUSED_PAD src0_sel:WORD_1 src1_sel:DWORD
	v_add_f32_e32 v141, v141, v148
	v_add3_u32 v150, v150, v154, s12
	v_add3_u32 v151, v151, v155, s12
	v_add3_u32 v152, v152, v156, s12
	v_add3_u32 v153, v153, v157, s12
	v_add_f32_e32 v141, v141, v149
	v_and_b32_e32 v151, 0xffff0000, v151
	v_and_b32_e32 v153, 0xffff0000, v153
	s_nop 0
	v_or_b32_sdwa v160, v151, v150 dst_sel:DWORD dst_unused:UNUSED_PAD src0_sel:DWORD src1_sel:WORD_1
	v_or_b32_sdwa v161, v153, v152 dst_sel:DWORD dst_unused:UNUSED_PAD src0_sel:DWORD src1_sel:WORD_1
	global_store_dwordx2 v165, v[160:161], s[92:93]
	s_nop 1
	v_add_f32_dpp v138, v138, v138 quad_perm:[1,0,3,2] row_mask:0xf bank_mask:0xf
	v_add_f32_dpp v139, v139, v139 quad_perm:[1,0,3,2] row_mask:0xf bank_mask:0xf
	v_add_f32_dpp v140, v140, v140 quad_perm:[1,0,3,2] row_mask:0xf bank_mask:0xf
	v_add_f32_dpp v141, v141, v141 quad_perm:[1,0,3,2] row_mask:0xf bank_mask:0xf
	v_add_f32_dpp v138, v138, v138 quad_perm:[2,3,0,1] row_mask:0xf bank_mask:0xf
	v_add_f32_dpp v139, v139, v139 quad_perm:[2,3,0,1] row_mask:0xf bank_mask:0xf
	v_add_f32_dpp v140, v140, v140 quad_perm:[2,3,0,1] row_mask:0xf bank_mask:0xf
	v_add_f32_dpp v141, v141, v141 quad_perm:[2,3,0,1] row_mask:0xf bank_mask:0xf
	v_add_f32_dpp v138, v138, v138 row_half_mirror row_mask:0xf bank_mask:0xf
	v_add_f32_dpp v139, v139, v139 row_half_mirror row_mask:0xf bank_mask:0xf
	v_add_f32_dpp v140, v140, v140 row_half_mirror row_mask:0xf bank_mask:0xf
	v_add_f32_dpp v141, v141, v141 row_half_mirror row_mask:0xf bank_mask:0xf
	v_add_f32_dpp v138, v138, v138 row_mirror row_mask:0xf bank_mask:0xf
	v_add_f32_dpp v139, v139, v139 row_mirror row_mask:0xf bank_mask:0xf
	v_add_f32_dpp v140, v140, v140 row_mirror row_mask:0xf bank_mask:0xf
	v_add_f32_dpp v141, v141, v141 row_mirror row_mask:0xf bank_mask:0xf
	v_add_f32_dpp v138, v138, v138 row_bcast:15 row_mask:0xa bank_mask:0xf
	v_add_f32_dpp v139, v139, v139 row_bcast:15 row_mask:0xa bank_mask:0xf
	v_add_f32_dpp v140, v140, v140 row_bcast:15 row_mask:0xa bank_mask:0xf
	v_add_f32_dpp v141, v141, v141 row_bcast:15 row_mask:0xa bank_mask:0xf
	s_waitcnt vmcnt(27) lgkmcnt(6)
	v_pk_add_f32 v[52:53], v[52:53], v[80:81]
	v_pk_add_f32 v[54:55], v[54:55], v[82:83]
	s_waitcnt vmcnt(26) lgkmcnt(4)
	v_pk_add_f32 v[56:57], v[56:57], v[84:85]
	v_pk_add_f32 v[58:59], v[58:59], v[86:87]
	s_waitcnt vmcnt(25) lgkmcnt(2)
	v_pk_add_f32 v[60:61], v[60:61], v[118:119]
	v_pk_add_f32 v[62:63], v[62:63], v[120:121]
	s_waitcnt vmcnt(24) lgkmcnt(0)
	v_pk_add_f32 v[76:77], v[76:77], v[122:123]
	v_pk_add_f32 v[78:79], v[78:79], v[124:125]
	v_add_u32_e32 v65, 0x60000, v64
	global_store_dwordx4 v65, v[52:55], s[80:81]
	v_pk_mul_f32 v[146:147], v[52:53], v[52:53]
	v_pk_mul_f32 v[148:149], v[54:55], v[54:55]
	v_pk_mul_f32 v[150:151], v[52:53], v[128:129]
	v_pk_mul_f32 v[152:153], v[54:55], v[130:131]
	v_lshrrev_b32_e32 v164, 1, v65
	v_add_f32_e32 v142, v146, v147
	v_and_b32_sdwa v154, v150, v163 dst_sel:DWORD dst_unused:UNUSED_PAD src0_sel:WORD_1 src1_sel:DWORD
	v_and_b32_sdwa v155, v151, v163 dst_sel:DWORD dst_unused:UNUSED_PAD src0_sel:WORD_1 src1_sel:DWORD
	v_and_b32_sdwa v156, v152, v163 dst_sel:DWORD dst_unused:UNUSED_PAD src0_sel:WORD_1 src1_sel:DWORD
	v_and_b32_sdwa v157, v153, v163 dst_sel:DWORD dst_unused:UNUSED_PAD src0_sel:WORD_1 src1_sel:DWORD
	v_add_f32_e32 v142, v142, v148
	v_add3_u32 v150, v150, v154, s12
	v_add3_u32 v151, v151, v155, s12
	v_add3_u32 v152, v152, v156, s12
	v_add3_u32 v153, v153, v157, s12
	v_add_f32_e32 v142, v142, v149
	v_and_b32_e32 v151, 0xffff0000, v151
	v_and_b32_e32 v153, 0xffff0000, v153
	s_nop 0
	v_or_b32_sdwa v158, v151, v150 dst_sel:DWORD dst_unused:UNUSED_PAD src0_sel:DWORD src1_sel:WORD_1
	v_or_b32_sdwa v159, v153, v152 dst_sel:DWORD dst_unused:UNUSED_PAD src0_sel:DWORD src1_sel:WORD_1
	global_store_dwordx2 v164, v[158:159], s[92:93]
	v_add_u32_e32 v74, 0x68000, v64
	global_store_dwordx4 v74, v[56:59], s[80:81]
	v_pk_mul_f32 v[146:147], v[56:57], v[56:57]
	v_pk_mul_f32 v[148:149], v[58:59], v[58:59]
	v_pk_mul_f32 v[150:151], v[56:57], v[128:129]
	v_pk_mul_f32 v[152:153], v[58:59], v[130:131]
	v_lshrrev_b32_e32 v165, 1, v74
	v_add_f32_e32 v143, v146, v147
	v_and_b32_sdwa v154, v150, v163 dst_sel:DWORD dst_unused:UNUSED_PAD src0_sel:WORD_1 src1_sel:DWORD
	v_and_b32_sdwa v155, v151, v163 dst_sel:DWORD dst_unused:UNUSED_PAD src0_sel:WORD_1 src1_sel:DWORD
	v_and_b32_sdwa v156, v152, v163 dst_sel:DWORD dst_unused:UNUSED_PAD src0_sel:WORD_1 src1_sel:DWORD
	v_and_b32_sdwa v157, v153, v163 dst_sel:DWORD dst_unused:UNUSED_PAD src0_sel:WORD_1 src1_sel:DWORD
	v_add_f32_e32 v143, v143, v148
	v_add3_u32 v150, v150, v154, s12
	v_add3_u32 v151, v151, v155, s12
	v_add3_u32 v152, v152, v156, s12
	v_add3_u32 v153, v153, v157, s12
	v_add_f32_e32 v143, v143, v149
	v_and_b32_e32 v151, 0xffff0000, v151
	v_and_b32_e32 v153, 0xffff0000, v153
	s_nop 0
	v_or_b32_sdwa v160, v151, v150 dst_sel:DWORD dst_unused:UNUSED_PAD src0_sel:DWORD src1_sel:WORD_1
	v_or_b32_sdwa v161, v153, v152 dst_sel:DWORD dst_unused:UNUSED_PAD src0_sel:DWORD src1_sel:WORD_1
	global_store_dwordx2 v165, v[160:161], s[92:93]
	v_add_u32_e32 v65, 0x70000, v64
	global_store_dwordx4 v65, v[60:63], s[80:81]
	v_pk_mul_f32 v[146:147], v[60:61], v[60:61]
	v_pk_mul_f32 v[148:149], v[62:63], v[62:63]
	v_pk_mul_f32 v[150:151], v[60:61], v[128:129]
	v_pk_mul_f32 v[152:153], v[62:63], v[130:131]
	v_lshrrev_b32_e32 v164, 1, v65
	v_add_f32_e32 v144, v146, v147
	v_and_b32_sdwa v154, v150, v163 dst_sel:DWORD dst_unused:UNUSED_PAD src0_sel:WORD_1 src1_sel:DWORD
	v_and_b32_sdwa v155, v151, v163 dst_sel:DWORD dst_unused:UNUSED_PAD src0_sel:WORD_1 src1_sel:DWORD
	v_and_b32_sdwa v156, v152, v163 dst_sel:DWORD dst_unused:UNUSED_PAD src0_sel:WORD_1 src1_sel:DWORD
	v_and_b32_sdwa v157, v153, v163 dst_sel:DWORD dst_unused:UNUSED_PAD src0_sel:WORD_1 src1_sel:DWORD
	v_add_f32_e32 v144, v144, v148
	v_add3_u32 v150, v150, v154, s12
	v_add3_u32 v151, v151, v155, s12
	v_add3_u32 v152, v152, v156, s12
	v_add3_u32 v153, v153, v157, s12
	v_add_f32_e32 v144, v144, v149
	v_and_b32_e32 v151, 0xffff0000, v151
	v_and_b32_e32 v153, 0xffff0000, v153
	s_nop 0
	v_or_b32_sdwa v158, v151, v150 dst_sel:DWORD dst_unused:UNUSED_PAD src0_sel:DWORD src1_sel:WORD_1
	v_or_b32_sdwa v159, v153, v152 dst_sel:DWORD dst_unused:UNUSED_PAD src0_sel:DWORD src1_sel:WORD_1
	global_store_dwordx2 v164, v[158:159], s[92:93]
	v_add_u32_e32 v74, 0x78000, v64
	global_store_dwordx4 v74, v[76:79], s[80:81]
	v_pk_mul_f32 v[146:147], v[76:77], v[76:77]
	v_pk_mul_f32 v[148:149], v[78:79], v[78:79]
	v_pk_mul_f32 v[150:151], v[76:77], v[128:129]
	v_pk_mul_f32 v[152:153], v[78:79], v[130:131]
	v_lshrrev_b32_e32 v165, 1, v74
	v_add_f32_e32 v145, v146, v147
	v_and_b32_sdwa v154, v150, v163 dst_sel:DWORD dst_unused:UNUSED_PAD src0_sel:WORD_1 src1_sel:DWORD
	v_and_b32_sdwa v155, v151, v163 dst_sel:DWORD dst_unused:UNUSED_PAD src0_sel:WORD_1 src1_sel:DWORD
	v_and_b32_sdwa v156, v152, v163 dst_sel:DWORD dst_unused:UNUSED_PAD src0_sel:WORD_1 src1_sel:DWORD
	v_and_b32_sdwa v157, v153, v163 dst_sel:DWORD dst_unused:UNUSED_PAD src0_sel:WORD_1 src1_sel:DWORD
	v_add_f32_e32 v145, v145, v148
	v_add3_u32 v150, v150, v154, s12
	v_add3_u32 v151, v151, v155, s12
	v_add3_u32 v152, v152, v156, s12
	v_add3_u32 v153, v153, v157, s12
	v_add_f32_e32 v145, v145, v149
	v_and_b32_e32 v151, 0xffff0000, v151
	v_and_b32_e32 v153, 0xffff0000, v153
	s_nop 0
	v_or_b32_sdwa v160, v151, v150 dst_sel:DWORD dst_unused:UNUSED_PAD src0_sel:DWORD src1_sel:WORD_1
	v_or_b32_sdwa v161, v153, v152 dst_sel:DWORD dst_unused:UNUSED_PAD src0_sel:DWORD src1_sel:WORD_1
	global_store_dwordx2 v165, v[160:161], s[92:93]
	s_nop 1
	v_add_f32_dpp v142, v142, v142 quad_perm:[1,0,3,2] row_mask:0xf bank_mask:0xf
	v_add_f32_dpp v143, v143, v143 quad_perm:[1,0,3,2] row_mask:0xf bank_mask:0xf
	v_add_f32_dpp v144, v144, v144 quad_perm:[1,0,3,2] row_mask:0xf bank_mask:0xf
	v_add_f32_dpp v145, v145, v145 quad_perm:[1,0,3,2] row_mask:0xf bank_mask:0xf
	v_add_f32_dpp v142, v142, v142 quad_perm:[2,3,0,1] row_mask:0xf bank_mask:0xf
	v_add_f32_dpp v143, v143, v143 quad_perm:[2,3,0,1] row_mask:0xf bank_mask:0xf
	v_add_f32_dpp v144, v144, v144 quad_perm:[2,3,0,1] row_mask:0xf bank_mask:0xf
	v_add_f32_dpp v145, v145, v145 quad_perm:[2,3,0,1] row_mask:0xf bank_mask:0xf
	v_add_f32_dpp v142, v142, v142 row_half_mirror row_mask:0xf bank_mask:0xf
	v_add_f32_dpp v143, v143, v143 row_half_mirror row_mask:0xf bank_mask:0xf
	v_add_f32_dpp v144, v144, v144 row_half_mirror row_mask:0xf bank_mask:0xf
	v_add_f32_dpp v145, v145, v145 row_half_mirror row_mask:0xf bank_mask:0xf
	v_add_f32_dpp v142, v142, v142 row_mirror row_mask:0xf bank_mask:0xf
	v_add_f32_dpp v143, v143, v143 row_mirror row_mask:0xf bank_mask:0xf
	v_add_f32_dpp v144, v144, v144 row_mirror row_mask:0xf bank_mask:0xf
	v_add_f32_dpp v145, v145, v145 row_mirror row_mask:0xf bank_mask:0xf
	v_add_f32_dpp v142, v142, v142 row_bcast:15 row_mask:0xa bank_mask:0xf
	v_add_f32_dpp v143, v143, v143 row_bcast:15 row_mask:0xa bank_mask:0xf
	v_add_f32_dpp v144, v144, v144 row_bcast:15 row_mask:0xa bank_mask:0xf
	v_add_f32_dpp v145, v145, v145 row_bcast:15 row_mask:0xa bank_mask:0xf
	s_nop 1
	s_mov_b32 exec_lo, 0x80000000
	s_mov_b32 exec_hi, 0x80000000
	global_atomic_add_f32 v162, v126, s[10:11]
	global_atomic_add_f32 v162, v127, s[10:11] offset:32
	global_atomic_add_f32 v162, v132, s[10:11] offset:64
	global_atomic_add_f32 v162, v133, s[10:11] offset:96
	global_atomic_add_f32 v162, v134, s[10:11] offset:128
	global_atomic_add_f32 v162, v135, s[10:11] offset:160
	global_atomic_add_f32 v162, v136, s[10:11] offset:192
	global_atomic_add_f32 v162, v137, s[10:11] offset:224
	global_atomic_add_f32 v162, v138, s[10:11] offset:256
	global_atomic_add_f32 v162, v139, s[10:11] offset:288
	global_atomic_add_f32 v162, v140, s[10:11] offset:320
	global_atomic_add_f32 v162, v141, s[10:11] offset:352
	global_atomic_add_f32 v162, v142, s[10:11] offset:384
	global_atomic_add_f32 v162, v143, s[10:11] offset:416
	global_atomic_add_f32 v162, v144, s[10:11] offset:448
	global_atomic_add_f32 v162, v145, s[10:11] offset:480
	s_mov_b64 exec, -1
	s_branch .LBB0_562

.LBB0_617:
	v_lshrrev_b32_e32 v4, 2, v134
	v_mov_b32_e32 v5, v2
	v_lshlrev_b32_e32 v6, 12, v5
	v_lshl_add_u32 v6, v4, 2, v6
	global_load_dwordx4 v[8:11], v6, s[80:81]
	v_add_u32_e32 v88, 0x8000, v6
	global_load_dwordx4 v[12:15], v88, s[80:81]
	v_add_u32_e32 v7, 0x10000, v6
	global_load_dwordx4 v[16:19], v7, s[80:81]
	v_add_u32_e32 v88, 0x18000, v6
	global_load_dwordx4 v[20:23], v88, s[80:81]
	v_add_u32_e32 v7, 0x20000, v6
	global_load_dwordx4 v[24:27], v7, s[80:81]
	v_add_u32_e32 v88, 0x28000, v6
	global_load_dwordx4 v[28:31], v88, s[80:81]
	v_add_u32_e32 v7, 0x30000, v6
	global_load_dwordx4 v[32:35], v7, s[80:81]
	v_add_u32_e32 v88, 0x38000, v6
	global_load_dwordx4 v[36:39], v88, s[80:81]
	v_add_u32_e32 v7, 0x40000, v6
	global_load_dwordx4 v[40:43], v7, s[80:81]
	v_add_u32_e32 v88, 0x48000, v6
	global_load_dwordx4 v[44:47], v88, s[80:81]
	v_add_u32_e32 v7, 0x50000, v6
	global_load_dwordx4 v[48:51], v7, s[80:81]
	v_add_u32_e32 v88, 0x58000, v6
	global_load_dwordx4 v[52:55], v88, s[80:81]
	v_add_u32_e32 v7, 0x60000, v6
	global_load_dwordx4 v[56:59], v7, s[80:81]
	v_add_u32_e32 v88, 0x68000, v6
	global_load_dwordx4 v[60:63], v88, s[80:81]
	v_add_u32_e32 v7, 0x70000, v6
	global_load_dwordx4 v[64:67], v7, s[80:81]
	v_add_u32_e32 v88, 0x78000, v6
	global_load_dwordx4 v[68:71], v88, s[80:81]
	v_and_b32_e32 v89, 7, v5
	v_mul_u32_u24_e32 v89, 0x204, v89
	v_and_b32_e32 v90, 0x7f, v4
	v_lshl_add_u32 v89, v90, 2, v89
	ds_read2_b32 v[72:73], v89 offset1:1
	ds_read2_b32 v[74:75], v89 offset0:2 offset1:3
	v_add_u32_e32 v91, 0x1020, v89
	ds_read2_b32 v[76:77], v91 offset1:1
	ds_read2_b32 v[78:79], v91 offset0:2 offset1:3
	v_add_u32_e32 v90, 0x2040, v89
	ds_read2_b32 v[80:81], v90 offset1:1
	ds_read2_b32 v[82:83], v90 offset0:2 offset1:3
	v_add_u32_e32 v91, 0x3060, v89
	ds_read2_b32 v[84:85], v91 offset1:1
	ds_read2_b32 v[86:87], v91 offset0:2 offset1:3
	s_waitcnt vmcnt(15) lgkmcnt(6)
	v_pk_add_f32 v[8:9], v[8:9], v[72:73]
	v_pk_add_f32 v[10:11], v[10:11], v[74:75]
	s_waitcnt vmcnt(14) lgkmcnt(4)
	v_pk_add_f32 v[12:13], v[12:13], v[76:77]
	v_pk_add_f32 v[14:15], v[14:15], v[78:79]
	s_waitcnt vmcnt(13) lgkmcnt(2)
	v_pk_add_f32 v[16:17], v[16:17], v[80:81]
	v_pk_add_f32 v[18:19], v[18:19], v[82:83]
	s_waitcnt vmcnt(12) lgkmcnt(0)
	v_pk_add_f32 v[20:21], v[20:21], v[84:85]
	v_pk_add_f32 v[22:23], v[22:23], v[86:87]
	v_add_u32_e32 v90, 0x4080, v89
	ds_read2_b32 v[72:73], v90 offset1:1
	ds_read2_b32 v[74:75], v90 offset0:2 offset1:3
	v_add_u32_e32 v91, 0x50a0, v89
	ds_read2_b32 v[76:77], v91 offset1:1
	ds_read2_b32 v[78:79], v91 offset0:2 offset1:3
	v_add_u32_e32 v90, 0x60c0, v89
	ds_read2_b32 v[80:81], v90 offset1:1
	ds_read2_b32 v[82:83], v90 offset0:2 offset1:3
	v_add_u32_e32 v91, 0x70e0, v89
	ds_read2_b32 v[84:85], v91 offset1:1
	ds_read2_b32 v[86:87], v91 offset0:2 offset1:3
	global_store_dwordx4 v6, v[8:11], s[80:81]
	v_add_u32_e32 v88, 0x8000, v6
	global_store_dwordx4 v88, v[12:15], s[80:81]
	v_add_u32_e32 v7, 0x10000, v6
	global_store_dwordx4 v7, v[16:19], s[80:81]
	v_add_u32_e32 v88, 0x18000, v6
	global_store_dwordx4 v88, v[20:23], s[80:81]
	s_waitcnt vmcnt(15) lgkmcnt(6)
	v_pk_add_f32 v[24:25], v[24:25], v[72:73]
	v_pk_add_f32 v[26:27], v[26:27], v[74:75]
	s_waitcnt vmcnt(14) lgkmcnt(4)
	v_pk_add_f32 v[28:29], v[28:29], v[76:77]
	v_pk_add_f32 v[30:31], v[30:31], v[78:79]
	s_waitcnt vmcnt(13) lgkmcnt(2)
	v_pk_add_f32 v[32:33], v[32:33], v[80:81]
	v_pk_add_f32 v[34:35], v[34:35], v[82:83]
	s_waitcnt vmcnt(12) lgkmcnt(0)
	v_pk_add_f32 v[36:37], v[36:37], v[84:85]
	v_pk_add_f32 v[38:39], v[38:39], v[86:87]
	v_add_u32_e32 v90, 0x8100, v89
	ds_read2_b32 v[72:73], v90 offset1:1
	ds_read2_b32 v[74:75], v90 offset0:2 offset1:3
	v_add_u32_e32 v91, 0x9120, v89
	ds_read2_b32 v[76:77], v91 offset1:1
	ds_read2_b32 v[78:79], v91 offset0:2 offset1:3
	v_add_u32_e32 v90, 0xa140, v89
	ds_read2_b32 v[80:81], v90 offset1:1
	ds_read2_b32 v[82:83], v90 offset0:2 offset1:3
	v_add_u32_e32 v91, 0xb160, v89
	ds_read2_b32 v[84:85], v91 offset1:1
	ds_read2_b32 v[86:87], v91 offset0:2 offset1:3
	v_add_u32_e32 v7, 0x20000, v6
	global_store_dwordx4 v7, v[24:27], s[80:81]
	v_add_u32_e32 v88, 0x28000, v6
	global_store_dwordx4 v88, v[28:31], s[80:81]
	v_add_u32_e32 v7, 0x30000, v6
	global_store_dwordx4 v7, v[32:35], s[80:81]
	v_add_u32_e32 v88, 0x38000, v6
	global_store_dwordx4 v88, v[36:39], s[80:81]
	s_waitcnt vmcnt(15) lgkmcnt(6)
	v_pk_add_f32 v[40:41], v[40:41], v[72:73]
	v_pk_add_f32 v[42:43], v[42:43], v[74:75]
	s_waitcnt vmcnt(14) lgkmcnt(4)
	v_pk_add_f32 v[44:45], v[44:45], v[76:77]
	v_pk_add_f32 v[46:47], v[46:47], v[78:79]
	s_waitcnt vmcnt(13) lgkmcnt(2)
	v_pk_add_f32 v[48:49], v[48:49], v[80:81]
	v_pk_add_f32 v[50:51], v[50:51], v[82:83]
	s_waitcnt vmcnt(12) lgkmcnt(0)
	v_pk_add_f32 v[52:53], v[52:53], v[84:85]
	v_pk_add_f32 v[54:55], v[54:55], v[86:87]
	v_add_u32_e32 v90, 0xc180, v89
	ds_read2_b32 v[72:73], v90 offset1:1
	ds_read2_b32 v[74:75], v90 offset0:2 offset1:3
	v_add_u32_e32 v91, 0xd1a0, v89
	ds_read2_b32 v[76:77], v91 offset1:1
	ds_read2_b32 v[78:79], v91 offset0:2 offset1:3
	v_add_u32_e32 v90, 0xe1c0, v89
	ds_read2_b32 v[80:81], v90 offset1:1
	ds_read2_b32 v[82:83], v90 offset0:2 offset1:3
	v_add_u32_e32 v91, 0xf1e0, v89
	ds_read2_b32 v[84:85], v91 offset1:1
	ds_read2_b32 v[86:87], v91 offset0:2 offset1:3
	v_add_u32_e32 v7, 0x40000, v6
	global_store_dwordx4 v7, v[40:43], s[80:81]
	v_add_u32_e32 v88, 0x48000, v6
	global_store_dwordx4 v88, v[44:47], s[80:81]
	v_add_u32_e32 v7, 0x50000, v6
	global_store_dwordx4 v7, v[48:51], s[80:81]
	v_add_u32_e32 v88, 0x58000, v6
	global_store_dwordx4 v88, v[52:55], s[80:81]
	s_waitcnt vmcnt(15) lgkmcnt(6)
	v_pk_add_f32 v[56:57], v[56:57], v[72:73]
	v_pk_add_f32 v[58:59], v[58:59], v[74:75]
	s_waitcnt vmcnt(14) lgkmcnt(4)
	v_pk_add_f32 v[60:61], v[60:61], v[76:77]
	v_pk_add_f32 v[62:63], v[62:63], v[78:79]
	s_waitcnt vmcnt(13) lgkmcnt(2)
	v_pk_add_f32 v[64:65], v[64:65], v[80:81]
	v_pk_add_f32 v[66:67], v[66:67], v[82:83]
	s_waitcnt vmcnt(12) lgkmcnt(0)
	v_pk_add_f32 v[68:69], v[68:69], v[84:85]
	v_pk_add_f32 v[70:71], v[70:71], v[86:87]
	v_add_u32_e32 v7, 0x60000, v6
	global_store_dwordx4 v7, v[56:59], s[80:81]
	v_add_u32_e32 v88, 0x68000, v6
	global_store_dwordx4 v88, v[60:63], s[80:81]
	v_add_u32_e32 v7, 0x70000, v6
	global_store_dwordx4 v7, v[64:67], s[80:81]
	v_add_u32_e32 v88, 0x78000, v6
	global_store_dwordx4 v88, v[68:71], s[80:81]
	s_add_i32 s9, s9, s10
	s_add_i32 s12, s12, s13
	s_add_i32 s14, s14, s15
	s_cmpk_lt_u32 s9, 0x100
	s_barrier
	s_cbranch_scc1 .LBB0_608
